# speedup vs baseline: 1.0333x; 1.0333x over previous
; __device__ __forceinline__ void wkv_phase(const WkvT& W, unsigned char* lds) {
;     const int tid = threadIdx.x, lane = tid & 63, wave = tid >> 6;
;     float* sP = (float*)lds; float* sV = sP + 2 * 12288; float* sY = sV + 1024;
;     for (int unit = blockIdx.x; unit < 256; unit += gridDim.x) {
;         const int q = (unit >> 3) & 3, hb = (unit & 7) + 8 * (unit >> 5), b = hb >> 5, h = hb & 31;
;         const size_t rowbase = (size_t)b * SEQ; const int cbase = h * 64;
;         float kkc[4], kac[4], rkc[4]; WkvRaw raw;
; #pragma unroll
;         for (int e = 0; e < 4; ++e) { const int j = cbase + 4 * (tid & 15) + e; kkc[e] = W.kk[j]; kac[e] = W.ka[j]; rkc[e] = W.rk[j]; }
;         f32x2 S = {0.f, 0.f};
;         const int il = 2 * wave + (lane >> 5), jj = lane & 31;
.LBB0_1610:
	s_cmp_lt_i32 s84, 15
	s_cselect_b64 s[48:49], -1, 0
	s_and_b64 s[0:1], s[48:49], s[0:1]
	s_andn2_b64 vcc, exec, s[0:1]
	s_cbranch_vccnz .LBB0_1647
	s_mov_b64 s[52:53], s[78:79]
	s_cmpk_gt_i32 s2, 0xff
	s_cbranch_scc1 .LBB0_1647
	s_add_u32 s54, s52, 0x3500000
	s_addc_u32 s55, s53, 0
	s_add_u32 s56, s52, 0x7500000
	s_addc_u32 s57, s53, 0
	s_add_u32 s68, s52, 0x19500000
	s_addc_u32 s69, s53, 0
	s_add_u32 s86, s52, 0xb500000
	s_addc_u32 s87, s53, 0
	s_add_u32 s88, s52, 0xf500000
	s_addc_u32 s89, s53, 0
	s_add_u32 s90, s52, 0x1e500000
	v_and_b32_e32 v18, 15, v0
	v_and_b32_e32 v4, 0x1f0, v0
	s_addc_u32 s91, s53, 0
	s_add_i32 s3, 0, 0x18000
	v_lshlrev_b32_e32 v4, 2, v4
	v_lshlrev_b32_e32 v5, 4, v18
	v_add3_u32 v15, s3, v4, v5
	v_lshrrev_b32_e32 v5, 3, v0
	v_and_b32_e32 v5, 60, v5
	v_and_b32_e32 v6, 16, v0
	v_and_b32_e32 v2, 31, v0
	v_lshrrev_b32_e32 v14, 4, v0
	v_lshlrev_b32_e32 v20, 2, v18
	v_add_u32_e32 v21, s3, v5
	v_cmp_ne_u32_e64 s[4:5], 0, v6
	v_lshlrev_b32_e32 v6, 6, v18
	s_add_i32 s3, 0, 0x19000
	v_lshlrev_b32_e32 v1, 2, v0
	v_mov_b32_e32 v17, 0
	v_mul_u32_u24_e32 v3, 0x60, v0
	v_mad_u32_u24 v19, v2, 48, 0
	v_cmp_eq_u32_e64 s[6:7], 31, v2
	s_waitcnt vmcnt(1)
	v_add3_u32 v29, s3, v6, v5
	v_add3_u32 v60, s3, v4, v20
	v_cmp_eq_u32_e64 s[10:11], 16, v2
	v_cmp_eq_u32_e64 s[12:13], 17, v2
	v_cmp_eq_u32_e64 s[14:15], 18, v2
	v_cmp_eq_u32_e64 s[16:17], 19, v2
	v_cmp_eq_u32_e64 s[18:19], 20, v2
	v_cmp_eq_u32_e64 s[20:21], 21, v2
	v_cmp_eq_u32_e64 s[22:23], 22, v2
	v_cmp_eq_u32_e64 s[24:25], 23, v2
	v_cmp_eq_u32_e64 s[26:27], 24, v2
	v_cmp_eq_u32_e64 s[28:29], 25, v2
	v_cmp_eq_u32_e64 s[30:31], 26, v2
	v_cmp_eq_u32_e64 s[34:35], 27, v2
	v_cmp_eq_u32_e64 s[36:37], 28, v2
	v_cmp_eq_u32_e64 s[38:39], 29, v2
	v_cmp_eq_u32_e64 s[40:41], 30, v2
	v_and_b32_e32 v243, 8, v0
	v_cmp_ne_u32_e64 s[10:11], 0, v243
	v_and_b32_e32 v243, 4, v0
	v_cmp_ne_u32_e64 s[12:13], 0, v243
	v_and_b32_e32 v243, 2, v0
	v_cmp_ne_u32_e64 s[14:15], 0, v243
	v_and_b32_e32 v243, 1, v0
	v_cmp_ne_u32_e64 s[16:17], 0, v243
	v_lshlrev_b32_e32 v2, 12, v14
	v_lshlrev_b32_e32 v4, 1, v18
	s_mov_b32 s3, 0x13500000
	v_and_b32_e32 v1, 60, v1
	v_cmp_gt_u32_e64 s[0:1], 4, v18
	s_mov_b32 s93, 0
	v_cmp_eq_u32_e64 s[8:9], 0, v18
	v_add_u32_e32 v61, 0x10200, v19
	v_add_u32_e32 v62, 0x10220, v19
	v_add_u32_e32 v63, 0x10210, v19
	v_add_u32_e32 v64, 0x10800, v19
	v_add_u32_e32 v65, 0x10820, v19
	v_add_u32_e32 v66, 0x10810, v19
	v_add_u32_e32 v67, 0x10e00, v19
	v_add_u32_e32 v68, 0x10e20, v19
	v_add_u32_e32 v69, 0x10e10, v19
	v_add_u32_e32 v70, 0x11400, v19
	v_add_u32_e32 v71, 0x11420, v19
	v_add_u32_e32 v72, 0x11410, v19
	v_add_u32_e32 v73, 0x11a00, v19
	v_add_u32_e32 v74, 0x11a20, v19
	v_add_u32_e32 v75, 0x11a10, v19
	v_add_u32_e32 v76, 0x12000, v19
	v_add_u32_e32 v77, 0x12020, v19
	v_add_u32_e32 v78, 0x12010, v19
	v_add_u32_e32 v79, 0x12600, v19
	v_add_u32_e32 v80, 0x12620, v19
	v_add_u32_e32 v81, 0x12610, v19
	v_add_u32_e32 v82, 0x12c00, v19
	v_add_u32_e32 v83, 0x12c20, v19
	v_add_u32_e32 v84, 0x12c10, v19
	v_add_u32_e32 v85, 0x13200, v19
	v_add_u32_e32 v86, 0x13220, v19
	v_add_u32_e32 v87, 0x13210, v19
	v_add_u32_e32 v88, 0x13800, v19
	v_add_u32_e32 v89, 0x13820, v19
	s_waitcnt vmcnt(0)
	v_add_u32_e32 v90, 0x13810, v19
	v_add_u32_e32 v91, 0x13e00, v19
	v_add_u32_e32 v92, 0x13e20, v19
	v_add_u32_e32 v93, 0x13e10, v19
	v_add_u32_e32 v94, 0x14400, v19
	v_add_u32_e32 v95, 0x14420, v19
	v_add_u32_e32 v96, 0x14410, v19
	v_add_u32_e32 v97, 0x14a00, v19
	v_add_u32_e32 v98, 0x14a20, v19
	v_add_u32_e32 v99, 0x14a10, v19
	v_add_u32_e32 v100, 0x15000, v19
	v_add_u32_e32 v101, 0x15020, v19
	v_add_u32_e32 v102, 0x15010, v19
	v_add_u32_e32 v103, 0x15600, v19
	v_add_u32_e32 v104, 0x15620, v19
	v_add_u32_e32 v105, 0x15610, v19
	v_add_u32_e32 v106, 0x15c00, v19
	v_add_u32_e32 v107, 0x15c20, v19
	v_add_u32_e32 v108, 0x15c10, v19
	v_add_u32_e32 v109, 0x16200, v19
	v_add_u32_e32 v110, 0x16220, v19
	v_add_u32_e32 v111, 0x16210, v19
	v_add_u32_e32 v112, 0x16800, v19
	v_add_u32_e32 v113, 0x16820, v19
	v_add_u32_e32 v114, 0x16810, v19
	v_add_u32_e32 v115, 0x16e00, v19
	v_add_u32_e32 v116, 0x16e20, v19
	v_add_u32_e32 v117, 0x16e10, v19
	v_add_u32_e32 v118, 0x17400, v19
	v_add_u32_e32 v119, 0x17420, v19
	v_add_u32_e32 v120, 0x17410, v19
	v_add_u32_e32 v121, 0x17a00, v19
	v_add_u32_e32 v122, 0x17a20, v19
	v_add_u32_e32 v123, 0x17a10, v19
	v_lshlrev_b32_e32 v22, 10, v14
	v_mov_b32_e32 v23, v17
	v_or_b32_e32 v24, 0x13520000, v2
	v_mov_b32_e32 v25, v17
	v_lshlrev_b32_e32 v26, 7, v14
	v_mov_b32_e32 v27, v17
	v_lshl_or_b32 v28, v18, 3, v2
	v_or3_b32 v30, v2, v4, s3
	v_mov_b32_e32 v31, v17
	s_mov_b32 s3, 0xf800000
	v_mov_b32_e32 v124, 0x260
	s_mov_b64 s[94:95], 0x40000
	v_add_u32_e32 v125, 0, v3
	s_mov_b32 s44, s2
	s_mov_b32 s45, s2
	s_branch .LBB0_1614

; __device__ __forceinline__ void wkv_phase(const WkvT& W, unsigned char* lds) {
;     ...
;         const int q = (unit >> 3) & 3, hb = (unit & 7) + 8 * (unit >> 5), b = hb >> 5, h = hb & 31;
;         const size_t rowbase = (size_t)b * SEQ; const int cbase = h * 64;
;         float kkc[4], kac[4], rkc[4]; WkvRaw raw;
; #pragma unroll
;         for (int e = 0; e < 4; ++e) { const int j = cbase + 4 * (tid & 15) + e; kkc[e] = W.kk[j]; kac[e] = W.ka[j]; rkc[e] = W.rk[j]; }
;         f32x2 S = {0.f, 0.f};
;         const int il = 2 * wave + (lane >> 5), jj = lane & 31;
;         __syncthreads();
;         wkv_issue(W, raw, rowbase, cbase, q, 0, tid);
.LBB0_1620:
	s_or_b64 exec, exec, s[96:97]
	s_lshr_b32 s70, s45, 3
	s_bfe_u32 s71, s45, 0x20005
	s_and_b32 s73, s44, 7
	s_lshl_b32 s72, s71, 8
	s_lshl_b32 s74, s73, 5
	s_and_b32 s70, s70, 3
	s_or_b32 s72, s72, s74
	s_lshl_b32 s74, s70, 3
	s_or_b32 s74, s72, s74
	s_lshl_b32 s92, s70, 5
	s_lshl_b32 s70, s71, 9
	s_lshl_b32 s72, s73, 6
	s_or_b32 s70, s70, s72
	s_lshl_b32 s71, s71, 5
	s_lshl_b32 s72, s73, 2
	s_or_b32 s80, s71, s72
	s_lshl_b64 s[72:73], s[46:47], 23
	s_or_b32 s72, s72, s74
	v_lshl_add_u64 v[34:35], s[72:73], 0, v[22:23]
	s_lshl_b64 s[72:73], s[46:47], 25
	v_or_b32_e32 v16, s70, v18
	s_lshl_b32 s70, s70, 1
	s_mov_b32 s71, s93
	s_waitcnt lgkmcnt(0)
	s_barrier
	s_or_b32 s74, s72, s92
	s_mov_b32 s75, s73
	s_lshl_b64 s[46:47], s[46:47], 20
	v_mov_b32_e32 v41, s73
	v_or_b32_e32 v40, s72, v28
	v_lshlrev_b32_e32 v16, 1, v16
	v_lshl_add_u64 v[36:37], s[74:75], 0, v[24:25]
	s_or_b32 s46, s46, s80
	v_lshl_add_u64 v[40:41], v[40:41], 0, s[70:71]
	s_or_b32 s72, s74, s70
	v_lshl_add_u64 v[36:37], v[36:37], 0, v[16:17]
	v_lshl_add_u64 v[38:39], s[46:47], 0, v[26:27]
	v_lshl_add_u64 v[42:43], v[40:41], 0, s[92:93]
	v_lshl_add_u64 v[44:45], s[72:73], 0, v[30:31]
	v_mov_b32_e32 v140, 0
	s_movk_i32 s80, 0xfe
	v_mov_b32_e32 v141, 0
	v_mov_b32_e32 v142, 0
	v_mov_b32_e32 v143, 0
	v_mov_b32_e32 v144, 0
	v_mov_b32_e32 v145, 0
	v_mov_b32_e32 v146, 0
	v_mov_b32_e32 v147, 0
	v_mov_b32_e32 v148, 0
	v_mov_b32_e32 v149, 0
	s_branch .LBB0_1622

; __device__ __forceinline__ float wkv_reduce(float x, float y, float& zy) {
;     auto f = __builtin_amdgcn_permlane16_swap(__float_as_uint(x), __float_as_uint(y), false, false);
;     float z = __uint_as_float(f[0]) + __uint_as_float(f[1]);
;     z += dpp_f(z, 0); z += dpp_f(z, 1); z += dpp_f(z, 2); z += dpp_f(z, 3);
;     zy = z;
;     const int zi = __builtin_bit_cast(int, z);
;     return __builtin_bit_cast(float, __builtin_amdgcn_update_dpp(zi, zi, 0x142, 0xA, 0xF, false));
; }
; __device__ __forceinline__ void wkv_phase(const WkvT& W, unsigned char* lds) {
;     ...
;                 const float* pp = sP + bo + jj * 12;
;                 const float* pv = sV + bi * 512 + il;
;                 f32x4 nA = *(const f32x4*)pp, nB = *(const f32x4*)(pp + 4); f32x2 nr = *(const f32x2*)(pp + 8); float nv = pv[0];
;                 float yk0 = 0.f, yk1 = 0.f, ep = 0.f;
;                 const bool oddrow = (lane & 16) != 0;
; #pragma unroll
;                 for (int t = 0; t < 32; ++t) {
;                     const f32x2 a2 = {nA[0], nA[1]}, w2 = {nA[2], nA[3]}, b2 = {nB[0], nB[1]}, k2 = {nB[2], nB[3]}, r2 = nr; const float v = nv;
;                     if (t + 1 < 32) { nA = *(const f32x4*)(pp + (t + 1) * 384); nB = *(const f32x4*)(pp + (t + 1) * 384 + 4); nr = *(const f32x2*)(pp + (t + 1) * 384 + 8); nv = pv[(t + 1) * 16]; }
;                     float S0 = S.x, S1 = S.y;
;                     float d = S0 * a2.x; d = __builtin_fmaf(S1, a2.y, d);
;                     float t0 = S0 * w2.x; t0 = __builtin_fmaf(v, k2.x, t0); asm volatile("" : "+v"(t0));
;                     float t1 = S1 * w2.y; t1 = __builtin_fmaf(v, k2.y, t1); asm volatile("" : "+v"(t1));
;                     float yprev; const float sa = wkv_reduce(d, ep, yprev);
;                     S0 = __builtin_fmaf(sa, b2.x, t0); asm volatile("" : "+v"(S0));
;                     S1 = __builtin_fmaf(sa, b2.y, t1); asm volatile("" : "+v"(S1));
;                     ep = S0 * r2.x; ep = __builtin_fmaf(S1, r2.y, ep);
;                     S.x = S0; S.y = S1;
;                     if (t >= 1) { const bool hit = oddrow && ((lane & 15) == ((t - 1) & 15)); if (t <= 16) yk0 = hit ? yprev : yk0; else yk1 = hit ? yprev : yk1; }
.LBB0_1624:
	s_or_b64 exec, exec, s[46:47]
	v_readfirstlane_b32 s99, v0
	s_nop 3
	s_bitcmp1_b32 s99, 8
	s_cbranch_scc1 .Lwkv4_b1_skip
	v_mul_u32_u24_e32 v182, 0x60, v18
	v_and_b32_e32 v188, 8, v18
	v_mul_u32_u24_e32 v183, 0xc0, v18
	v_mad_u32_u24 v182, v188, 6, v182
	v_add_u32_e32 v183, 48, v183
	v_lshrrev_b32_e32 v188, 4, v0
	v_sub_u32_e32 v183, v183, v182
	v_lshlrev_b32_e32 v188, 2, v188
	v_add_u32_e32 v184, 0x10200, v182
	v_add_u32_e32 v186, 0x18000, v188
	v_add_u32_e32 v185, 0x10200, v183
	v_lshl_add_u32 v187, v18, 6, v188
	v_add_u32_e32 v187, 0x19000, v187
	ds_read_b128 v[190:193], v182
	ds_read_b128 v[194:197], v182 offset:16
	ds_read_b64 v[228:229], v182 offset:32
	ds_read_b128 v[198:201], v183
	ds_read_b128 v[202:205], v183 offset:16
	ds_read_b64 v[230:231], v183 offset:32
	ds_read_b32 v240, v186 offset:0
	ds_read_b128 v[206:209], v182 offset:1536
	ds_read_b128 v[210:213], v182 offset:1552
	ds_read_b64 v[232:233], v182 offset:1568
	ds_read_b128 v[214:217], v183 offset:1536
	ds_read_b128 v[218:221], v183 offset:1552
	ds_read_b64 v[234:235], v183 offset:1568
	ds_read_b32 v241, v186 offset:64
	s_waitcnt lgkmcnt(7)
	v_pk_mul_f32 v[150:151], v[142:143], v[190:191]
	v_pk_fma_f32 v[150:151], v[144:145], v[198:199], v[150:151]
	v_pk_mul_f32 v[146:147], v[142:143], v[192:193]
	v_add_f32_e32 v154, v150, v151
	v_pk_mul_f32 v[148:149], v[144:145], v[200:201]
	v_pk_fma_f32 v[146:147], v[240:241], v[196:197], v[146:147] op_sel:[0,0,0] op_sel_hi:[0,1,1]
	v_add_f32_dpp v154, v154, v154 quad_perm:[1,0,3,2] row_mask:0xf bank_mask:0xf bound_ctrl:1
	v_pk_fma_f32 v[148:149], v[240:241], v[204:205], v[148:149] op_sel:[0,0,0] op_sel_hi:[0,1,1]
	s_nop 0
	v_add_f32_dpp v154, v154, v154 quad_perm:[2,3,0,1] row_mask:0xf bank_mask:0xf bound_ctrl:1
	ds_read_b128 v[126:129], v182 offset:3072
	ds_read_b128 v[130:133], v182 offset:3088
	v_add_f32_dpp v154, v154, v154 row_half_mirror row_mask:0xf bank_mask:0xf bound_ctrl:1
	ds_read_b64 v[236:237], v182 offset:3104
	ds_read_b128 v[134:137], v183 offset:3072
	v_add_f32_dpp v154, v154, v154 row_mirror row_mask:0xf bank_mask:0xf bound_ctrl:1
	v_pk_fma_f32 v[146:147], v[154:155], v[194:195], v[146:147] op_sel_hi:[0,1,1]
	v_pk_fma_f32 v[148:149], v[154:155], v[202:203], v[148:149] op_sel_hi:[0,1,1]
	ds_read_b128 v[222:225], v183 offset:3088
	ds_read_b64 v[238:239], v183 offset:3104
	ds_read_b32 v242, v186 offset:128
	s_waitcnt lgkmcnt(7)
	v_pk_mul_f32 v[150:151], v[146:147], v[206:207]
	v_pk_fma_f32 v[150:151], v[148:149], v[214:215], v[150:151]
	v_pk_mul_f32 v[152:153], v[146:147], v[228:229]
	v_add_f32_e32 v154, v150, v151
	v_pk_fma_f32 v[152:153], v[148:149], v[230:231], v[152:153]
	v_pk_mul_f32 v[142:143], v[146:147], v[208:209]
	v_add_f32_dpp v154, v154, v154 quad_perm:[1,0,3,2] row_mask:0xf bank_mask:0xf bound_ctrl:1
	v_pk_mul_f32 v[144:145], v[148:149], v[216:217]
	v_add_f32_e32 v156, v152, v153
	v_add_f32_dpp v154, v154, v154 quad_perm:[2,3,0,1] row_mask:0xf bank_mask:0xf bound_ctrl:1
	v_pk_fma_f32 v[142:143], v[240:241], v[212:213], v[142:143] op_sel:[1,0,0] op_sel_hi:[1,1,1]
	v_pk_fma_f32 v[144:145], v[240:241], v[220:221], v[144:145] op_sel:[1,0,0] op_sel_hi:[1,1,1]
	v_add_f32_dpp v154, v154, v154 row_half_mirror row_mask:0xf bank_mask:0xf bound_ctrl:1
	ds_read_b128 v[190:193], v182 offset:4608
	ds_read_b128 v[194:197], v182 offset:4624
	v_add_f32_dpp v154, v154, v154 row_mirror row_mask:0xf bank_mask:0xf bound_ctrl:1
	ds_read_b64 v[228:229], v182 offset:4640
	ds_read_b128 v[198:201], v183 offset:4608
	v_pk_fma_f32 v[142:143], v[154:155], v[210:211], v[142:143] op_sel_hi:[0,1,1]
	v_pk_fma_f32 v[144:145], v[154:155], v[218:219], v[144:145] op_sel_hi:[0,1,1]
	ds_read_b128 v[202:205], v183 offset:4624
	ds_read_b64 v[230:231], v183 offset:4640
	ds_read_b32 v240, v186 offset:192
	s_waitcnt lgkmcnt(7)
	v_pk_mul_f32 v[150:151], v[142:143], v[126:127]
	v_pk_fma_f32 v[150:151], v[144:145], v[134:135], v[150:151]
	v_pk_mul_f32 v[152:153], v[142:143], v[232:233]
	v_add_f32_e32 v154, v150, v151
	v_pk_fma_f32 v[152:153], v[144:145], v[234:235], v[152:153]
	v_pk_mul_f32 v[146:147], v[142:143], v[128:129]
	v_add_f32_dpp v154, v154, v154 quad_perm:[1,0,3,2] row_mask:0xf bank_mask:0xf bound_ctrl:1
	v_pk_mul_f32 v[148:149], v[144:145], v[136:137]
	v_add_f32_e32 v157, v152, v153
	v_add_f32_dpp v154, v154, v154 quad_perm:[2,3,0,1] row_mask:0xf bank_mask:0xf bound_ctrl:1
	v_pk_fma_f32 v[146:147], v[242:243], v[132:133], v[146:147] op_sel:[0,0,0] op_sel_hi:[0,1,1]
	v_pk_fma_f32 v[148:149], v[242:243], v[224:225], v[148:149] op_sel:[0,0,0] op_sel_hi:[0,1,1]
	v_add_f32_dpp v154, v154, v154 row_half_mirror row_mask:0xf bank_mask:0xf bound_ctrl:1
	ds_read_b128 v[206:209], v182 offset:6144
	ds_read_b128 v[210:213], v182 offset:6160
	v_add_f32_dpp v154, v154, v154 row_mirror row_mask:0xf bank_mask:0xf bound_ctrl:1
	ds_read_b64 v[232:233], v182 offset:6176
	ds_read_b128 v[214:217], v183 offset:6144
	v_pk_fma_f32 v[146:147], v[154:155], v[130:131], v[146:147] op_sel_hi:[0,1,1]
	v_pk_fma_f32 v[148:149], v[154:155], v[222:223], v[148:149] op_sel_hi:[0,1,1]
	ds_read_b128 v[218:221], v183 offset:6160
	ds_read_b64 v[234:235], v183 offset:6176
	ds_read_b32 v241, v186 offset:256
	s_waitcnt lgkmcnt(7)
; __device__ __forceinline__ float wkv_reduce(float x, float y, float& zy) {
;     auto f = __builtin_amdgcn_permlane16_swap(__float_as_uint(x), __float_as_uint(y), false, false);
;     float z = __uint_as_float(f[0]) + __uint_as_float(f[1]);
;     z += dpp_f(z, 0); z += dpp_f(z, 1); z += dpp_f(z, 2); z += dpp_f(z, 3);
;     zy = z;
;     const int zi = __builtin_bit_cast(int, z);
;     return __builtin_bit_cast(float, __builtin_amdgcn_update_dpp(zi, zi, 0x142, 0xA, 0xF, false));
; }
; __device__ __forceinline__ void wkv_phase(const WkvT& W, unsigned char* lds) {
;     ...
;                 const float* pp = sP + bo + jj * 12;
;                 const float* pv = sV + bi * 512 + il;
;                 f32x4 nA = *(const f32x4*)pp, nB = *(const f32x4*)(pp + 4); f32x2 nr = *(const f32x2*)(pp + 8); float nv = pv[0];
;                 float yk0 = 0.f, yk1 = 0.f, ep = 0.f;
;                 const bool oddrow = (lane & 16) != 0;
; #pragma unroll
;                 for (int t = 0; t < 32; ++t) {
;                     const f32x2 a2 = {nA[0], nA[1]}, w2 = {nA[2], nA[3]}, b2 = {nB[0], nB[1]}, k2 = {nB[2], nB[3]}, r2 = nr; const float v = nv;
;                     if (t + 1 < 32) { nA = *(const f32x4*)(pp + (t + 1) * 384); nB = *(const f32x4*)(pp + (t + 1) * 384 + 4); nr = *(const f32x2*)(pp + (t + 1) * 384 + 8); nv = pv[(t + 1) * 16]; }
;                     float S0 = S.x, S1 = S.y;
;                     float d = S0 * a2.x; d = __builtin_fmaf(S1, a2.y, d);
;                     float t0 = S0 * w2.x; t0 = __builtin_fmaf(v, k2.x, t0); asm volatile("" : "+v"(t0));
;                     float t1 = S1 * w2.y; t1 = __builtin_fmaf(v, k2.y, t1); asm volatile("" : "+v"(t1));
;                     float yprev; const float sa = wkv_reduce(d, ep, yprev);
;                     S0 = __builtin_fmaf(sa, b2.x, t0); asm volatile("" : "+v"(S0));
;                     S1 = __builtin_fmaf(sa, b2.y, t1); asm volatile("" : "+v"(S1));
;                     ep = S0 * r2.x; ep = __builtin_fmaf(S1, r2.y, ep);
;                     S.x = S0; S.y = S1;
;                     if (t >= 1) { const bool hit = oddrow && ((lane & 15) == ((t - 1) & 15)); if (t <= 16) yk0 = hit ? yprev : yk0; else yk1 = hit ? yprev : yk1; }
	v_pk_mul_f32 v[150:151], v[146:147], v[190:191]
	v_pk_fma_f32 v[150:151], v[148:149], v[198:199], v[150:151]
	v_pk_mul_f32 v[152:153], v[146:147], v[236:237]
	v_add_f32_e32 v154, v150, v151
	v_pk_fma_f32 v[152:153], v[148:149], v[238:239], v[152:153]
	v_pk_mul_f32 v[142:143], v[146:147], v[192:193]
	v_add_f32_dpp v154, v154, v154 quad_perm:[1,0,3,2] row_mask:0xf bank_mask:0xf bound_ctrl:1
	v_pk_mul_f32 v[144:145], v[148:149], v[200:201]
	v_add_f32_e32 v158, v152, v153
	v_add_f32_dpp v154, v154, v154 quad_perm:[2,3,0,1] row_mask:0xf bank_mask:0xf bound_ctrl:1
	v_pk_fma_f32 v[142:143], v[240:241], v[196:197], v[142:143] op_sel:[0,0,0] op_sel_hi:[0,1,1]
	v_pk_fma_f32 v[144:145], v[240:241], v[204:205], v[144:145] op_sel:[0,0,0] op_sel_hi:[0,1,1]
	v_add_f32_dpp v154, v154, v154 row_half_mirror row_mask:0xf bank_mask:0xf bound_ctrl:1
	ds_read_b128 v[126:129], v182 offset:7680
	ds_read_b128 v[130:133], v182 offset:7696
	v_add_f32_dpp v154, v154, v154 row_mirror row_mask:0xf bank_mask:0xf bound_ctrl:1
	ds_read_b64 v[236:237], v182 offset:7712
	ds_read_b128 v[134:137], v183 offset:7680
	v_pk_fma_f32 v[142:143], v[154:155], v[194:195], v[142:143] op_sel_hi:[0,1,1]
	v_pk_fma_f32 v[144:145], v[154:155], v[202:203], v[144:145] op_sel_hi:[0,1,1]
	ds_read_b128 v[222:225], v183 offset:7696
	ds_read_b64 v[238:239], v183 offset:7712
	ds_read_b32 v242, v186 offset:320
	s_waitcnt lgkmcnt(7)
	v_pk_mul_f32 v[150:151], v[142:143], v[206:207]
	v_pk_fma_f32 v[150:151], v[144:145], v[214:215], v[150:151]
	v_pk_mul_f32 v[152:153], v[142:143], v[228:229]
	v_add_f32_e32 v154, v150, v151
	v_pk_fma_f32 v[152:153], v[144:145], v[230:231], v[152:153]
	v_pk_mul_f32 v[146:147], v[142:143], v[208:209]
	v_add_f32_dpp v154, v154, v154 quad_perm:[1,0,3,2] row_mask:0xf bank_mask:0xf bound_ctrl:1
	v_pk_mul_f32 v[148:149], v[144:145], v[216:217]
	v_add_f32_e32 v159, v152, v153
	v_add_f32_dpp v154, v154, v154 quad_perm:[2,3,0,1] row_mask:0xf bank_mask:0xf bound_ctrl:1
	v_pk_fma_f32 v[146:147], v[240:241], v[212:213], v[146:147] op_sel:[1,0,0] op_sel_hi:[1,1,1]
	v_pk_fma_f32 v[148:149], v[240:241], v[220:221], v[148:149] op_sel:[1,0,0] op_sel_hi:[1,1,1]
	v_add_f32_dpp v154, v154, v154 row_half_mirror row_mask:0xf bank_mask:0xf bound_ctrl:1
	ds_read_b128 v[190:193], v182 offset:9216
	ds_read_b128 v[194:197], v182 offset:9232
	v_add_f32_dpp v154, v154, v154 row_mirror row_mask:0xf bank_mask:0xf bound_ctrl:1
	ds_read_b64 v[228:229], v182 offset:9248
	ds_read_b128 v[198:201], v183 offset:9216
	v_pk_fma_f32 v[146:147], v[154:155], v[210:211], v[146:147] op_sel_hi:[0,1,1]
	v_pk_fma_f32 v[148:149], v[154:155], v[218:219], v[148:149] op_sel_hi:[0,1,1]
	ds_read_b128 v[202:205], v183 offset:9232
	ds_read_b64 v[230:231], v183 offset:9248
	ds_read_b32 v240, v186 offset:384
	s_waitcnt lgkmcnt(7)
	v_pk_mul_f32 v[150:151], v[146:147], v[126:127]
	v_pk_fma_f32 v[150:151], v[148:149], v[134:135], v[150:151]
	v_pk_mul_f32 v[152:153], v[146:147], v[232:233]
	v_add_f32_e32 v154, v150, v151
	v_pk_fma_f32 v[152:153], v[148:149], v[234:235], v[152:153]
	v_pk_mul_f32 v[142:143], v[146:147], v[128:129]
	v_add_f32_dpp v154, v154, v154 quad_perm:[1,0,3,2] row_mask:0xf bank_mask:0xf bound_ctrl:1
	v_pk_mul_f32 v[144:145], v[148:149], v[136:137]
	v_add_f32_e32 v160, v152, v153
	v_add_f32_dpp v154, v154, v154 quad_perm:[2,3,0,1] row_mask:0xf bank_mask:0xf bound_ctrl:1
	v_pk_fma_f32 v[142:143], v[242:243], v[132:133], v[142:143] op_sel:[0,0,0] op_sel_hi:[0,1,1]
	v_pk_fma_f32 v[144:145], v[242:243], v[224:225], v[144:145] op_sel:[0,0,0] op_sel_hi:[0,1,1]
	v_add_f32_dpp v154, v154, v154 row_half_mirror row_mask:0xf bank_mask:0xf bound_ctrl:1
	ds_read_b128 v[206:209], v182 offset:10752
	ds_read_b128 v[210:213], v182 offset:10768
	v_add_f32_dpp v154, v154, v154 row_mirror row_mask:0xf bank_mask:0xf bound_ctrl:1
	ds_read_b64 v[232:233], v182 offset:10784
	ds_read_b128 v[214:217], v183 offset:10752
	v_pk_fma_f32 v[142:143], v[154:155], v[130:131], v[142:143] op_sel_hi:[0,1,1]
	v_pk_fma_f32 v[144:145], v[154:155], v[222:223], v[144:145] op_sel_hi:[0,1,1]
	ds_read_b128 v[218:221], v183 offset:10768
	ds_read_b64 v[234:235], v183 offset:10784
	ds_read_b32 v241, v186 offset:448
	s_waitcnt lgkmcnt(7)
	v_pk_mul_f32 v[150:151], v[142:143], v[190:191]
	v_pk_fma_f32 v[150:151], v[144:145], v[198:199], v[150:151]
	v_pk_mul_f32 v[152:153], v[142:143], v[236:237]
	v_add_f32_e32 v154, v150, v151
	v_pk_fma_f32 v[152:153], v[144:145], v[238:239], v[152:153]
	v_pk_mul_f32 v[146:147], v[142:143], v[192:193]
	v_add_f32_dpp v154, v154, v154 quad_perm:[1,0,3,2] row_mask:0xf bank_mask:0xf bound_ctrl:1
	v_pk_mul_f32 v[148:149], v[144:145], v[200:201]
	v_add_f32_e32 v161, v152, v153
	v_add_f32_dpp v154, v154, v154 quad_perm:[2,3,0,1] row_mask:0xf bank_mask:0xf bound_ctrl:1
	v_pk_fma_f32 v[146:147], v[240:241], v[196:197], v[146:147] op_sel:[0,0,0] op_sel_hi:[0,1,1]
	v_pk_fma_f32 v[148:149], v[240:241], v[204:205], v[148:149] op_sel:[0,0,0] op_sel_hi:[0,1,1]
	v_add_f32_dpp v154, v154, v154 row_half_mirror row_mask:0xf bank_mask:0xf bound_ctrl:1
	ds_read_b128 v[126:129], v182 offset:12288
	ds_read_b128 v[130:133], v182 offset:12304
	v_add_f32_dpp v154, v154, v154 row_mirror row_mask:0xf bank_mask:0xf bound_ctrl:1
	ds_read_b64 v[236:237], v182 offset:12320
	ds_read_b128 v[134:137], v183 offset:12288
	v_pk_fma_f32 v[146:147], v[154:155], v[194:195], v[146:147] op_sel_hi:[0,1,1]
	v_pk_fma_f32 v[148:149], v[154:155], v[202:203], v[148:149] op_sel_hi:[0,1,1]
	ds_read_b128 v[222:225], v183 offset:12304
	ds_read_b64 v[238:239], v183 offset:12320
	ds_read_b32 v242, v186 offset:512
	s_waitcnt lgkmcnt(7)
; __device__ __forceinline__ float wkv_reduce(float x, float y, float& zy) {
;     auto f = __builtin_amdgcn_permlane16_swap(__float_as_uint(x), __float_as_uint(y), false, false);
;     float z = __uint_as_float(f[0]) + __uint_as_float(f[1]);
;     z += dpp_f(z, 0); z += dpp_f(z, 1); z += dpp_f(z, 2); z += dpp_f(z, 3);
;     zy = z;
;     const int zi = __builtin_bit_cast(int, z);
;     return __builtin_bit_cast(float, __builtin_amdgcn_update_dpp(zi, zi, 0x142, 0xA, 0xF, false));
; }
; __device__ __forceinline__ void wkv_phase(const WkvT& W, unsigned char* lds) {
;     ...
;                 const float* pp = sP + bo + jj * 12;
;                 const float* pv = sV + bi * 512 + il;
;                 f32x4 nA = *(const f32x4*)pp, nB = *(const f32x4*)(pp + 4); f32x2 nr = *(const f32x2*)(pp + 8); float nv = pv[0];
;                 float yk0 = 0.f, yk1 = 0.f, ep = 0.f;
;                 const bool oddrow = (lane & 16) != 0;
; #pragma unroll
;                 for (int t = 0; t < 32; ++t) {
;                     const f32x2 a2 = {nA[0], nA[1]}, w2 = {nA[2], nA[3]}, b2 = {nB[0], nB[1]}, k2 = {nB[2], nB[3]}, r2 = nr; const float v = nv;
;                     if (t + 1 < 32) { nA = *(const f32x4*)(pp + (t + 1) * 384); nB = *(const f32x4*)(pp + (t + 1) * 384 + 4); nr = *(const f32x2*)(pp + (t + 1) * 384 + 8); nv = pv[(t + 1) * 16]; }
;                     float S0 = S.x, S1 = S.y;
;                     float d = S0 * a2.x; d = __builtin_fmaf(S1, a2.y, d);
;                     float t0 = S0 * w2.x; t0 = __builtin_fmaf(v, k2.x, t0); asm volatile("" : "+v"(t0));
;                     float t1 = S1 * w2.y; t1 = __builtin_fmaf(v, k2.y, t1); asm volatile("" : "+v"(t1));
;                     float yprev; const float sa = wkv_reduce(d, ep, yprev);
;                     S0 = __builtin_fmaf(sa, b2.x, t0); asm volatile("" : "+v"(S0));
;                     S1 = __builtin_fmaf(sa, b2.y, t1); asm volatile("" : "+v"(S1));
;                     ep = S0 * r2.x; ep = __builtin_fmaf(S1, r2.y, ep);
;                     S.x = S0; S.y = S1;
;                     if (t >= 1) { const bool hit = oddrow && ((lane & 15) == ((t - 1) & 15)); if (t <= 16) yk0 = hit ? yprev : yk0; else yk1 = hit ? yprev : yk1; }
	v_pk_mul_f32 v[150:151], v[146:147], v[206:207]
	v_pk_fma_f32 v[150:151], v[148:149], v[214:215], v[150:151]
	v_pk_mul_f32 v[152:153], v[146:147], v[228:229]
	v_add_f32_e32 v154, v150, v151
	v_pk_fma_f32 v[152:153], v[148:149], v[230:231], v[152:153]
	v_pk_mul_f32 v[142:143], v[146:147], v[208:209]
	v_add_f32_dpp v154, v154, v154 quad_perm:[1,0,3,2] row_mask:0xf bank_mask:0xf bound_ctrl:1
	v_pk_mul_f32 v[144:145], v[148:149], v[216:217]
	v_add_f32_e32 v162, v152, v153
	v_add_f32_dpp v154, v154, v154 quad_perm:[2,3,0,1] row_mask:0xf bank_mask:0xf bound_ctrl:1
	v_pk_fma_f32 v[142:143], v[240:241], v[212:213], v[142:143] op_sel:[1,0,0] op_sel_hi:[1,1,1]
	v_pk_fma_f32 v[144:145], v[240:241], v[220:221], v[144:145] op_sel:[1,0,0] op_sel_hi:[1,1,1]
	v_add_f32_dpp v154, v154, v154 row_half_mirror row_mask:0xf bank_mask:0xf bound_ctrl:1
	ds_read_b128 v[190:193], v182 offset:13824
	ds_read_b128 v[194:197], v182 offset:13840
	v_add_f32_dpp v154, v154, v154 row_mirror row_mask:0xf bank_mask:0xf bound_ctrl:1
	ds_read_b64 v[228:229], v182 offset:13856
	ds_read_b128 v[198:201], v183 offset:13824
	v_pk_fma_f32 v[142:143], v[154:155], v[210:211], v[142:143] op_sel_hi:[0,1,1]
	v_pk_fma_f32 v[144:145], v[154:155], v[218:219], v[144:145] op_sel_hi:[0,1,1]
	ds_read_b128 v[202:205], v183 offset:13840
	ds_read_b64 v[230:231], v183 offset:13856
	ds_read_b32 v240, v186 offset:576
	s_waitcnt lgkmcnt(7)
	v_pk_mul_f32 v[150:151], v[142:143], v[126:127]
	v_pk_fma_f32 v[150:151], v[144:145], v[134:135], v[150:151]
	v_pk_mul_f32 v[152:153], v[142:143], v[232:233]
	v_add_f32_e32 v154, v150, v151
	v_pk_fma_f32 v[152:153], v[144:145], v[234:235], v[152:153]
	v_pk_mul_f32 v[146:147], v[142:143], v[128:129]
	v_add_f32_dpp v154, v154, v154 quad_perm:[1,0,3,2] row_mask:0xf bank_mask:0xf bound_ctrl:1
	v_pk_mul_f32 v[148:149], v[144:145], v[136:137]
	v_add_f32_e32 v163, v152, v153
	v_add_f32_dpp v154, v154, v154 quad_perm:[2,3,0,1] row_mask:0xf bank_mask:0xf bound_ctrl:1
	v_pk_fma_f32 v[146:147], v[242:243], v[132:133], v[146:147] op_sel:[0,0,0] op_sel_hi:[0,1,1]
	v_pk_fma_f32 v[148:149], v[242:243], v[224:225], v[148:149] op_sel:[0,0,0] op_sel_hi:[0,1,1]
	v_add_f32_dpp v154, v154, v154 row_half_mirror row_mask:0xf bank_mask:0xf bound_ctrl:1
	ds_read_b128 v[206:209], v182 offset:15360
	ds_read_b128 v[210:213], v182 offset:15376
	v_add_f32_dpp v154, v154, v154 row_mirror row_mask:0xf bank_mask:0xf bound_ctrl:1
	ds_read_b64 v[232:233], v182 offset:15392
	ds_read_b128 v[214:217], v183 offset:15360
	v_pk_fma_f32 v[146:147], v[154:155], v[130:131], v[146:147] op_sel_hi:[0,1,1]
	v_pk_fma_f32 v[148:149], v[154:155], v[222:223], v[148:149] op_sel_hi:[0,1,1]
	ds_read_b128 v[218:221], v183 offset:15376
	ds_read_b64 v[234:235], v183 offset:15392
	ds_read_b32 v241, v186 offset:640
	s_waitcnt lgkmcnt(7)
	v_pk_mul_f32 v[150:151], v[146:147], v[190:191]
	v_pk_fma_f32 v[150:151], v[148:149], v[198:199], v[150:151]
	v_pk_mul_f32 v[152:153], v[146:147], v[236:237]
	v_add_f32_e32 v154, v150, v151
	v_pk_fma_f32 v[152:153], v[148:149], v[238:239], v[152:153]
	v_pk_mul_f32 v[142:143], v[146:147], v[192:193]
	v_add_f32_dpp v154, v154, v154 quad_perm:[1,0,3,2] row_mask:0xf bank_mask:0xf bound_ctrl:1
	v_pk_mul_f32 v[144:145], v[148:149], v[200:201]
	v_add_f32_e32 v164, v152, v153
	v_add_f32_dpp v154, v154, v154 quad_perm:[2,3,0,1] row_mask:0xf bank_mask:0xf bound_ctrl:1
	v_pk_fma_f32 v[142:143], v[240:241], v[196:197], v[142:143] op_sel:[0,0,0] op_sel_hi:[0,1,1]
	v_pk_fma_f32 v[144:145], v[240:241], v[204:205], v[144:145] op_sel:[0,0,0] op_sel_hi:[0,1,1]
	v_add_f32_dpp v154, v154, v154 row_half_mirror row_mask:0xf bank_mask:0xf bound_ctrl:1
	ds_read_b128 v[126:129], v182 offset:16896
	ds_read_b128 v[130:133], v182 offset:16912
	v_add_f32_dpp v154, v154, v154 row_mirror row_mask:0xf bank_mask:0xf bound_ctrl:1
	ds_read_b64 v[236:237], v182 offset:16928
	ds_read_b128 v[134:137], v183 offset:16896
	v_pk_fma_f32 v[142:143], v[154:155], v[194:195], v[142:143] op_sel_hi:[0,1,1]
	v_pk_fma_f32 v[144:145], v[154:155], v[202:203], v[144:145] op_sel_hi:[0,1,1]
	ds_read_b128 v[222:225], v183 offset:16912
	ds_read_b64 v[238:239], v183 offset:16928
	ds_read_b32 v242, v186 offset:704
	s_waitcnt lgkmcnt(7)
	v_pk_mul_f32 v[150:151], v[142:143], v[206:207]
	v_pk_fma_f32 v[150:151], v[144:145], v[214:215], v[150:151]
	v_pk_mul_f32 v[152:153], v[142:143], v[228:229]
	v_add_f32_e32 v154, v150, v151
	v_pk_fma_f32 v[152:153], v[144:145], v[230:231], v[152:153]
	v_pk_mul_f32 v[146:147], v[142:143], v[208:209]
	v_add_f32_dpp v154, v154, v154 quad_perm:[1,0,3,2] row_mask:0xf bank_mask:0xf bound_ctrl:1
	v_pk_mul_f32 v[148:149], v[144:145], v[216:217]
	v_add_f32_e32 v165, v152, v153
	v_add_f32_dpp v154, v154, v154 quad_perm:[2,3,0,1] row_mask:0xf bank_mask:0xf bound_ctrl:1
	v_pk_fma_f32 v[146:147], v[240:241], v[212:213], v[146:147] op_sel:[1,0,0] op_sel_hi:[1,1,1]
	v_pk_fma_f32 v[148:149], v[240:241], v[220:221], v[148:149] op_sel:[1,0,0] op_sel_hi:[1,1,1]
	v_add_f32_dpp v154, v154, v154 row_half_mirror row_mask:0xf bank_mask:0xf bound_ctrl:1
	ds_read_b128 v[190:193], v182 offset:18432
	ds_read_b128 v[194:197], v182 offset:18448
	v_add_f32_dpp v154, v154, v154 row_mirror row_mask:0xf bank_mask:0xf bound_ctrl:1
	ds_read_b64 v[228:229], v182 offset:18464
	ds_read_b128 v[198:201], v183 offset:18432
	v_pk_fma_f32 v[146:147], v[154:155], v[210:211], v[146:147] op_sel_hi:[0,1,1]
	v_pk_fma_f32 v[148:149], v[154:155], v[218:219], v[148:149] op_sel_hi:[0,1,1]
	ds_read_b128 v[202:205], v183 offset:18448
	ds_read_b64 v[230:231], v183 offset:18464
	ds_read_b32 v240, v186 offset:768
	s_waitcnt lgkmcnt(7)
; __device__ __forceinline__ float wkv_reduce(float x, float y, float& zy) {
;     auto f = __builtin_amdgcn_permlane16_swap(__float_as_uint(x), __float_as_uint(y), false, false);
;     float z = __uint_as_float(f[0]) + __uint_as_float(f[1]);
;     z += dpp_f(z, 0); z += dpp_f(z, 1); z += dpp_f(z, 2); z += dpp_f(z, 3);
;     zy = z;
;     const int zi = __builtin_bit_cast(int, z);
;     return __builtin_bit_cast(float, __builtin_amdgcn_update_dpp(zi, zi, 0x142, 0xA, 0xF, false));
; }
; __device__ __forceinline__ void wkv_phase(const WkvT& W, unsigned char* lds) {
;     ...
;                 const float* pp = sP + bo + jj * 12;
;                 const float* pv = sV + bi * 512 + il;
;                 f32x4 nA = *(const f32x4*)pp, nB = *(const f32x4*)(pp + 4); f32x2 nr = *(const f32x2*)(pp + 8); float nv = pv[0];
;                 float yk0 = 0.f, yk1 = 0.f, ep = 0.f;
;                 const bool oddrow = (lane & 16) != 0;
; #pragma unroll
;                 for (int t = 0; t < 32; ++t) {
;                     const f32x2 a2 = {nA[0], nA[1]}, w2 = {nA[2], nA[3]}, b2 = {nB[0], nB[1]}, k2 = {nB[2], nB[3]}, r2 = nr; const float v = nv;
;                     if (t + 1 < 32) { nA = *(const f32x4*)(pp + (t + 1) * 384); nB = *(const f32x4*)(pp + (t + 1) * 384 + 4); nr = *(const f32x2*)(pp + (t + 1) * 384 + 8); nv = pv[(t + 1) * 16]; }
;                     float S0 = S.x, S1 = S.y;
;                     float d = S0 * a2.x; d = __builtin_fmaf(S1, a2.y, d);
;                     float t0 = S0 * w2.x; t0 = __builtin_fmaf(v, k2.x, t0); asm volatile("" : "+v"(t0));
;                     float t1 = S1 * w2.y; t1 = __builtin_fmaf(v, k2.y, t1); asm volatile("" : "+v"(t1));
;                     float yprev; const float sa = wkv_reduce(d, ep, yprev);
;                     S0 = __builtin_fmaf(sa, b2.x, t0); asm volatile("" : "+v"(S0));
;                     S1 = __builtin_fmaf(sa, b2.y, t1); asm volatile("" : "+v"(S1));
;                     ep = S0 * r2.x; ep = __builtin_fmaf(S1, r2.y, ep);
;                     S.x = S0; S.y = S1;
;                     if (t >= 1) { const bool hit = oddrow && ((lane & 15) == ((t - 1) & 15)); if (t <= 16) yk0 = hit ? yprev : yk0; else yk1 = hit ? yprev : yk1; }
	v_pk_mul_f32 v[150:151], v[146:147], v[126:127]
	v_pk_fma_f32 v[150:151], v[148:149], v[134:135], v[150:151]
	v_pk_mul_f32 v[152:153], v[146:147], v[232:233]
	v_add_f32_e32 v154, v150, v151
	v_pk_fma_f32 v[152:153], v[148:149], v[234:235], v[152:153]
	v_pk_mul_f32 v[142:143], v[146:147], v[128:129]
	v_add_f32_dpp v154, v154, v154 quad_perm:[1,0,3,2] row_mask:0xf bank_mask:0xf bound_ctrl:1
	v_pk_mul_f32 v[144:145], v[148:149], v[136:137]
	v_add_f32_e32 v166, v152, v153
	v_add_f32_dpp v154, v154, v154 quad_perm:[2,3,0,1] row_mask:0xf bank_mask:0xf bound_ctrl:1
	v_pk_fma_f32 v[142:143], v[242:243], v[132:133], v[142:143] op_sel:[0,0,0] op_sel_hi:[0,1,1]
	v_pk_fma_f32 v[144:145], v[242:243], v[224:225], v[144:145] op_sel:[0,0,0] op_sel_hi:[0,1,1]
	v_add_f32_dpp v154, v154, v154 row_half_mirror row_mask:0xf bank_mask:0xf bound_ctrl:1
	ds_read_b128 v[206:209], v182 offset:19968
	ds_read_b128 v[210:213], v182 offset:19984
	v_add_f32_dpp v154, v154, v154 row_mirror row_mask:0xf bank_mask:0xf bound_ctrl:1
	ds_read_b64 v[232:233], v182 offset:20000
	ds_read_b128 v[214:217], v183 offset:19968
	v_pk_fma_f32 v[142:143], v[154:155], v[130:131], v[142:143] op_sel_hi:[0,1,1]
	v_pk_fma_f32 v[144:145], v[154:155], v[222:223], v[144:145] op_sel_hi:[0,1,1]
	ds_read_b128 v[218:221], v183 offset:19984
	ds_read_b64 v[234:235], v183 offset:20000
	ds_read_b32 v241, v186 offset:832
	s_waitcnt lgkmcnt(7)
	v_pk_mul_f32 v[150:151], v[142:143], v[190:191]
	v_pk_fma_f32 v[150:151], v[144:145], v[198:199], v[150:151]
	v_pk_mul_f32 v[152:153], v[142:143], v[236:237]
	v_add_f32_e32 v154, v150, v151
	v_pk_fma_f32 v[152:153], v[144:145], v[238:239], v[152:153]
	v_pk_mul_f32 v[146:147], v[142:143], v[192:193]
	v_add_f32_dpp v154, v154, v154 quad_perm:[1,0,3,2] row_mask:0xf bank_mask:0xf bound_ctrl:1
	v_pk_mul_f32 v[148:149], v[144:145], v[200:201]
	v_add_f32_e32 v167, v152, v153
	v_add_f32_dpp v154, v154, v154 quad_perm:[2,3,0,1] row_mask:0xf bank_mask:0xf bound_ctrl:1
	v_pk_fma_f32 v[146:147], v[240:241], v[196:197], v[146:147] op_sel:[0,0,0] op_sel_hi:[0,1,1]
	v_pk_fma_f32 v[148:149], v[240:241], v[204:205], v[148:149] op_sel:[0,0,0] op_sel_hi:[0,1,1]
	v_add_f32_dpp v154, v154, v154 row_half_mirror row_mask:0xf bank_mask:0xf bound_ctrl:1
	ds_read_b128 v[126:129], v182 offset:21504
	ds_read_b128 v[130:133], v182 offset:21520
	v_add_f32_dpp v154, v154, v154 row_mirror row_mask:0xf bank_mask:0xf bound_ctrl:1
	ds_read_b64 v[236:237], v182 offset:21536
	ds_read_b128 v[134:137], v183 offset:21504
	v_pk_fma_f32 v[146:147], v[154:155], v[194:195], v[146:147] op_sel_hi:[0,1,1]
	v_pk_fma_f32 v[148:149], v[154:155], v[202:203], v[148:149] op_sel_hi:[0,1,1]
	ds_read_b128 v[222:225], v183 offset:21520
	ds_read_b64 v[238:239], v183 offset:21536
	ds_read_b32 v242, v186 offset:896
	s_waitcnt lgkmcnt(7)
	v_pk_mul_f32 v[150:151], v[146:147], v[206:207]
	v_pk_fma_f32 v[150:151], v[148:149], v[214:215], v[150:151]
	v_pk_mul_f32 v[152:153], v[146:147], v[228:229]
	v_add_f32_e32 v154, v150, v151
	v_pk_fma_f32 v[152:153], v[148:149], v[230:231], v[152:153]
	v_pk_mul_f32 v[142:143], v[146:147], v[208:209]
	v_add_f32_dpp v154, v154, v154 quad_perm:[1,0,3,2] row_mask:0xf bank_mask:0xf bound_ctrl:1
	v_pk_mul_f32 v[144:145], v[148:149], v[216:217]
	v_add_f32_e32 v168, v152, v153
	v_add_f32_dpp v154, v154, v154 quad_perm:[2,3,0,1] row_mask:0xf bank_mask:0xf bound_ctrl:1
	v_pk_fma_f32 v[142:143], v[240:241], v[212:213], v[142:143] op_sel:[1,0,0] op_sel_hi:[1,1,1]
	v_pk_fma_f32 v[144:145], v[240:241], v[220:221], v[144:145] op_sel:[1,0,0] op_sel_hi:[1,1,1]
	v_add_f32_dpp v154, v154, v154 row_half_mirror row_mask:0xf bank_mask:0xf bound_ctrl:1
	ds_read_b128 v[190:193], v182 offset:23040
	ds_read_b128 v[194:197], v182 offset:23056
	v_add_f32_dpp v154, v154, v154 row_mirror row_mask:0xf bank_mask:0xf bound_ctrl:1
	ds_read_b64 v[228:229], v182 offset:23072
	ds_read_b128 v[198:201], v183 offset:23040
	v_pk_fma_f32 v[142:143], v[154:155], v[210:211], v[142:143] op_sel_hi:[0,1,1]
	v_pk_fma_f32 v[144:145], v[154:155], v[218:219], v[144:145] op_sel_hi:[0,1,1]
	ds_read_b128 v[202:205], v183 offset:23056
	ds_read_b64 v[230:231], v183 offset:23072
	ds_read_b32 v240, v186 offset:960
	s_waitcnt lgkmcnt(7)
	v_pk_mul_f32 v[150:151], v[142:143], v[126:127]
	v_pk_fma_f32 v[150:151], v[144:145], v[134:135], v[150:151]
	v_pk_mul_f32 v[152:153], v[142:143], v[232:233]
	v_add_f32_e32 v154, v150, v151
	v_pk_fma_f32 v[152:153], v[144:145], v[234:235], v[152:153]
	v_pk_mul_f32 v[146:147], v[142:143], v[128:129]
	v_add_f32_dpp v154, v154, v154 quad_perm:[1,0,3,2] row_mask:0xf bank_mask:0xf bound_ctrl:1
	v_pk_mul_f32 v[148:149], v[144:145], v[136:137]
	v_add_f32_e32 v169, v152, v153
	v_add_f32_dpp v154, v154, v154 quad_perm:[2,3,0,1] row_mask:0xf bank_mask:0xf bound_ctrl:1
	v_pk_fma_f32 v[146:147], v[242:243], v[132:133], v[146:147] op_sel:[0,0,0] op_sel_hi:[0,1,1]
	v_pk_fma_f32 v[148:149], v[242:243], v[224:225], v[148:149] op_sel:[0,0,0] op_sel_hi:[0,1,1]
	v_add_f32_dpp v154, v154, v154 row_half_mirror row_mask:0xf bank_mask:0xf bound_ctrl:1
	ds_read_b128 v[206:209], v182 offset:24576
	ds_read_b128 v[210:213], v182 offset:24592
	v_add_f32_dpp v154, v154, v154 row_mirror row_mask:0xf bank_mask:0xf bound_ctrl:1
	ds_read_b64 v[232:233], v182 offset:24608
	ds_read_b128 v[214:217], v183 offset:24576
	v_pk_fma_f32 v[146:147], v[154:155], v[130:131], v[146:147] op_sel_hi:[0,1,1]
	v_pk_fma_f32 v[148:149], v[154:155], v[222:223], v[148:149] op_sel_hi:[0,1,1]
	ds_read_b128 v[218:221], v183 offset:24592
	ds_read_b64 v[234:235], v183 offset:24608
	ds_read_b32 v241, v186 offset:1024
	s_waitcnt lgkmcnt(7)
; __device__ __forceinline__ void wkv_phase(const WkvT& W, unsigned char* lds) {
;     ...
;                 for (int t = 0; t < 32; ++t) {
;                     const f32x2 a2 = {nA[0], nA[1]}, w2 = {nA[2], nA[3]}, b2 = {nB[0], nB[1]}, k2 = {nB[2], nB[3]}, r2 = nr; const float v = nv;
;                     if (t + 1 < 32) { nA = *(const f32x4*)(pp + (t + 1) * 384); nB = *(const f32x4*)(pp + (t + 1) * 384 + 4); nr = *(const f32x2*)(pp + (t + 1) * 384 + 8); nv = pv[(t + 1) * 16]; }
;                     float S0 = S.x, S1 = S.y;
;                     float d = S0 * a2.x; d = __builtin_fmaf(S1, a2.y, d);
;                     float t0 = S0 * w2.x; t0 = __builtin_fmaf(v, k2.x, t0); asm volatile("" : "+v"(t0));
;                     float t1 = S1 * w2.y; t1 = __builtin_fmaf(v, k2.y, t1); asm volatile("" : "+v"(t1));
;                     float yprev; const float sa = wkv_reduce(d, ep, yprev);
;                     S0 = __builtin_fmaf(sa, b2.x, t0); asm volatile("" : "+v"(S0));
;                     S1 = __builtin_fmaf(sa, b2.y, t1); asm volatile("" : "+v"(S1));
;                     ep = S0 * r2.x; ep = __builtin_fmaf(S1, r2.y, ep);
;                     S.x = S0; S.y = S1;
;                     if (t >= 1) { const bool hit = oddrow && ((lane & 15) == ((t - 1) & 15)); if (t <= 16) yk0 = hit ? yprev : yk0; else yk1 = hit ? yprev : yk1; }
;                 }
;                 { float ylast; (void)wkv_reduce(0.f, ep, ylast); yk1 = (oddrow && (lane & 15) == 15) ? ylast : yk1; }
;                 if (oddrow) { sY[bi * 512 + (lane & 15) * 16 + il] = yk0; sY[bi * 512 + (16 + (lane & 15)) * 16 + il] = yk1; }
	v_pk_mul_f32 v[150:151], v[146:147], v[190:191]
	v_pk_fma_f32 v[150:151], v[148:149], v[198:199], v[150:151]
	v_pk_mul_f32 v[152:153], v[146:147], v[236:237]
	v_add_f32_e32 v154, v150, v151
	v_pk_fma_f32 v[152:153], v[148:149], v[238:239], v[152:153]
	v_pk_mul_f32 v[142:143], v[146:147], v[192:193]
	v_add_f32_dpp v154, v154, v154 quad_perm:[1,0,3,2] row_mask:0xf bank_mask:0xf bound_ctrl:1
	v_pk_mul_f32 v[144:145], v[148:149], v[200:201]
	v_add_f32_e32 v170, v152, v153
	v_add_f32_dpp v154, v154, v154 quad_perm:[2,3,0,1] row_mask:0xf bank_mask:0xf bound_ctrl:1
	v_pk_fma_f32 v[142:143], v[240:241], v[196:197], v[142:143] op_sel:[0,0,0] op_sel_hi:[0,1,1]
	v_pk_fma_f32 v[144:145], v[240:241], v[204:205], v[144:145] op_sel:[0,0,0] op_sel_hi:[0,1,1]
	v_add_f32_dpp v154, v154, v154 row_half_mirror row_mask:0xf bank_mask:0xf bound_ctrl:1
	ds_read_b128 v[126:129], v182 offset:26112
	ds_read_b128 v[130:133], v182 offset:26128
	v_add_f32_dpp v154, v154, v154 row_mirror row_mask:0xf bank_mask:0xf bound_ctrl:1
	ds_read_b64 v[236:237], v182 offset:26144
	ds_read_b128 v[134:137], v183 offset:26112
	v_pk_fma_f32 v[142:143], v[154:155], v[194:195], v[142:143] op_sel_hi:[0,1,1]
	v_pk_fma_f32 v[144:145], v[154:155], v[202:203], v[144:145] op_sel_hi:[0,1,1]
	ds_read_b128 v[222:225], v183 offset:26128
	ds_read_b64 v[238:239], v183 offset:26144
	ds_read_b32 v242, v186 offset:1088
	s_waitcnt lgkmcnt(7)
	v_pk_mul_f32 v[150:151], v[142:143], v[206:207]
	v_pk_fma_f32 v[150:151], v[144:145], v[214:215], v[150:151]
	v_pk_mul_f32 v[152:153], v[142:143], v[228:229]
	v_add_f32_e32 v154, v150, v151
	v_pk_fma_f32 v[152:153], v[144:145], v[230:231], v[152:153]
	v_pk_mul_f32 v[146:147], v[142:143], v[208:209]
	v_add_f32_dpp v154, v154, v154 quad_perm:[1,0,3,2] row_mask:0xf bank_mask:0xf bound_ctrl:1
	v_pk_mul_f32 v[148:149], v[144:145], v[216:217]
	v_add_f32_e32 v171, v152, v153
	v_add_f32_dpp v154, v154, v154 quad_perm:[2,3,0,1] row_mask:0xf bank_mask:0xf bound_ctrl:1
	v_pk_fma_f32 v[146:147], v[240:241], v[212:213], v[146:147] op_sel:[1,0,0] op_sel_hi:[1,1,1]
	v_pk_fma_f32 v[148:149], v[240:241], v[220:221], v[148:149] op_sel:[1,0,0] op_sel_hi:[1,1,1]
	v_add_f32_dpp v154, v154, v154 row_half_mirror row_mask:0xf bank_mask:0xf bound_ctrl:1
	ds_read_b128 v[190:193], v182 offset:27648
	ds_read_b128 v[194:197], v182 offset:27664
	v_add_f32_dpp v154, v154, v154 row_mirror row_mask:0xf bank_mask:0xf bound_ctrl:1
	ds_read_b64 v[228:229], v182 offset:27680
	ds_read_b128 v[198:201], v183 offset:27648
	v_pk_fma_f32 v[146:147], v[154:155], v[210:211], v[146:147] op_sel_hi:[0,1,1]
	v_pk_fma_f32 v[148:149], v[154:155], v[218:219], v[148:149] op_sel_hi:[0,1,1]
	ds_read_b128 v[202:205], v183 offset:27664
	ds_read_b64 v[230:231], v183 offset:27680
	ds_read_b32 v240, v186 offset:1152
	s_waitcnt lgkmcnt(7)
	v_cndmask_b32_e64 v172, v164, v156, s[10:11]
	v_cndmask_b32_e64 v174, v165, v157, s[10:11]
	v_cndmask_b32_e64 v176, v166, v158, s[10:11]
	v_cndmask_b32_e64 v178, v167, v159, s[10:11]
	v_cndmask_b32_e64 v173, v156, v164, s[10:11]
	v_cndmask_b32_e64 v175, v157, v165, s[10:11]
	v_cndmask_b32_e64 v177, v158, v166, s[10:11]
	v_cndmask_b32_e64 v179, v159, v167, s[10:11]
	v_add_f32_dpp v156, v172, v173 row_ror:8 row_mask:0xf bank_mask:0xf
	v_add_f32_dpp v157, v174, v175 row_ror:8 row_mask:0xf bank_mask:0xf
	v_add_f32_dpp v158, v176, v177 row_ror:8 row_mask:0xf bank_mask:0xf
	v_add_f32_dpp v159, v178, v179 row_ror:8 row_mask:0xf bank_mask:0xf
	v_cndmask_b32_e64 v172, v168, v160, s[10:11]
	v_cndmask_b32_e64 v174, v169, v161, s[10:11]
	v_cndmask_b32_e64 v176, v170, v162, s[10:11]
	v_cndmask_b32_e64 v178, v171, v163, s[10:11]
	v_cndmask_b32_e64 v173, v160, v168, s[10:11]
	v_cndmask_b32_e64 v175, v161, v169, s[10:11]
	v_cndmask_b32_e64 v177, v162, v170, s[10:11]
	v_cndmask_b32_e64 v179, v163, v171, s[10:11]
	v_add_f32_dpp v160, v172, v173 row_ror:8 row_mask:0xf bank_mask:0xf
	v_add_f32_dpp v161, v174, v175 row_ror:8 row_mask:0xf bank_mask:0xf
	v_add_f32_dpp v162, v176, v177 row_ror:8 row_mask:0xf bank_mask:0xf
	v_add_f32_dpp v163, v178, v179 row_ror:8 row_mask:0xf bank_mask:0xf
	v_cndmask_b32_e64 v172, v160, v156, s[12:13]
	v_cndmask_b32_e64 v174, v161, v157, s[12:13]
	v_cndmask_b32_e64 v176, v162, v158, s[12:13]
	v_cndmask_b32_e64 v178, v163, v159, s[12:13]
	v_cndmask_b32_e64 v173, v156, v160, s[12:13]
	v_cndmask_b32_e64 v175, v157, v161, s[12:13]
	v_cndmask_b32_e64 v177, v158, v162, s[12:13]
	v_cndmask_b32_e64 v179, v159, v163, s[12:13]
	v_add_f32_dpp v156, v172, v173 row_half_mirror row_mask:0xf bank_mask:0xf
	v_add_f32_dpp v157, v174, v175 row_half_mirror row_mask:0xf bank_mask:0xf
	v_add_f32_dpp v158, v176, v177 row_half_mirror row_mask:0xf bank_mask:0xf
	v_add_f32_dpp v159, v178, v179 row_half_mirror row_mask:0xf bank_mask:0xf
	v_cndmask_b32_e64 v172, v158, v156, s[14:15]
	v_cndmask_b32_e64 v174, v159, v157, s[14:15]
	v_cndmask_b32_e64 v173, v156, v158, s[14:15]
	v_cndmask_b32_e64 v175, v157, v159, s[14:15]
	v_add_f32_dpp v156, v172, v173 quad_perm:[2,3,0,1] row_mask:0xf bank_mask:0xf
	v_add_f32_dpp v157, v174, v175 quad_perm:[2,3,0,1] row_mask:0xf bank_mask:0xf
	v_cndmask_b32_e64 v172, v157, v156, s[16:17]
	v_cndmask_b32_e64 v173, v156, v157, s[16:17]
	s_nop 0
	v_add_f32_dpp v156, v172, v173 quad_perm:[1,0,3,2] row_mask:0xf bank_mask:0xf
	v_mov_b32_e32 v180, v156
	v_pk_mul_f32 v[150:151], v[146:147], v[126:127]
	v_pk_fma_f32 v[150:151], v[148:149], v[134:135], v[150:151]
	v_pk_mul_f32 v[152:153], v[146:147], v[232:233]
	v_add_f32_e32 v154, v150, v151
	v_pk_fma_f32 v[152:153], v[148:149], v[234:235], v[152:153]
	v_pk_mul_f32 v[142:143], v[146:147], v[128:129]
	v_add_f32_dpp v154, v154, v154 quad_perm:[1,0,3,2] row_mask:0xf bank_mask:0xf bound_ctrl:1
	v_pk_mul_f32 v[144:145], v[148:149], v[136:137]
	v_add_f32_e32 v156, v152, v153
	v_add_f32_dpp v154, v154, v154 quad_perm:[2,3,0,1] row_mask:0xf bank_mask:0xf bound_ctrl:1
	v_pk_fma_f32 v[142:143], v[242:243], v[132:133], v[142:143] op_sel:[0,0,0] op_sel_hi:[0,1,1]
	v_pk_fma_f32 v[144:145], v[242:243], v[224:225], v[144:145] op_sel:[0,0,0] op_sel_hi:[0,1,1]
	v_add_f32_dpp v154, v154, v154 row_half_mirror row_mask:0xf bank_mask:0xf bound_ctrl:1
	ds_read_b128 v[206:209], v182 offset:29184
	ds_read_b128 v[210:213], v182 offset:29200
	v_add_f32_dpp v154, v154, v154 row_mirror row_mask:0xf bank_mask:0xf bound_ctrl:1
	ds_read_b64 v[232:233], v182 offset:29216
	ds_read_b128 v[214:217], v183 offset:29184
	v_pk_fma_f32 v[142:143], v[154:155], v[130:131], v[142:143] op_sel_hi:[0,1,1]
	v_pk_fma_f32 v[144:145], v[154:155], v[222:223], v[144:145] op_sel_hi:[0,1,1]
	ds_read_b128 v[218:221], v183 offset:29200
	ds_read_b64 v[234:235], v183 offset:29216
	ds_read_b32 v241, v186 offset:1216
	s_waitcnt lgkmcnt(7)
; __device__ __forceinline__ void wkv_phase(const WkvT& W, unsigned char* lds) {
;     ...
;                 for (int t = 0; t < 32; ++t) {
;                     const f32x2 a2 = {nA[0], nA[1]}, w2 = {nA[2], nA[3]}, b2 = {nB[0], nB[1]}, k2 = {nB[2], nB[3]}, r2 = nr; const float v = nv;
;                     if (t + 1 < 32) { nA = *(const f32x4*)(pp + (t + 1) * 384); nB = *(const f32x4*)(pp + (t + 1) * 384 + 4); nr = *(const f32x2*)(pp + (t + 1) * 384 + 8); nv = pv[(t + 1) * 16]; }
;                     float S0 = S.x, S1 = S.y;
;                     float d = S0 * a2.x; d = __builtin_fmaf(S1, a2.y, d);
;                     float t0 = S0 * w2.x; t0 = __builtin_fmaf(v, k2.x, t0); asm volatile("" : "+v"(t0));
;                     float t1 = S1 * w2.y; t1 = __builtin_fmaf(v, k2.y, t1); asm volatile("" : "+v"(t1));
;                     float yprev; const float sa = wkv_reduce(d, ep, yprev);
;                     S0 = __builtin_fmaf(sa, b2.x, t0); asm volatile("" : "+v"(S0));
;                     S1 = __builtin_fmaf(sa, b2.y, t1); asm volatile("" : "+v"(S1));
;                     ep = S0 * r2.x; ep = __builtin_fmaf(S1, r2.y, ep);
;                     S.x = S0; S.y = S1;
	v_pk_mul_f32 v[150:151], v[142:143], v[190:191]
	v_pk_fma_f32 v[150:151], v[144:145], v[198:199], v[150:151]
	v_pk_mul_f32 v[152:153], v[142:143], v[236:237]
	v_add_f32_e32 v154, v150, v151
	v_pk_fma_f32 v[152:153], v[144:145], v[238:239], v[152:153]
	v_pk_mul_f32 v[146:147], v[142:143], v[192:193]
	v_add_f32_dpp v154, v154, v154 quad_perm:[1,0,3,2] row_mask:0xf bank_mask:0xf bound_ctrl:1
	v_pk_mul_f32 v[148:149], v[144:145], v[200:201]
	v_add_f32_e32 v157, v152, v153
	v_add_f32_dpp v154, v154, v154 quad_perm:[2,3,0,1] row_mask:0xf bank_mask:0xf bound_ctrl:1
	v_pk_fma_f32 v[146:147], v[240:241], v[196:197], v[146:147] op_sel:[0,0,0] op_sel_hi:[0,1,1]
	v_pk_fma_f32 v[148:149], v[240:241], v[204:205], v[148:149] op_sel:[0,0,0] op_sel_hi:[0,1,1]
	v_add_f32_dpp v154, v154, v154 row_half_mirror row_mask:0xf bank_mask:0xf bound_ctrl:1
	ds_read_b128 v[126:129], v182 offset:30720
	ds_read_b128 v[130:133], v182 offset:30736
	v_add_f32_dpp v154, v154, v154 row_mirror row_mask:0xf bank_mask:0xf bound_ctrl:1
	ds_read_b64 v[236:237], v182 offset:30752
	ds_read_b128 v[134:137], v183 offset:30720
	v_pk_fma_f32 v[146:147], v[154:155], v[194:195], v[146:147] op_sel_hi:[0,1,1]
	v_pk_fma_f32 v[148:149], v[154:155], v[202:203], v[148:149] op_sel_hi:[0,1,1]
	ds_read_b128 v[222:225], v183 offset:30736
	ds_read_b64 v[238:239], v183 offset:30752
	ds_read_b32 v242, v186 offset:1280
	s_waitcnt lgkmcnt(7)
	v_pk_mul_f32 v[150:151], v[146:147], v[206:207]
	v_pk_fma_f32 v[150:151], v[148:149], v[214:215], v[150:151]
	v_pk_mul_f32 v[152:153], v[146:147], v[228:229]
	v_add_f32_e32 v154, v150, v151
	v_pk_fma_f32 v[152:153], v[148:149], v[230:231], v[152:153]
	v_pk_mul_f32 v[142:143], v[146:147], v[208:209]
	v_add_f32_dpp v154, v154, v154 quad_perm:[1,0,3,2] row_mask:0xf bank_mask:0xf bound_ctrl:1
	v_pk_mul_f32 v[144:145], v[148:149], v[216:217]
	v_add_f32_e32 v158, v152, v153
	v_add_f32_dpp v154, v154, v154 quad_perm:[2,3,0,1] row_mask:0xf bank_mask:0xf bound_ctrl:1
	v_pk_fma_f32 v[142:143], v[240:241], v[212:213], v[142:143] op_sel:[1,0,0] op_sel_hi:[1,1,1]
	v_pk_fma_f32 v[144:145], v[240:241], v[220:221], v[144:145] op_sel:[1,0,0] op_sel_hi:[1,1,1]
	v_add_f32_dpp v154, v154, v154 row_half_mirror row_mask:0xf bank_mask:0xf bound_ctrl:1
	ds_read_b128 v[190:193], v182 offset:32256
	ds_read_b128 v[194:197], v182 offset:32272
	v_add_f32_dpp v154, v154, v154 row_mirror row_mask:0xf bank_mask:0xf bound_ctrl:1
	ds_read_b64 v[228:229], v182 offset:32288
	ds_read_b128 v[198:201], v183 offset:32256
	v_pk_fma_f32 v[142:143], v[154:155], v[210:211], v[142:143] op_sel_hi:[0,1,1]
	v_pk_fma_f32 v[144:145], v[154:155], v[218:219], v[144:145] op_sel_hi:[0,1,1]
	ds_read_b128 v[202:205], v183 offset:32272
	ds_read_b64 v[230:231], v183 offset:32288
	ds_read_b32 v240, v186 offset:1344
	s_waitcnt lgkmcnt(7)
	v_pk_mul_f32 v[150:151], v[142:143], v[126:127]
	v_pk_fma_f32 v[150:151], v[144:145], v[134:135], v[150:151]
	v_pk_mul_f32 v[152:153], v[142:143], v[232:233]
	v_add_f32_e32 v154, v150, v151
	v_pk_fma_f32 v[152:153], v[144:145], v[234:235], v[152:153]
	v_pk_mul_f32 v[146:147], v[142:143], v[128:129]
	v_add_f32_dpp v154, v154, v154 quad_perm:[1,0,3,2] row_mask:0xf bank_mask:0xf bound_ctrl:1
	v_pk_mul_f32 v[148:149], v[144:145], v[136:137]
	v_add_f32_e32 v159, v152, v153
	v_add_f32_dpp v154, v154, v154 quad_perm:[2,3,0,1] row_mask:0xf bank_mask:0xf bound_ctrl:1
	v_pk_fma_f32 v[146:147], v[242:243], v[132:133], v[146:147] op_sel:[0,0,0] op_sel_hi:[0,1,1]
	v_pk_fma_f32 v[148:149], v[242:243], v[224:225], v[148:149] op_sel:[0,0,0] op_sel_hi:[0,1,1]
	v_add_f32_dpp v154, v154, v154 row_half_mirror row_mask:0xf bank_mask:0xf bound_ctrl:1
	ds_read_b128 v[206:209], v182 offset:33792
	ds_read_b128 v[210:213], v182 offset:33808
	v_add_f32_dpp v154, v154, v154 row_mirror row_mask:0xf bank_mask:0xf bound_ctrl:1
	ds_read_b64 v[232:233], v182 offset:33824
	ds_read_b128 v[214:217], v183 offset:33792
	v_pk_fma_f32 v[146:147], v[154:155], v[130:131], v[146:147] op_sel_hi:[0,1,1]
	v_pk_fma_f32 v[148:149], v[154:155], v[222:223], v[148:149] op_sel_hi:[0,1,1]
	ds_read_b128 v[218:221], v183 offset:33808
	ds_read_b64 v[234:235], v183 offset:33824
	ds_read_b32 v241, v186 offset:1408
	s_waitcnt lgkmcnt(7)
	v_pk_mul_f32 v[150:151], v[146:147], v[190:191]
	v_pk_fma_f32 v[150:151], v[148:149], v[198:199], v[150:151]
	v_pk_mul_f32 v[152:153], v[146:147], v[236:237]
	v_add_f32_e32 v154, v150, v151
	v_pk_fma_f32 v[152:153], v[148:149], v[238:239], v[152:153]
	v_pk_mul_f32 v[142:143], v[146:147], v[192:193]
	v_add_f32_dpp v154, v154, v154 quad_perm:[1,0,3,2] row_mask:0xf bank_mask:0xf bound_ctrl:1
	v_pk_mul_f32 v[144:145], v[148:149], v[200:201]
	v_add_f32_e32 v160, v152, v153
	v_add_f32_dpp v154, v154, v154 quad_perm:[2,3,0,1] row_mask:0xf bank_mask:0xf bound_ctrl:1
	v_pk_fma_f32 v[142:143], v[240:241], v[196:197], v[142:143] op_sel:[0,0,0] op_sel_hi:[0,1,1]
	v_pk_fma_f32 v[144:145], v[240:241], v[204:205], v[144:145] op_sel:[0,0,0] op_sel_hi:[0,1,1]
	v_add_f32_dpp v154, v154, v154 row_half_mirror row_mask:0xf bank_mask:0xf bound_ctrl:1
	ds_read_b128 v[126:129], v182 offset:35328
	ds_read_b128 v[130:133], v182 offset:35344
	v_add_f32_dpp v154, v154, v154 row_mirror row_mask:0xf bank_mask:0xf bound_ctrl:1
	ds_read_b64 v[236:237], v182 offset:35360
	ds_read_b128 v[134:137], v183 offset:35328
	v_pk_fma_f32 v[142:143], v[154:155], v[194:195], v[142:143] op_sel_hi:[0,1,1]
	v_pk_fma_f32 v[144:145], v[154:155], v[202:203], v[144:145] op_sel_hi:[0,1,1]
	ds_read_b128 v[222:225], v183 offset:35344
	ds_read_b64 v[238:239], v183 offset:35360
	ds_read_b32 v242, v186 offset:1472
	s_waitcnt lgkmcnt(7)
; __device__ __forceinline__ void wkv_phase(const WkvT& W, unsigned char* lds) {
;     ...
;                 for (int t = 0; t < 32; ++t) {
;                     const f32x2 a2 = {nA[0], nA[1]}, w2 = {nA[2], nA[3]}, b2 = {nB[0], nB[1]}, k2 = {nB[2], nB[3]}, r2 = nr; const float v = nv;
;                     if (t + 1 < 32) { nA = *(const f32x4*)(pp + (t + 1) * 384); nB = *(const f32x4*)(pp + (t + 1) * 384 + 4); nr = *(const f32x2*)(pp + (t + 1) * 384 + 8); nv = pv[(t + 1) * 16]; }
;                     float S0 = S.x, S1 = S.y;
;                     float d = S0 * a2.x; d = __builtin_fmaf(S1, a2.y, d);
;                     float t0 = S0 * w2.x; t0 = __builtin_fmaf(v, k2.x, t0); asm volatile("" : "+v"(t0));
;                     float t1 = S1 * w2.y; t1 = __builtin_fmaf(v, k2.y, t1); asm volatile("" : "+v"(t1));
;                     float yprev; const float sa = wkv_reduce(d, ep, yprev);
;                     S0 = __builtin_fmaf(sa, b2.x, t0); asm volatile("" : "+v"(S0));
;                     S1 = __builtin_fmaf(sa, b2.y, t1); asm volatile("" : "+v"(S1));
;                     ep = S0 * r2.x; ep = __builtin_fmaf(S1, r2.y, ep);
;                     S.x = S0; S.y = S1;
	v_pk_mul_f32 v[150:151], v[142:143], v[206:207]
	v_pk_fma_f32 v[150:151], v[144:145], v[214:215], v[150:151]
	v_pk_mul_f32 v[152:153], v[142:143], v[228:229]
	v_add_f32_e32 v154, v150, v151
	v_pk_fma_f32 v[152:153], v[144:145], v[230:231], v[152:153]
	v_pk_mul_f32 v[146:147], v[142:143], v[208:209]
	v_add_f32_dpp v154, v154, v154 quad_perm:[1,0,3,2] row_mask:0xf bank_mask:0xf bound_ctrl:1
	v_pk_mul_f32 v[148:149], v[144:145], v[216:217]
	v_add_f32_e32 v161, v152, v153
	v_add_f32_dpp v154, v154, v154 quad_perm:[2,3,0,1] row_mask:0xf bank_mask:0xf bound_ctrl:1
	v_pk_fma_f32 v[146:147], v[240:241], v[212:213], v[146:147] op_sel:[1,0,0] op_sel_hi:[1,1,1]
	v_pk_fma_f32 v[148:149], v[240:241], v[220:221], v[148:149] op_sel:[1,0,0] op_sel_hi:[1,1,1]
	v_add_f32_dpp v154, v154, v154 row_half_mirror row_mask:0xf bank_mask:0xf bound_ctrl:1
	ds_read_b128 v[190:193], v182 offset:36864
	ds_read_b128 v[194:197], v182 offset:36880
	v_add_f32_dpp v154, v154, v154 row_mirror row_mask:0xf bank_mask:0xf bound_ctrl:1
	ds_read_b64 v[228:229], v182 offset:36896
	ds_read_b128 v[198:201], v183 offset:36864
	v_pk_fma_f32 v[146:147], v[154:155], v[210:211], v[146:147] op_sel_hi:[0,1,1]
	v_pk_fma_f32 v[148:149], v[154:155], v[218:219], v[148:149] op_sel_hi:[0,1,1]
	ds_read_b128 v[202:205], v183 offset:36880
	ds_read_b64 v[230:231], v183 offset:36896
	ds_read_b32 v240, v186 offset:1536
	s_waitcnt lgkmcnt(7)
	v_pk_mul_f32 v[150:151], v[146:147], v[126:127]
	v_pk_fma_f32 v[150:151], v[148:149], v[134:135], v[150:151]
	v_pk_mul_f32 v[152:153], v[146:147], v[232:233]
	v_add_f32_e32 v154, v150, v151
	v_pk_fma_f32 v[152:153], v[148:149], v[234:235], v[152:153]
	v_pk_mul_f32 v[142:143], v[146:147], v[128:129]
	v_add_f32_dpp v154, v154, v154 quad_perm:[1,0,3,2] row_mask:0xf bank_mask:0xf bound_ctrl:1
	v_pk_mul_f32 v[144:145], v[148:149], v[136:137]
	v_add_f32_e32 v162, v152, v153
	v_add_f32_dpp v154, v154, v154 quad_perm:[2,3,0,1] row_mask:0xf bank_mask:0xf bound_ctrl:1
	v_pk_fma_f32 v[142:143], v[242:243], v[132:133], v[142:143] op_sel:[0,0,0] op_sel_hi:[0,1,1]
	v_pk_fma_f32 v[144:145], v[242:243], v[224:225], v[144:145] op_sel:[0,0,0] op_sel_hi:[0,1,1]
	v_add_f32_dpp v154, v154, v154 row_half_mirror row_mask:0xf bank_mask:0xf bound_ctrl:1
	ds_read_b128 v[206:209], v182 offset:38400
	ds_read_b128 v[210:213], v182 offset:38416
	v_add_f32_dpp v154, v154, v154 row_mirror row_mask:0xf bank_mask:0xf bound_ctrl:1
	ds_read_b64 v[232:233], v182 offset:38432
	ds_read_b128 v[214:217], v183 offset:38400
	v_pk_fma_f32 v[142:143], v[154:155], v[130:131], v[142:143] op_sel_hi:[0,1,1]
	v_pk_fma_f32 v[144:145], v[154:155], v[222:223], v[144:145] op_sel_hi:[0,1,1]
	ds_read_b128 v[218:221], v183 offset:38416
	ds_read_b64 v[234:235], v183 offset:38432
	ds_read_b32 v241, v186 offset:1600
	s_waitcnt lgkmcnt(7)
	v_pk_mul_f32 v[150:151], v[142:143], v[190:191]
	v_pk_fma_f32 v[150:151], v[144:145], v[198:199], v[150:151]
	v_pk_mul_f32 v[152:153], v[142:143], v[236:237]
	v_add_f32_e32 v154, v150, v151
	v_pk_fma_f32 v[152:153], v[144:145], v[238:239], v[152:153]
	v_pk_mul_f32 v[146:147], v[142:143], v[192:193]
	v_add_f32_dpp v154, v154, v154 quad_perm:[1,0,3,2] row_mask:0xf bank_mask:0xf bound_ctrl:1
	v_pk_mul_f32 v[148:149], v[144:145], v[200:201]
	v_add_f32_e32 v163, v152, v153
	v_add_f32_dpp v154, v154, v154 quad_perm:[2,3,0,1] row_mask:0xf bank_mask:0xf bound_ctrl:1
	v_pk_fma_f32 v[146:147], v[240:241], v[196:197], v[146:147] op_sel:[0,0,0] op_sel_hi:[0,1,1]
	v_pk_fma_f32 v[148:149], v[240:241], v[204:205], v[148:149] op_sel:[0,0,0] op_sel_hi:[0,1,1]
	v_add_f32_dpp v154, v154, v154 row_half_mirror row_mask:0xf bank_mask:0xf bound_ctrl:1
	ds_read_b128 v[126:129], v182 offset:39936
	ds_read_b128 v[130:133], v182 offset:39952
	v_add_f32_dpp v154, v154, v154 row_mirror row_mask:0xf bank_mask:0xf bound_ctrl:1
	ds_read_b64 v[236:237], v182 offset:39968
	ds_read_b128 v[134:137], v183 offset:39936
	v_pk_fma_f32 v[146:147], v[154:155], v[194:195], v[146:147] op_sel_hi:[0,1,1]
	v_pk_fma_f32 v[148:149], v[154:155], v[202:203], v[148:149] op_sel_hi:[0,1,1]
	ds_read_b128 v[222:225], v183 offset:39952
	ds_read_b64 v[238:239], v183 offset:39968
	ds_read_b32 v242, v186 offset:1664
	s_waitcnt lgkmcnt(7)
	v_pk_mul_f32 v[150:151], v[146:147], v[206:207]
	v_pk_fma_f32 v[150:151], v[148:149], v[214:215], v[150:151]
	v_pk_mul_f32 v[152:153], v[146:147], v[228:229]
	v_add_f32_e32 v154, v150, v151
	v_pk_fma_f32 v[152:153], v[148:149], v[230:231], v[152:153]
	v_pk_mul_f32 v[142:143], v[146:147], v[208:209]
	v_add_f32_dpp v154, v154, v154 quad_perm:[1,0,3,2] row_mask:0xf bank_mask:0xf bound_ctrl:1
	v_pk_mul_f32 v[144:145], v[148:149], v[216:217]
	v_add_f32_e32 v164, v152, v153
	v_add_f32_dpp v154, v154, v154 quad_perm:[2,3,0,1] row_mask:0xf bank_mask:0xf bound_ctrl:1
	v_pk_fma_f32 v[142:143], v[240:241], v[212:213], v[142:143] op_sel:[1,0,0] op_sel_hi:[1,1,1]
	v_pk_fma_f32 v[144:145], v[240:241], v[220:221], v[144:145] op_sel:[1,0,0] op_sel_hi:[1,1,1]
	v_add_f32_dpp v154, v154, v154 row_half_mirror row_mask:0xf bank_mask:0xf bound_ctrl:1
	ds_read_b128 v[190:193], v182 offset:41472
	ds_read_b128 v[194:197], v182 offset:41488
	v_add_f32_dpp v154, v154, v154 row_mirror row_mask:0xf bank_mask:0xf bound_ctrl:1
	ds_read_b64 v[228:229], v182 offset:41504
	ds_read_b128 v[198:201], v183 offset:41472
	v_pk_fma_f32 v[142:143], v[154:155], v[210:211], v[142:143] op_sel_hi:[0,1,1]
	v_pk_fma_f32 v[144:145], v[154:155], v[218:219], v[144:145] op_sel_hi:[0,1,1]
	ds_read_b128 v[202:205], v183 offset:41488
	ds_read_b64 v[230:231], v183 offset:41504
	ds_read_b32 v240, v186 offset:1728
	s_waitcnt lgkmcnt(7)
; __device__ __forceinline__ void wkv_phase(const WkvT& W, unsigned char* lds) {
;     ...
;                 for (int t = 0; t < 32; ++t) {
;                     const f32x2 a2 = {nA[0], nA[1]}, w2 = {nA[2], nA[3]}, b2 = {nB[0], nB[1]}, k2 = {nB[2], nB[3]}, r2 = nr; const float v = nv;
;                     if (t + 1 < 32) { nA = *(const f32x4*)(pp + (t + 1) * 384); nB = *(const f32x4*)(pp + (t + 1) * 384 + 4); nr = *(const f32x2*)(pp + (t + 1) * 384 + 8); nv = pv[(t + 1) * 16]; }
;                     float S0 = S.x, S1 = S.y;
;                     float d = S0 * a2.x; d = __builtin_fmaf(S1, a2.y, d);
;                     float t0 = S0 * w2.x; t0 = __builtin_fmaf(v, k2.x, t0); asm volatile("" : "+v"(t0));
;                     float t1 = S1 * w2.y; t1 = __builtin_fmaf(v, k2.y, t1); asm volatile("" : "+v"(t1));
;                     float yprev; const float sa = wkv_reduce(d, ep, yprev);
;                     S0 = __builtin_fmaf(sa, b2.x, t0); asm volatile("" : "+v"(S0));
;                     S1 = __builtin_fmaf(sa, b2.y, t1); asm volatile("" : "+v"(S1));
;                     ep = S0 * r2.x; ep = __builtin_fmaf(S1, r2.y, ep);
;                     S.x = S0; S.y = S1;
	v_pk_mul_f32 v[150:151], v[142:143], v[126:127]
	v_pk_fma_f32 v[150:151], v[144:145], v[134:135], v[150:151]
	v_pk_mul_f32 v[152:153], v[142:143], v[232:233]
	v_add_f32_e32 v154, v150, v151
	v_pk_fma_f32 v[152:153], v[144:145], v[234:235], v[152:153]
	v_pk_mul_f32 v[146:147], v[142:143], v[128:129]
	v_add_f32_dpp v154, v154, v154 quad_perm:[1,0,3,2] row_mask:0xf bank_mask:0xf bound_ctrl:1
	v_pk_mul_f32 v[148:149], v[144:145], v[136:137]
	v_add_f32_e32 v165, v152, v153
	v_add_f32_dpp v154, v154, v154 quad_perm:[2,3,0,1] row_mask:0xf bank_mask:0xf bound_ctrl:1
	v_pk_fma_f32 v[146:147], v[242:243], v[132:133], v[146:147] op_sel:[0,0,0] op_sel_hi:[0,1,1]
	v_pk_fma_f32 v[148:149], v[242:243], v[224:225], v[148:149] op_sel:[0,0,0] op_sel_hi:[0,1,1]
	v_add_f32_dpp v154, v154, v154 row_half_mirror row_mask:0xf bank_mask:0xf bound_ctrl:1
	ds_read_b128 v[206:209], v182 offset:43008
	ds_read_b128 v[210:213], v182 offset:43024
	v_add_f32_dpp v154, v154, v154 row_mirror row_mask:0xf bank_mask:0xf bound_ctrl:1
	ds_read_b64 v[232:233], v182 offset:43040
	ds_read_b128 v[214:217], v183 offset:43008
	v_pk_fma_f32 v[146:147], v[154:155], v[130:131], v[146:147] op_sel_hi:[0,1,1]
	v_pk_fma_f32 v[148:149], v[154:155], v[222:223], v[148:149] op_sel_hi:[0,1,1]
	ds_read_b128 v[218:221], v183 offset:43024
	ds_read_b64 v[234:235], v183 offset:43040
	ds_read_b32 v241, v186 offset:1792
	s_waitcnt lgkmcnt(7)
	v_pk_mul_f32 v[150:151], v[146:147], v[190:191]
	v_pk_fma_f32 v[150:151], v[148:149], v[198:199], v[150:151]
	v_pk_mul_f32 v[152:153], v[146:147], v[236:237]
	v_add_f32_e32 v154, v150, v151
	v_pk_fma_f32 v[152:153], v[148:149], v[238:239], v[152:153]
	v_pk_mul_f32 v[142:143], v[146:147], v[192:193]
	v_add_f32_dpp v154, v154, v154 quad_perm:[1,0,3,2] row_mask:0xf bank_mask:0xf bound_ctrl:1
	v_pk_mul_f32 v[144:145], v[148:149], v[200:201]
	v_add_f32_e32 v166, v152, v153
	v_add_f32_dpp v154, v154, v154 quad_perm:[2,3,0,1] row_mask:0xf bank_mask:0xf bound_ctrl:1
	v_pk_fma_f32 v[142:143], v[240:241], v[196:197], v[142:143] op_sel:[0,0,0] op_sel_hi:[0,1,1]
	v_pk_fma_f32 v[144:145], v[240:241], v[204:205], v[144:145] op_sel:[0,0,0] op_sel_hi:[0,1,1]
	v_add_f32_dpp v154, v154, v154 row_half_mirror row_mask:0xf bank_mask:0xf bound_ctrl:1
	ds_read_b128 v[126:129], v182 offset:44544
	ds_read_b128 v[130:133], v182 offset:44560
	v_add_f32_dpp v154, v154, v154 row_mirror row_mask:0xf bank_mask:0xf bound_ctrl:1
	ds_read_b64 v[236:237], v182 offset:44576
	ds_read_b128 v[134:137], v183 offset:44544
	v_pk_fma_f32 v[142:143], v[154:155], v[194:195], v[142:143] op_sel_hi:[0,1,1]
	v_pk_fma_f32 v[144:145], v[154:155], v[202:203], v[144:145] op_sel_hi:[0,1,1]
	ds_read_b128 v[222:225], v183 offset:44560
	ds_read_b64 v[238:239], v183 offset:44576
	ds_read_b32 v242, v186 offset:1856
	s_waitcnt lgkmcnt(7)
	v_pk_mul_f32 v[150:151], v[142:143], v[206:207]
	v_pk_fma_f32 v[150:151], v[144:145], v[214:215], v[150:151]
	v_pk_mul_f32 v[152:153], v[142:143], v[228:229]
	v_add_f32_e32 v154, v150, v151
	v_pk_fma_f32 v[152:153], v[144:145], v[230:231], v[152:153]
	v_pk_mul_f32 v[146:147], v[142:143], v[208:209]
	v_add_f32_dpp v154, v154, v154 quad_perm:[1,0,3,2] row_mask:0xf bank_mask:0xf bound_ctrl:1
	v_pk_mul_f32 v[148:149], v[144:145], v[216:217]
	v_add_f32_e32 v167, v152, v153
	v_add_f32_dpp v154, v154, v154 quad_perm:[2,3,0,1] row_mask:0xf bank_mask:0xf bound_ctrl:1
	v_pk_fma_f32 v[146:147], v[240:241], v[212:213], v[146:147] op_sel:[1,0,0] op_sel_hi:[1,1,1]
	v_pk_fma_f32 v[148:149], v[240:241], v[220:221], v[148:149] op_sel:[1,0,0] op_sel_hi:[1,1,1]
	v_add_f32_dpp v154, v154, v154 row_half_mirror row_mask:0xf bank_mask:0xf bound_ctrl:1
	ds_read_b128 v[190:193], v182 offset:46080
	ds_read_b128 v[194:197], v182 offset:46096
	v_add_f32_dpp v154, v154, v154 row_mirror row_mask:0xf bank_mask:0xf bound_ctrl:1
	ds_read_b64 v[228:229], v182 offset:46112
	ds_read_b128 v[198:201], v183 offset:46080
	v_pk_fma_f32 v[146:147], v[154:155], v[210:211], v[146:147] op_sel_hi:[0,1,1]
	v_pk_fma_f32 v[148:149], v[154:155], v[218:219], v[148:149] op_sel_hi:[0,1,1]
	ds_read_b128 v[202:205], v183 offset:46096
	ds_read_b64 v[230:231], v183 offset:46112
	ds_read_b32 v240, v186 offset:1920
	s_waitcnt lgkmcnt(7)
	v_pk_mul_f32 v[150:151], v[146:147], v[126:127]
	v_pk_fma_f32 v[150:151], v[148:149], v[134:135], v[150:151]
	v_pk_mul_f32 v[152:153], v[146:147], v[232:233]
	v_add_f32_e32 v154, v150, v151
	v_pk_fma_f32 v[152:153], v[148:149], v[234:235], v[152:153]
	v_pk_mul_f32 v[142:143], v[146:147], v[128:129]
	v_add_f32_dpp v154, v154, v154 quad_perm:[1,0,3,2] row_mask:0xf bank_mask:0xf bound_ctrl:1
	v_pk_mul_f32 v[144:145], v[148:149], v[136:137]
	v_add_f32_e32 v168, v152, v153
	v_add_f32_dpp v154, v154, v154 quad_perm:[2,3,0,1] row_mask:0xf bank_mask:0xf bound_ctrl:1
	v_pk_fma_f32 v[142:143], v[242:243], v[132:133], v[142:143] op_sel:[0,0,0] op_sel_hi:[0,1,1]
	v_pk_fma_f32 v[144:145], v[242:243], v[224:225], v[144:145] op_sel:[0,0,0] op_sel_hi:[0,1,1]
	v_add_f32_dpp v154, v154, v154 row_half_mirror row_mask:0xf bank_mask:0xf bound_ctrl:1
	ds_read_b128 v[206:209], v182 offset:47616
	ds_read_b128 v[210:213], v182 offset:47632
	v_add_f32_dpp v154, v154, v154 row_mirror row_mask:0xf bank_mask:0xf bound_ctrl:1
	ds_read_b64 v[232:233], v182 offset:47648
	ds_read_b128 v[214:217], v183 offset:47616
	v_pk_fma_f32 v[142:143], v[154:155], v[130:131], v[142:143] op_sel_hi:[0,1,1]
	v_pk_fma_f32 v[144:145], v[154:155], v[222:223], v[144:145] op_sel_hi:[0,1,1]
	ds_read_b128 v[218:221], v183 offset:47632
	ds_read_b64 v[234:235], v183 offset:47648
	ds_read_b32 v241, v186 offset:1984
	s_waitcnt lgkmcnt(7)
; __device__ __forceinline__ void wkv_phase(const WkvT& W, unsigned char* lds) {
;     ...
;                 for (int t = 0; t < 32; ++t) {
;                     const f32x2 a2 = {nA[0], nA[1]}, w2 = {nA[2], nA[3]}, b2 = {nB[0], nB[1]}, k2 = {nB[2], nB[3]}, r2 = nr; const float v = nv;
;                     if (t + 1 < 32) { nA = *(const f32x4*)(pp + (t + 1) * 384); nB = *(const f32x4*)(pp + (t + 1) * 384 + 4); nr = *(const f32x2*)(pp + (t + 1) * 384 + 8); nv = pv[(t + 1) * 16]; }
;                     float S0 = S.x, S1 = S.y;
;                     float d = S0 * a2.x; d = __builtin_fmaf(S1, a2.y, d);
;                     float t0 = S0 * w2.x; t0 = __builtin_fmaf(v, k2.x, t0); asm volatile("" : "+v"(t0));
;                     float t1 = S1 * w2.y; t1 = __builtin_fmaf(v, k2.y, t1); asm volatile("" : "+v"(t1));
;                     float yprev; const float sa = wkv_reduce(d, ep, yprev);
;                     S0 = __builtin_fmaf(sa, b2.x, t0); asm volatile("" : "+v"(S0));
;                     S1 = __builtin_fmaf(sa, b2.y, t1); asm volatile("" : "+v"(S1));
;                     ep = S0 * r2.x; ep = __builtin_fmaf(S1, r2.y, ep);
;                     S.x = S0; S.y = S1;
;                     if (t >= 1) { const bool hit = oddrow && ((lane & 15) == ((t - 1) & 15)); if (t <= 16) yk0 = hit ? yprev : yk0; else yk1 = hit ? yprev : yk1; }
;                 }
;                 { float ylast; (void)wkv_reduce(0.f, ep, ylast); yk1 = (oddrow && (lane & 15) == 15) ? ylast : yk1; }
;                 if (oddrow) { sY[bi * 512 + (lane & 15) * 16 + il] = yk0; sY[bi * 512 + (16 + (lane & 15)) * 16 + il] = yk1; }
	v_pk_mul_f32 v[150:151], v[142:143], v[190:191]
	v_pk_fma_f32 v[150:151], v[144:145], v[198:199], v[150:151]
	v_pk_mul_f32 v[152:153], v[142:143], v[236:237]
	v_add_f32_e32 v154, v150, v151
	v_pk_fma_f32 v[152:153], v[144:145], v[238:239], v[152:153]
	v_pk_mul_f32 v[146:147], v[142:143], v[192:193]
	v_add_f32_dpp v154, v154, v154 quad_perm:[1,0,3,2] row_mask:0xf bank_mask:0xf bound_ctrl:1
	v_pk_mul_f32 v[148:149], v[144:145], v[200:201]
	v_add_f32_e32 v169, v152, v153
	v_add_f32_dpp v154, v154, v154 quad_perm:[2,3,0,1] row_mask:0xf bank_mask:0xf bound_ctrl:1
	v_pk_fma_f32 v[146:147], v[240:241], v[196:197], v[146:147] op_sel:[0,0,0] op_sel_hi:[0,1,1]
	v_pk_fma_f32 v[148:149], v[240:241], v[204:205], v[148:149] op_sel:[0,0,0] op_sel_hi:[0,1,1]
	v_add_f32_dpp v154, v154, v154 row_half_mirror row_mask:0xf bank_mask:0xf bound_ctrl:1
	s_nop 1
	v_add_f32_dpp v154, v154, v154 row_mirror row_mask:0xf bank_mask:0xf bound_ctrl:1
	v_pk_fma_f32 v[146:147], v[154:155], v[194:195], v[146:147] op_sel_hi:[0,1,1]
	v_pk_fma_f32 v[148:149], v[154:155], v[202:203], v[148:149] op_sel_hi:[0,1,1]
	s_waitcnt lgkmcnt(0)
	v_pk_mul_f32 v[150:151], v[146:147], v[206:207]
	v_pk_fma_f32 v[150:151], v[148:149], v[214:215], v[150:151]
	v_pk_mul_f32 v[152:153], v[146:147], v[228:229]
	v_add_f32_e32 v154, v150, v151
	v_pk_fma_f32 v[152:153], v[148:149], v[230:231], v[152:153]
	v_pk_mul_f32 v[142:143], v[146:147], v[208:209]
	v_add_f32_dpp v154, v154, v154 quad_perm:[1,0,3,2] row_mask:0xf bank_mask:0xf bound_ctrl:1
	v_pk_mul_f32 v[144:145], v[148:149], v[216:217]
	v_add_f32_e32 v170, v152, v153
	v_add_f32_dpp v154, v154, v154 quad_perm:[2,3,0,1] row_mask:0xf bank_mask:0xf bound_ctrl:1
	v_pk_fma_f32 v[142:143], v[240:241], v[212:213], v[142:143] op_sel:[1,0,0] op_sel_hi:[1,1,1]
	v_pk_fma_f32 v[144:145], v[240:241], v[220:221], v[144:145] op_sel:[1,0,0] op_sel_hi:[1,1,1]
	v_add_f32_dpp v154, v154, v154 row_half_mirror row_mask:0xf bank_mask:0xf bound_ctrl:1
	s_nop 1
	v_add_f32_dpp v154, v154, v154 row_mirror row_mask:0xf bank_mask:0xf bound_ctrl:1
	v_pk_fma_f32 v[142:143], v[154:155], v[210:211], v[142:143] op_sel_hi:[0,1,1]
	v_pk_fma_f32 v[144:145], v[154:155], v[218:219], v[144:145] op_sel_hi:[0,1,1]
	v_pk_mul_f32 v[152:153], v[142:143], v[232:233]
	v_pk_fma_f32 v[152:153], v[144:145], v[234:235], v[152:153]
	s_nop 0
	v_add_f32_e32 v171, v152, v153
	v_cndmask_b32_e64 v172, v164, v156, s[10:11]
	v_cndmask_b32_e64 v174, v165, v157, s[10:11]
	v_cndmask_b32_e64 v176, v166, v158, s[10:11]
	v_cndmask_b32_e64 v178, v167, v159, s[10:11]
	v_cndmask_b32_e64 v173, v156, v164, s[10:11]
	v_cndmask_b32_e64 v175, v157, v165, s[10:11]
	v_cndmask_b32_e64 v177, v158, v166, s[10:11]
	v_cndmask_b32_e64 v179, v159, v167, s[10:11]
	v_add_f32_dpp v156, v172, v173 row_ror:8 row_mask:0xf bank_mask:0xf
	v_add_f32_dpp v157, v174, v175 row_ror:8 row_mask:0xf bank_mask:0xf
	v_add_f32_dpp v158, v176, v177 row_ror:8 row_mask:0xf bank_mask:0xf
	v_add_f32_dpp v159, v178, v179 row_ror:8 row_mask:0xf bank_mask:0xf
	v_cndmask_b32_e64 v172, v168, v160, s[10:11]
	v_cndmask_b32_e64 v174, v169, v161, s[10:11]
	v_cndmask_b32_e64 v176, v170, v162, s[10:11]
	v_cndmask_b32_e64 v178, v171, v163, s[10:11]
	v_cndmask_b32_e64 v173, v160, v168, s[10:11]
	v_cndmask_b32_e64 v175, v161, v169, s[10:11]
	v_cndmask_b32_e64 v177, v162, v170, s[10:11]
	v_cndmask_b32_e64 v179, v163, v171, s[10:11]
	v_add_f32_dpp v160, v172, v173 row_ror:8 row_mask:0xf bank_mask:0xf
	v_add_f32_dpp v161, v174, v175 row_ror:8 row_mask:0xf bank_mask:0xf
	v_add_f32_dpp v162, v176, v177 row_ror:8 row_mask:0xf bank_mask:0xf
	v_add_f32_dpp v163, v178, v179 row_ror:8 row_mask:0xf bank_mask:0xf
	v_cndmask_b32_e64 v172, v160, v156, s[12:13]
	v_cndmask_b32_e64 v174, v161, v157, s[12:13]
	v_cndmask_b32_e64 v176, v162, v158, s[12:13]
	v_cndmask_b32_e64 v178, v163, v159, s[12:13]
	v_cndmask_b32_e64 v173, v156, v160, s[12:13]
	v_cndmask_b32_e64 v175, v157, v161, s[12:13]
	v_cndmask_b32_e64 v177, v158, v162, s[12:13]
	v_cndmask_b32_e64 v179, v159, v163, s[12:13]
	v_add_f32_dpp v156, v172, v173 row_half_mirror row_mask:0xf bank_mask:0xf
	v_add_f32_dpp v157, v174, v175 row_half_mirror row_mask:0xf bank_mask:0xf
	v_add_f32_dpp v158, v176, v177 row_half_mirror row_mask:0xf bank_mask:0xf
	v_add_f32_dpp v159, v178, v179 row_half_mirror row_mask:0xf bank_mask:0xf
	v_cndmask_b32_e64 v172, v158, v156, s[14:15]
	v_cndmask_b32_e64 v174, v159, v157, s[14:15]
	v_cndmask_b32_e64 v173, v156, v158, s[14:15]
	v_cndmask_b32_e64 v175, v157, v159, s[14:15]
	v_add_f32_dpp v156, v172, v173 quad_perm:[2,3,0,1] row_mask:0xf bank_mask:0xf
	v_add_f32_dpp v157, v174, v175 quad_perm:[2,3,0,1] row_mask:0xf bank_mask:0xf
	v_cndmask_b32_e64 v172, v157, v156, s[16:17]
	v_cndmask_b32_e64 v173, v156, v157, s[16:17]
	s_nop 0
	v_add_f32_dpp v156, v172, v173 quad_perm:[1,0,3,2] row_mask:0xf bank_mask:0xf
	v_mov_b32_e32 v181, v156
	ds_write2st64_b32 v187, v180, v181 offset0:0 offset1:4
.Lwkv4_b1_skip:
	s_mov_b64 s[46:47], exec

; __device__ __forceinline__ void wkv_phase(const WkvT& W, unsigned char* lds) {
;     ...
;                 const float* pp = sP + bo + jj * 12;
;                 const float* pv = sV + bi * 512 + il;
;                 f32x4 nA = *(const f32x4*)pp, nB = *(const f32x4*)(pp + 4); f32x2 nr = *(const f32x2*)(pp + 8); float nv = pv[0];
;                 float yk0 = 0.f, yk1 = 0.f, ep = 0.f;
;                 const bool oddrow = (lane & 16) != 0;
; #pragma unroll
;                 for (int t = 0; t < 32; ++t) {
;                     const f32x2 a2 = {nA[0], nA[1]}, w2 = {nA[2], nA[3]}, b2 = {nB[0], nB[1]}, k2 = {nB[2], nB[3]}, r2 = nr; const float v = nv;
;                     if (t + 1 < 32) { nA = *(const f32x4*)(pp + (t + 1) * 384); nB = *(const f32x4*)(pp + (t + 1) * 384 + 4); nr = *(const f32x2*)(pp + (t + 1) * 384 + 8); nv = pv[(t + 1) * 16]; }
;                     float S0 = S.x, S1 = S.y;
;                     float d = S0 * a2.x; d = __builtin_fmaf(S1, a2.y, d);
;                     float t0 = S0 * w2.x; t0 = __builtin_fmaf(v, k2.x, t0); asm volatile("" : "+v"(t0));
;                     float t1 = S1 * w2.y; t1 = __builtin_fmaf(v, k2.y, t1); asm volatile("" : "+v"(t1));
;                     float yprev; const float sa = wkv_reduce(d, ep, yprev);
;                     S0 = __builtin_fmaf(sa, b2.x, t0); asm volatile("" : "+v"(S0));
;                     S1 = __builtin_fmaf(sa, b2.y, t1); asm volatile("" : "+v"(S1));
;                     ep = S0 * r2.x; ep = __builtin_fmaf(S1, r2.y, ep);
;                     S.x = S0; S.y = S1;
.LBB0_1636:
	v_readfirstlane_b32 s99, v0
	s_nop 3
	s_bitcmp1_b32 s99, 8
	s_cbranch_scc1 .Lwkv4_b2_skip
	v_mul_u32_u24_e32 v182, 0x60, v18
	v_and_b32_e32 v188, 8, v18
	v_mul_u32_u24_e32 v183, 0xc0, v18
	v_mad_u32_u24 v182, v188, 6, v182
	v_add_u32_e32 v183, 48, v183
	v_lshrrev_b32_e32 v188, 4, v0
	v_sub_u32_e32 v183, v183, v182
	v_lshlrev_b32_e32 v188, 2, v188
	v_add_u32_e32 v184, 0x10200, v182
	v_add_u32_e32 v186, 0x18000, v188
	v_add_u32_e32 v185, 0x10200, v183
	v_lshl_add_u32 v187, v18, 6, v188
	v_add_u32_e32 v187, 0x19000, v187
	ds_read_b128 v[190:193], v182 offset:49152
	ds_read_b128 v[194:197], v182 offset:49168
	ds_read_b64 v[228:229], v182 offset:49184
	ds_read_b128 v[198:201], v183 offset:49152
	ds_read_b128 v[202:205], v183 offset:49168
	ds_read_b64 v[230:231], v183 offset:49184
	ds_read_b32 v240, v186 offset:2048
	ds_read_b128 v[206:209], v182 offset:50688
	ds_read_b128 v[210:213], v182 offset:50704
	ds_read_b64 v[232:233], v182 offset:50720
	ds_read_b128 v[214:217], v183 offset:50688
	ds_read_b128 v[218:221], v183 offset:50704
	ds_read_b64 v[234:235], v183 offset:50720
	ds_read_b32 v241, v186 offset:2112
	s_waitcnt lgkmcnt(7)
	v_pk_mul_f32 v[150:151], v[142:143], v[190:191]
	v_pk_fma_f32 v[150:151], v[144:145], v[198:199], v[150:151]
	v_pk_mul_f32 v[146:147], v[142:143], v[192:193]
	v_add_f32_e32 v154, v150, v151
	v_pk_mul_f32 v[148:149], v[144:145], v[200:201]
	v_pk_fma_f32 v[146:147], v[240:241], v[196:197], v[146:147] op_sel:[0,0,0] op_sel_hi:[0,1,1]
	v_add_f32_dpp v154, v154, v154 quad_perm:[1,0,3,2] row_mask:0xf bank_mask:0xf bound_ctrl:1
	v_pk_fma_f32 v[148:149], v[240:241], v[204:205], v[148:149] op_sel:[0,0,0] op_sel_hi:[0,1,1]
	s_nop 0
	v_add_f32_dpp v154, v154, v154 quad_perm:[2,3,0,1] row_mask:0xf bank_mask:0xf bound_ctrl:1
	ds_read_b128 v[126:129], v182 offset:52224
	ds_read_b128 v[130:133], v182 offset:52240
	v_add_f32_dpp v154, v154, v154 row_half_mirror row_mask:0xf bank_mask:0xf bound_ctrl:1
	ds_read_b64 v[236:237], v182 offset:52256
	ds_read_b128 v[134:137], v183 offset:52224
	v_add_f32_dpp v154, v154, v154 row_mirror row_mask:0xf bank_mask:0xf bound_ctrl:1
	v_pk_fma_f32 v[146:147], v[154:155], v[194:195], v[146:147] op_sel_hi:[0,1,1]
	v_pk_fma_f32 v[148:149], v[154:155], v[202:203], v[148:149] op_sel_hi:[0,1,1]
	ds_read_b128 v[222:225], v183 offset:52240
	ds_read_b64 v[238:239], v183 offset:52256
	ds_read_b32 v242, v186 offset:2176
	s_waitcnt lgkmcnt(7)
	v_pk_mul_f32 v[150:151], v[146:147], v[206:207]
	v_pk_fma_f32 v[150:151], v[148:149], v[214:215], v[150:151]
	v_pk_mul_f32 v[152:153], v[146:147], v[228:229]
	v_add_f32_e32 v154, v150, v151
	v_pk_fma_f32 v[152:153], v[148:149], v[230:231], v[152:153]
	v_pk_mul_f32 v[142:143], v[146:147], v[208:209]
	v_add_f32_dpp v154, v154, v154 quad_perm:[1,0,3,2] row_mask:0xf bank_mask:0xf bound_ctrl:1
	v_pk_mul_f32 v[144:145], v[148:149], v[216:217]
	v_add_f32_e32 v156, v152, v153
	v_add_f32_dpp v154, v154, v154 quad_perm:[2,3,0,1] row_mask:0xf bank_mask:0xf bound_ctrl:1
	v_pk_fma_f32 v[142:143], v[240:241], v[212:213], v[142:143] op_sel:[1,0,0] op_sel_hi:[1,1,1]
	v_pk_fma_f32 v[144:145], v[240:241], v[220:221], v[144:145] op_sel:[1,0,0] op_sel_hi:[1,1,1]
	v_add_f32_dpp v154, v154, v154 row_half_mirror row_mask:0xf bank_mask:0xf bound_ctrl:1
	ds_read_b128 v[190:193], v182 offset:53760
	ds_read_b128 v[194:197], v182 offset:53776
	v_add_f32_dpp v154, v154, v154 row_mirror row_mask:0xf bank_mask:0xf bound_ctrl:1
	ds_read_b64 v[228:229], v182 offset:53792
	ds_read_b128 v[198:201], v183 offset:53760
	v_pk_fma_f32 v[142:143], v[154:155], v[210:211], v[142:143] op_sel_hi:[0,1,1]
	v_pk_fma_f32 v[144:145], v[154:155], v[218:219], v[144:145] op_sel_hi:[0,1,1]
	ds_read_b128 v[202:205], v183 offset:53776
	ds_read_b64 v[230:231], v183 offset:53792
	ds_read_b32 v240, v186 offset:2240
	s_waitcnt lgkmcnt(7)
	v_pk_mul_f32 v[150:151], v[142:143], v[126:127]
	v_pk_fma_f32 v[150:151], v[144:145], v[134:135], v[150:151]
	v_pk_mul_f32 v[152:153], v[142:143], v[232:233]
	v_add_f32_e32 v154, v150, v151
	v_pk_fma_f32 v[152:153], v[144:145], v[234:235], v[152:153]
	v_pk_mul_f32 v[146:147], v[142:143], v[128:129]
	v_add_f32_dpp v154, v154, v154 quad_perm:[1,0,3,2] row_mask:0xf bank_mask:0xf bound_ctrl:1
	v_pk_mul_f32 v[148:149], v[144:145], v[136:137]
	v_add_f32_e32 v157, v152, v153
	v_add_f32_dpp v154, v154, v154 quad_perm:[2,3,0,1] row_mask:0xf bank_mask:0xf bound_ctrl:1
	v_pk_fma_f32 v[146:147], v[242:243], v[132:133], v[146:147] op_sel:[0,0,0] op_sel_hi:[0,1,1]
	v_pk_fma_f32 v[148:149], v[242:243], v[224:225], v[148:149] op_sel:[0,0,0] op_sel_hi:[0,1,1]
	v_add_f32_dpp v154, v154, v154 row_half_mirror row_mask:0xf bank_mask:0xf bound_ctrl:1
	ds_read_b128 v[206:209], v182 offset:55296
	ds_read_b128 v[210:213], v182 offset:55312
	v_add_f32_dpp v154, v154, v154 row_mirror row_mask:0xf bank_mask:0xf bound_ctrl:1
	ds_read_b64 v[232:233], v182 offset:55328
	ds_read_b128 v[214:217], v183 offset:55296
	v_pk_fma_f32 v[146:147], v[154:155], v[130:131], v[146:147] op_sel_hi:[0,1,1]
	v_pk_fma_f32 v[148:149], v[154:155], v[222:223], v[148:149] op_sel_hi:[0,1,1]
	ds_read_b128 v[218:221], v183 offset:55312
	ds_read_b64 v[234:235], v183 offset:55328
	ds_read_b32 v241, v186 offset:2304
	s_waitcnt lgkmcnt(7)
; __device__ __forceinline__ void wkv_phase(const WkvT& W, unsigned char* lds) {
;     ...
;                 for (int t = 0; t < 32; ++t) {
;                     const f32x2 a2 = {nA[0], nA[1]}, w2 = {nA[2], nA[3]}, b2 = {nB[0], nB[1]}, k2 = {nB[2], nB[3]}, r2 = nr; const float v = nv;
;                     if (t + 1 < 32) { nA = *(const f32x4*)(pp + (t + 1) * 384); nB = *(const f32x4*)(pp + (t + 1) * 384 + 4); nr = *(const f32x2*)(pp + (t + 1) * 384 + 8); nv = pv[(t + 1) * 16]; }
;                     float S0 = S.x, S1 = S.y;
;                     float d = S0 * a2.x; d = __builtin_fmaf(S1, a2.y, d);
;                     float t0 = S0 * w2.x; t0 = __builtin_fmaf(v, k2.x, t0); asm volatile("" : "+v"(t0));
;                     float t1 = S1 * w2.y; t1 = __builtin_fmaf(v, k2.y, t1); asm volatile("" : "+v"(t1));
;                     float yprev; const float sa = wkv_reduce(d, ep, yprev);
;                     S0 = __builtin_fmaf(sa, b2.x, t0); asm volatile("" : "+v"(S0));
;                     S1 = __builtin_fmaf(sa, b2.y, t1); asm volatile("" : "+v"(S1));
;                     ep = S0 * r2.x; ep = __builtin_fmaf(S1, r2.y, ep);
;                     S.x = S0; S.y = S1;
	v_pk_mul_f32 v[150:151], v[146:147], v[190:191]
	v_pk_fma_f32 v[150:151], v[148:149], v[198:199], v[150:151]
	v_pk_mul_f32 v[152:153], v[146:147], v[236:237]
	v_add_f32_e32 v154, v150, v151
	v_pk_fma_f32 v[152:153], v[148:149], v[238:239], v[152:153]
	v_pk_mul_f32 v[142:143], v[146:147], v[192:193]
	v_add_f32_dpp v154, v154, v154 quad_perm:[1,0,3,2] row_mask:0xf bank_mask:0xf bound_ctrl:1
	v_pk_mul_f32 v[144:145], v[148:149], v[200:201]
	v_add_f32_e32 v158, v152, v153
	v_add_f32_dpp v154, v154, v154 quad_perm:[2,3,0,1] row_mask:0xf bank_mask:0xf bound_ctrl:1
	v_pk_fma_f32 v[142:143], v[240:241], v[196:197], v[142:143] op_sel:[0,0,0] op_sel_hi:[0,1,1]
	v_pk_fma_f32 v[144:145], v[240:241], v[204:205], v[144:145] op_sel:[0,0,0] op_sel_hi:[0,1,1]
	v_add_f32_dpp v154, v154, v154 row_half_mirror row_mask:0xf bank_mask:0xf bound_ctrl:1
	ds_read_b128 v[126:129], v182 offset:56832
	ds_read_b128 v[130:133], v182 offset:56848
	v_add_f32_dpp v154, v154, v154 row_mirror row_mask:0xf bank_mask:0xf bound_ctrl:1
	ds_read_b64 v[236:237], v182 offset:56864
	ds_read_b128 v[134:137], v183 offset:56832
	v_pk_fma_f32 v[142:143], v[154:155], v[194:195], v[142:143] op_sel_hi:[0,1,1]
	v_pk_fma_f32 v[144:145], v[154:155], v[202:203], v[144:145] op_sel_hi:[0,1,1]
	ds_read_b128 v[222:225], v183 offset:56848
	ds_read_b64 v[238:239], v183 offset:56864
	ds_read_b32 v242, v186 offset:2368
	s_waitcnt lgkmcnt(7)
	v_pk_mul_f32 v[150:151], v[142:143], v[206:207]
	v_pk_fma_f32 v[150:151], v[144:145], v[214:215], v[150:151]
	v_pk_mul_f32 v[152:153], v[142:143], v[228:229]
	v_add_f32_e32 v154, v150, v151
	v_pk_fma_f32 v[152:153], v[144:145], v[230:231], v[152:153]
	v_pk_mul_f32 v[146:147], v[142:143], v[208:209]
	v_add_f32_dpp v154, v154, v154 quad_perm:[1,0,3,2] row_mask:0xf bank_mask:0xf bound_ctrl:1
	v_pk_mul_f32 v[148:149], v[144:145], v[216:217]
	v_add_f32_e32 v159, v152, v153
	v_add_f32_dpp v154, v154, v154 quad_perm:[2,3,0,1] row_mask:0xf bank_mask:0xf bound_ctrl:1
	v_pk_fma_f32 v[146:147], v[240:241], v[212:213], v[146:147] op_sel:[1,0,0] op_sel_hi:[1,1,1]
	v_pk_fma_f32 v[148:149], v[240:241], v[220:221], v[148:149] op_sel:[1,0,0] op_sel_hi:[1,1,1]
	v_add_f32_dpp v154, v154, v154 row_half_mirror row_mask:0xf bank_mask:0xf bound_ctrl:1
	ds_read_b128 v[190:193], v182 offset:58368
	ds_read_b128 v[194:197], v182 offset:58384
	v_add_f32_dpp v154, v154, v154 row_mirror row_mask:0xf bank_mask:0xf bound_ctrl:1
	ds_read_b64 v[228:229], v182 offset:58400
	ds_read_b128 v[198:201], v183 offset:58368
	v_pk_fma_f32 v[146:147], v[154:155], v[210:211], v[146:147] op_sel_hi:[0,1,1]
	v_pk_fma_f32 v[148:149], v[154:155], v[218:219], v[148:149] op_sel_hi:[0,1,1]
	ds_read_b128 v[202:205], v183 offset:58384
	ds_read_b64 v[230:231], v183 offset:58400
	ds_read_b32 v240, v186 offset:2432
	s_waitcnt lgkmcnt(7)
	v_pk_mul_f32 v[150:151], v[146:147], v[126:127]
	v_pk_fma_f32 v[150:151], v[148:149], v[134:135], v[150:151]
	v_pk_mul_f32 v[152:153], v[146:147], v[232:233]
	v_add_f32_e32 v154, v150, v151
	v_pk_fma_f32 v[152:153], v[148:149], v[234:235], v[152:153]
	v_pk_mul_f32 v[142:143], v[146:147], v[128:129]
	v_add_f32_dpp v154, v154, v154 quad_perm:[1,0,3,2] row_mask:0xf bank_mask:0xf bound_ctrl:1
	v_pk_mul_f32 v[144:145], v[148:149], v[136:137]
	v_add_f32_e32 v160, v152, v153
	v_add_f32_dpp v154, v154, v154 quad_perm:[2,3,0,1] row_mask:0xf bank_mask:0xf bound_ctrl:1
	v_pk_fma_f32 v[142:143], v[242:243], v[132:133], v[142:143] op_sel:[0,0,0] op_sel_hi:[0,1,1]
	v_pk_fma_f32 v[144:145], v[242:243], v[224:225], v[144:145] op_sel:[0,0,0] op_sel_hi:[0,1,1]
	v_add_f32_dpp v154, v154, v154 row_half_mirror row_mask:0xf bank_mask:0xf bound_ctrl:1
	ds_read_b128 v[206:209], v182 offset:59904
	ds_read_b128 v[210:213], v182 offset:59920
	v_add_f32_dpp v154, v154, v154 row_mirror row_mask:0xf bank_mask:0xf bound_ctrl:1
	ds_read_b64 v[232:233], v182 offset:59936
	ds_read_b128 v[214:217], v183 offset:59904
	v_pk_fma_f32 v[142:143], v[154:155], v[130:131], v[142:143] op_sel_hi:[0,1,1]
	v_pk_fma_f32 v[144:145], v[154:155], v[222:223], v[144:145] op_sel_hi:[0,1,1]
	ds_read_b128 v[218:221], v183 offset:59920
	ds_read_b64 v[234:235], v183 offset:59936
	ds_read_b32 v241, v186 offset:2496
	s_waitcnt lgkmcnt(7)
	v_pk_mul_f32 v[150:151], v[142:143], v[190:191]
	v_pk_fma_f32 v[150:151], v[144:145], v[198:199], v[150:151]
	v_pk_mul_f32 v[152:153], v[142:143], v[236:237]
	v_add_f32_e32 v154, v150, v151
	v_pk_fma_f32 v[152:153], v[144:145], v[238:239], v[152:153]
	v_pk_mul_f32 v[146:147], v[142:143], v[192:193]
	v_add_f32_dpp v154, v154, v154 quad_perm:[1,0,3,2] row_mask:0xf bank_mask:0xf bound_ctrl:1
	v_pk_mul_f32 v[148:149], v[144:145], v[200:201]
	v_add_f32_e32 v161, v152, v153
	v_add_f32_dpp v154, v154, v154 quad_perm:[2,3,0,1] row_mask:0xf bank_mask:0xf bound_ctrl:1
	v_pk_fma_f32 v[146:147], v[240:241], v[196:197], v[146:147] op_sel:[0,0,0] op_sel_hi:[0,1,1]
	v_pk_fma_f32 v[148:149], v[240:241], v[204:205], v[148:149] op_sel:[0,0,0] op_sel_hi:[0,1,1]
	v_add_f32_dpp v154, v154, v154 row_half_mirror row_mask:0xf bank_mask:0xf bound_ctrl:1
	ds_read_b128 v[126:129], v182 offset:61440
	ds_read_b128 v[130:133], v182 offset:61456
	v_add_f32_dpp v154, v154, v154 row_mirror row_mask:0xf bank_mask:0xf bound_ctrl:1
	ds_read_b64 v[236:237], v182 offset:61472
	ds_read_b128 v[134:137], v183 offset:61440
	v_pk_fma_f32 v[146:147], v[154:155], v[194:195], v[146:147] op_sel_hi:[0,1,1]
	v_pk_fma_f32 v[148:149], v[154:155], v[202:203], v[148:149] op_sel_hi:[0,1,1]
	ds_read_b128 v[222:225], v183 offset:61456
	ds_read_b64 v[238:239], v183 offset:61472
	ds_read_b32 v242, v186 offset:2560
	s_waitcnt lgkmcnt(7)
; __device__ __forceinline__ void wkv_phase(const WkvT& W, unsigned char* lds) {
;     ...
;                 for (int t = 0; t < 32; ++t) {
;                     const f32x2 a2 = {nA[0], nA[1]}, w2 = {nA[2], nA[3]}, b2 = {nB[0], nB[1]}, k2 = {nB[2], nB[3]}, r2 = nr; const float v = nv;
;                     if (t + 1 < 32) { nA = *(const f32x4*)(pp + (t + 1) * 384); nB = *(const f32x4*)(pp + (t + 1) * 384 + 4); nr = *(const f32x2*)(pp + (t + 1) * 384 + 8); nv = pv[(t + 1) * 16]; }
;                     float S0 = S.x, S1 = S.y;
;                     float d = S0 * a2.x; d = __builtin_fmaf(S1, a2.y, d);
;                     float t0 = S0 * w2.x; t0 = __builtin_fmaf(v, k2.x, t0); asm volatile("" : "+v"(t0));
;                     float t1 = S1 * w2.y; t1 = __builtin_fmaf(v, k2.y, t1); asm volatile("" : "+v"(t1));
;                     float yprev; const float sa = wkv_reduce(d, ep, yprev);
;                     S0 = __builtin_fmaf(sa, b2.x, t0); asm volatile("" : "+v"(S0));
;                     S1 = __builtin_fmaf(sa, b2.y, t1); asm volatile("" : "+v"(S1));
;                     ep = S0 * r2.x; ep = __builtin_fmaf(S1, r2.y, ep);
;                     S.x = S0; S.y = S1;
	v_pk_mul_f32 v[150:151], v[146:147], v[206:207]
	v_pk_fma_f32 v[150:151], v[148:149], v[214:215], v[150:151]
	v_pk_mul_f32 v[152:153], v[146:147], v[228:229]
	v_add_f32_e32 v154, v150, v151
	v_pk_fma_f32 v[152:153], v[148:149], v[230:231], v[152:153]
	v_pk_mul_f32 v[142:143], v[146:147], v[208:209]
	v_add_f32_dpp v154, v154, v154 quad_perm:[1,0,3,2] row_mask:0xf bank_mask:0xf bound_ctrl:1
	v_pk_mul_f32 v[144:145], v[148:149], v[216:217]
	v_add_f32_e32 v162, v152, v153
	v_add_f32_dpp v154, v154, v154 quad_perm:[2,3,0,1] row_mask:0xf bank_mask:0xf bound_ctrl:1
	v_pk_fma_f32 v[142:143], v[240:241], v[212:213], v[142:143] op_sel:[1,0,0] op_sel_hi:[1,1,1]
	v_pk_fma_f32 v[144:145], v[240:241], v[220:221], v[144:145] op_sel:[1,0,0] op_sel_hi:[1,1,1]
	v_add_f32_dpp v154, v154, v154 row_half_mirror row_mask:0xf bank_mask:0xf bound_ctrl:1
	ds_read_b128 v[190:193], v182 offset:62976
	ds_read_b128 v[194:197], v182 offset:62992
	v_add_f32_dpp v154, v154, v154 row_mirror row_mask:0xf bank_mask:0xf bound_ctrl:1
	ds_read_b64 v[228:229], v182 offset:63008
	ds_read_b128 v[198:201], v183 offset:62976
	v_pk_fma_f32 v[142:143], v[154:155], v[210:211], v[142:143] op_sel_hi:[0,1,1]
	v_pk_fma_f32 v[144:145], v[154:155], v[218:219], v[144:145] op_sel_hi:[0,1,1]
	ds_read_b128 v[202:205], v183 offset:62992
	ds_read_b64 v[230:231], v183 offset:63008
	ds_read_b32 v240, v186 offset:2624
	s_waitcnt lgkmcnt(7)
	v_pk_mul_f32 v[150:151], v[142:143], v[126:127]
	v_pk_fma_f32 v[150:151], v[144:145], v[134:135], v[150:151]
	v_pk_mul_f32 v[152:153], v[142:143], v[232:233]
	v_add_f32_e32 v154, v150, v151
	v_pk_fma_f32 v[152:153], v[144:145], v[234:235], v[152:153]
	v_pk_mul_f32 v[146:147], v[142:143], v[128:129]
	v_add_f32_dpp v154, v154, v154 quad_perm:[1,0,3,2] row_mask:0xf bank_mask:0xf bound_ctrl:1
	v_pk_mul_f32 v[148:149], v[144:145], v[136:137]
	v_add_f32_e32 v163, v152, v153
	v_add_f32_dpp v154, v154, v154 quad_perm:[2,3,0,1] row_mask:0xf bank_mask:0xf bound_ctrl:1
	v_pk_fma_f32 v[146:147], v[242:243], v[132:133], v[146:147] op_sel:[0,0,0] op_sel_hi:[0,1,1]
	v_pk_fma_f32 v[148:149], v[242:243], v[224:225], v[148:149] op_sel:[0,0,0] op_sel_hi:[0,1,1]
	v_add_f32_dpp v154, v154, v154 row_half_mirror row_mask:0xf bank_mask:0xf bound_ctrl:1
	ds_read_b128 v[206:209], v182 offset:64512
	ds_read_b128 v[210:213], v182 offset:64528
	v_add_f32_dpp v154, v154, v154 row_mirror row_mask:0xf bank_mask:0xf bound_ctrl:1
	ds_read_b64 v[232:233], v182 offset:64544
	ds_read_b128 v[214:217], v183 offset:64512
	v_pk_fma_f32 v[146:147], v[154:155], v[130:131], v[146:147] op_sel_hi:[0,1,1]
	v_pk_fma_f32 v[148:149], v[154:155], v[222:223], v[148:149] op_sel_hi:[0,1,1]
	ds_read_b128 v[218:221], v183 offset:64528
	ds_read_b64 v[234:235], v183 offset:64544
	ds_read_b32 v241, v186 offset:2688
	s_waitcnt lgkmcnt(7)
	v_pk_mul_f32 v[150:151], v[146:147], v[190:191]
	v_pk_fma_f32 v[150:151], v[148:149], v[198:199], v[150:151]
	v_pk_mul_f32 v[152:153], v[146:147], v[236:237]
	v_add_f32_e32 v154, v150, v151
	v_pk_fma_f32 v[152:153], v[148:149], v[238:239], v[152:153]
	v_pk_mul_f32 v[142:143], v[146:147], v[192:193]
	v_add_f32_dpp v154, v154, v154 quad_perm:[1,0,3,2] row_mask:0xf bank_mask:0xf bound_ctrl:1
	v_pk_mul_f32 v[144:145], v[148:149], v[200:201]
	v_add_f32_e32 v164, v152, v153
	v_add_f32_dpp v154, v154, v154 quad_perm:[2,3,0,1] row_mask:0xf bank_mask:0xf bound_ctrl:1
	v_pk_fma_f32 v[142:143], v[240:241], v[196:197], v[142:143] op_sel:[0,0,0] op_sel_hi:[0,1,1]
	v_pk_fma_f32 v[144:145], v[240:241], v[204:205], v[144:145] op_sel:[0,0,0] op_sel_hi:[0,1,1]
	v_add_f32_dpp v154, v154, v154 row_half_mirror row_mask:0xf bank_mask:0xf bound_ctrl:1
	ds_read_b128 v[126:129], v184
	ds_read_b128 v[130:133], v184 offset:16
	v_add_f32_dpp v154, v154, v154 row_mirror row_mask:0xf bank_mask:0xf bound_ctrl:1
	ds_read_b64 v[236:237], v184 offset:32
	ds_read_b128 v[134:137], v185
	v_pk_fma_f32 v[142:143], v[154:155], v[194:195], v[142:143] op_sel_hi:[0,1,1]
	v_pk_fma_f32 v[144:145], v[154:155], v[202:203], v[144:145] op_sel_hi:[0,1,1]
	ds_read_b128 v[222:225], v185 offset:16
	ds_read_b64 v[238:239], v185 offset:32
	ds_read_b32 v242, v186 offset:2752
	s_waitcnt lgkmcnt(7)
	v_pk_mul_f32 v[150:151], v[142:143], v[206:207]
	v_pk_fma_f32 v[150:151], v[144:145], v[214:215], v[150:151]
	v_pk_mul_f32 v[152:153], v[142:143], v[228:229]
	v_add_f32_e32 v154, v150, v151
	v_pk_fma_f32 v[152:153], v[144:145], v[230:231], v[152:153]
	v_pk_mul_f32 v[146:147], v[142:143], v[208:209]
	v_add_f32_dpp v154, v154, v154 quad_perm:[1,0,3,2] row_mask:0xf bank_mask:0xf bound_ctrl:1
	v_pk_mul_f32 v[148:149], v[144:145], v[216:217]
	v_add_f32_e32 v165, v152, v153
	v_add_f32_dpp v154, v154, v154 quad_perm:[2,3,0,1] row_mask:0xf bank_mask:0xf bound_ctrl:1
	v_pk_fma_f32 v[146:147], v[240:241], v[212:213], v[146:147] op_sel:[1,0,0] op_sel_hi:[1,1,1]
	v_pk_fma_f32 v[148:149], v[240:241], v[220:221], v[148:149] op_sel:[1,0,0] op_sel_hi:[1,1,1]
	v_add_f32_dpp v154, v154, v154 row_half_mirror row_mask:0xf bank_mask:0xf bound_ctrl:1
	ds_read_b128 v[190:193], v184 offset:1536
	ds_read_b128 v[194:197], v184 offset:1552
	v_add_f32_dpp v154, v154, v154 row_mirror row_mask:0xf bank_mask:0xf bound_ctrl:1
	ds_read_b64 v[228:229], v184 offset:1568
	ds_read_b128 v[198:201], v185 offset:1536
	v_pk_fma_f32 v[146:147], v[154:155], v[210:211], v[146:147] op_sel_hi:[0,1,1]
	v_pk_fma_f32 v[148:149], v[154:155], v[218:219], v[148:149] op_sel_hi:[0,1,1]
	ds_read_b128 v[202:205], v185 offset:1552
	ds_read_b64 v[230:231], v185 offset:1568
	ds_read_b32 v240, v186 offset:2816
	s_waitcnt lgkmcnt(7)
; __device__ __forceinline__ void wkv_phase(const WkvT& W, unsigned char* lds) {
;     ...
;                 for (int t = 0; t < 32; ++t) {
;                     const f32x2 a2 = {nA[0], nA[1]}, w2 = {nA[2], nA[3]}, b2 = {nB[0], nB[1]}, k2 = {nB[2], nB[3]}, r2 = nr; const float v = nv;
;                     if (t + 1 < 32) { nA = *(const f32x4*)(pp + (t + 1) * 384); nB = *(const f32x4*)(pp + (t + 1) * 384 + 4); nr = *(const f32x2*)(pp + (t + 1) * 384 + 8); nv = pv[(t + 1) * 16]; }
;                     float S0 = S.x, S1 = S.y;
;                     float d = S0 * a2.x; d = __builtin_fmaf(S1, a2.y, d);
;                     float t0 = S0 * w2.x; t0 = __builtin_fmaf(v, k2.x, t0); asm volatile("" : "+v"(t0));
;                     float t1 = S1 * w2.y; t1 = __builtin_fmaf(v, k2.y, t1); asm volatile("" : "+v"(t1));
;                     float yprev; const float sa = wkv_reduce(d, ep, yprev);
;                     S0 = __builtin_fmaf(sa, b2.x, t0); asm volatile("" : "+v"(S0));
;                     S1 = __builtin_fmaf(sa, b2.y, t1); asm volatile("" : "+v"(S1));
;                     ep = S0 * r2.x; ep = __builtin_fmaf(S1, r2.y, ep);
;                     S.x = S0; S.y = S1;
	v_pk_mul_f32 v[150:151], v[146:147], v[126:127]
	v_pk_fma_f32 v[150:151], v[148:149], v[134:135], v[150:151]
	v_pk_mul_f32 v[152:153], v[146:147], v[232:233]
	v_add_f32_e32 v154, v150, v151
	v_pk_fma_f32 v[152:153], v[148:149], v[234:235], v[152:153]
	v_pk_mul_f32 v[142:143], v[146:147], v[128:129]
	v_add_f32_dpp v154, v154, v154 quad_perm:[1,0,3,2] row_mask:0xf bank_mask:0xf bound_ctrl:1
	v_pk_mul_f32 v[144:145], v[148:149], v[136:137]
	v_add_f32_e32 v166, v152, v153
	v_add_f32_dpp v154, v154, v154 quad_perm:[2,3,0,1] row_mask:0xf bank_mask:0xf bound_ctrl:1
	v_pk_fma_f32 v[142:143], v[242:243], v[132:133], v[142:143] op_sel:[0,0,0] op_sel_hi:[0,1,1]
	v_pk_fma_f32 v[144:145], v[242:243], v[224:225], v[144:145] op_sel:[0,0,0] op_sel_hi:[0,1,1]
	v_add_f32_dpp v154, v154, v154 row_half_mirror row_mask:0xf bank_mask:0xf bound_ctrl:1
	ds_read_b128 v[206:209], v184 offset:3072
	ds_read_b128 v[210:213], v184 offset:3088
	v_add_f32_dpp v154, v154, v154 row_mirror row_mask:0xf bank_mask:0xf bound_ctrl:1
	ds_read_b64 v[232:233], v184 offset:3104
	ds_read_b128 v[214:217], v185 offset:3072
	v_pk_fma_f32 v[142:143], v[154:155], v[130:131], v[142:143] op_sel_hi:[0,1,1]
	v_pk_fma_f32 v[144:145], v[154:155], v[222:223], v[144:145] op_sel_hi:[0,1,1]
	ds_read_b128 v[218:221], v185 offset:3088
	ds_read_b64 v[234:235], v185 offset:3104
	ds_read_b32 v241, v186 offset:2880
	s_waitcnt lgkmcnt(7)
	v_pk_mul_f32 v[150:151], v[142:143], v[190:191]
	v_pk_fma_f32 v[150:151], v[144:145], v[198:199], v[150:151]
	v_pk_mul_f32 v[152:153], v[142:143], v[236:237]
	v_add_f32_e32 v154, v150, v151
	v_pk_fma_f32 v[152:153], v[144:145], v[238:239], v[152:153]
	v_pk_mul_f32 v[146:147], v[142:143], v[192:193]
	v_add_f32_dpp v154, v154, v154 quad_perm:[1,0,3,2] row_mask:0xf bank_mask:0xf bound_ctrl:1
	v_pk_mul_f32 v[148:149], v[144:145], v[200:201]
	v_add_f32_e32 v167, v152, v153
	v_add_f32_dpp v154, v154, v154 quad_perm:[2,3,0,1] row_mask:0xf bank_mask:0xf bound_ctrl:1
	v_pk_fma_f32 v[146:147], v[240:241], v[196:197], v[146:147] op_sel:[0,0,0] op_sel_hi:[0,1,1]
	v_pk_fma_f32 v[148:149], v[240:241], v[204:205], v[148:149] op_sel:[0,0,0] op_sel_hi:[0,1,1]
	v_add_f32_dpp v154, v154, v154 row_half_mirror row_mask:0xf bank_mask:0xf bound_ctrl:1
	ds_read_b128 v[126:129], v184 offset:4608
	ds_read_b128 v[130:133], v184 offset:4624
	v_add_f32_dpp v154, v154, v154 row_mirror row_mask:0xf bank_mask:0xf bound_ctrl:1
	ds_read_b64 v[236:237], v184 offset:4640
	ds_read_b128 v[134:137], v185 offset:4608
	v_pk_fma_f32 v[146:147], v[154:155], v[194:195], v[146:147] op_sel_hi:[0,1,1]
	v_pk_fma_f32 v[148:149], v[154:155], v[202:203], v[148:149] op_sel_hi:[0,1,1]
	ds_read_b128 v[222:225], v185 offset:4624
	ds_read_b64 v[238:239], v185 offset:4640
	ds_read_b32 v242, v186 offset:2944
	s_waitcnt lgkmcnt(7)
	v_pk_mul_f32 v[150:151], v[146:147], v[206:207]
	v_pk_fma_f32 v[150:151], v[148:149], v[214:215], v[150:151]
	v_pk_mul_f32 v[152:153], v[146:147], v[228:229]
	v_add_f32_e32 v154, v150, v151
	v_pk_fma_f32 v[152:153], v[148:149], v[230:231], v[152:153]
	v_pk_mul_f32 v[142:143], v[146:147], v[208:209]
	v_add_f32_dpp v154, v154, v154 quad_perm:[1,0,3,2] row_mask:0xf bank_mask:0xf bound_ctrl:1
	v_pk_mul_f32 v[144:145], v[148:149], v[216:217]
	v_add_f32_e32 v168, v152, v153
	v_add_f32_dpp v154, v154, v154 quad_perm:[2,3,0,1] row_mask:0xf bank_mask:0xf bound_ctrl:1
	v_pk_fma_f32 v[142:143], v[240:241], v[212:213], v[142:143] op_sel:[1,0,0] op_sel_hi:[1,1,1]
	v_pk_fma_f32 v[144:145], v[240:241], v[220:221], v[144:145] op_sel:[1,0,0] op_sel_hi:[1,1,1]
	v_add_f32_dpp v154, v154, v154 row_half_mirror row_mask:0xf bank_mask:0xf bound_ctrl:1
	ds_read_b128 v[190:193], v184 offset:6144
	ds_read_b128 v[194:197], v184 offset:6160
	v_add_f32_dpp v154, v154, v154 row_mirror row_mask:0xf bank_mask:0xf bound_ctrl:1
	ds_read_b64 v[228:229], v184 offset:6176
	ds_read_b128 v[198:201], v185 offset:6144
	v_pk_fma_f32 v[142:143], v[154:155], v[210:211], v[142:143] op_sel_hi:[0,1,1]
	v_pk_fma_f32 v[144:145], v[154:155], v[218:219], v[144:145] op_sel_hi:[0,1,1]
	ds_read_b128 v[202:205], v185 offset:6160
	ds_read_b64 v[230:231], v185 offset:6176
	ds_read_b32 v240, v186 offset:3008
	s_waitcnt lgkmcnt(7)
	v_pk_mul_f32 v[150:151], v[142:143], v[126:127]
	v_pk_fma_f32 v[150:151], v[144:145], v[134:135], v[150:151]
	v_pk_mul_f32 v[152:153], v[142:143], v[232:233]
	v_add_f32_e32 v154, v150, v151
	v_pk_fma_f32 v[152:153], v[144:145], v[234:235], v[152:153]
	v_pk_mul_f32 v[146:147], v[142:143], v[128:129]
	v_add_f32_dpp v154, v154, v154 quad_perm:[1,0,3,2] row_mask:0xf bank_mask:0xf bound_ctrl:1
	v_pk_mul_f32 v[148:149], v[144:145], v[136:137]
	v_add_f32_e32 v169, v152, v153
	v_add_f32_dpp v154, v154, v154 quad_perm:[2,3,0,1] row_mask:0xf bank_mask:0xf bound_ctrl:1
	v_pk_fma_f32 v[146:147], v[242:243], v[132:133], v[146:147] op_sel:[0,0,0] op_sel_hi:[0,1,1]
	v_pk_fma_f32 v[148:149], v[242:243], v[224:225], v[148:149] op_sel:[0,0,0] op_sel_hi:[0,1,1]
	v_add_f32_dpp v154, v154, v154 row_half_mirror row_mask:0xf bank_mask:0xf bound_ctrl:1
	ds_read_b128 v[206:209], v184 offset:7680
	ds_read_b128 v[210:213], v184 offset:7696
	v_add_f32_dpp v154, v154, v154 row_mirror row_mask:0xf bank_mask:0xf bound_ctrl:1
	ds_read_b64 v[232:233], v184 offset:7712
	ds_read_b128 v[214:217], v185 offset:7680
	v_pk_fma_f32 v[146:147], v[154:155], v[130:131], v[146:147] op_sel_hi:[0,1,1]
	v_pk_fma_f32 v[148:149], v[154:155], v[222:223], v[148:149] op_sel_hi:[0,1,1]
	ds_read_b128 v[218:221], v185 offset:7696
	ds_read_b64 v[234:235], v185 offset:7712
	ds_read_b32 v241, v186 offset:3072
	s_waitcnt lgkmcnt(7)
; __device__ __forceinline__ void wkv_phase(const WkvT& W, unsigned char* lds) {
;     ...
;                 for (int t = 0; t < 32; ++t) {
;                     const f32x2 a2 = {nA[0], nA[1]}, w2 = {nA[2], nA[3]}, b2 = {nB[0], nB[1]}, k2 = {nB[2], nB[3]}, r2 = nr; const float v = nv;
;                     if (t + 1 < 32) { nA = *(const f32x4*)(pp + (t + 1) * 384); nB = *(const f32x4*)(pp + (t + 1) * 384 + 4); nr = *(const f32x2*)(pp + (t + 1) * 384 + 8); nv = pv[(t + 1) * 16]; }
;                     float S0 = S.x, S1 = S.y;
;                     float d = S0 * a2.x; d = __builtin_fmaf(S1, a2.y, d);
;                     float t0 = S0 * w2.x; t0 = __builtin_fmaf(v, k2.x, t0); asm volatile("" : "+v"(t0));
;                     float t1 = S1 * w2.y; t1 = __builtin_fmaf(v, k2.y, t1); asm volatile("" : "+v"(t1));
;                     float yprev; const float sa = wkv_reduce(d, ep, yprev);
;                     S0 = __builtin_fmaf(sa, b2.x, t0); asm volatile("" : "+v"(S0));
;                     S1 = __builtin_fmaf(sa, b2.y, t1); asm volatile("" : "+v"(S1));
;                     ep = S0 * r2.x; ep = __builtin_fmaf(S1, r2.y, ep);
;                     S.x = S0; S.y = S1;
;                     if (t >= 1) { const bool hit = oddrow && ((lane & 15) == ((t - 1) & 15)); if (t <= 16) yk0 = hit ? yprev : yk0; else yk1 = hit ? yprev : yk1; }
;                 }
;                 { float ylast; (void)wkv_reduce(0.f, ep, ylast); yk1 = (oddrow && (lane & 15) == 15) ? ylast : yk1; }
;                 if (oddrow) { sY[bi * 512 + (lane & 15) * 16 + il] = yk0; sY[bi * 512 + (16 + (lane & 15)) * 16 + il] = yk1; }
	v_pk_mul_f32 v[150:151], v[146:147], v[190:191]
	v_pk_fma_f32 v[150:151], v[148:149], v[198:199], v[150:151]
	v_pk_mul_f32 v[152:153], v[146:147], v[236:237]
	v_add_f32_e32 v154, v150, v151
	v_pk_fma_f32 v[152:153], v[148:149], v[238:239], v[152:153]
	v_pk_mul_f32 v[142:143], v[146:147], v[192:193]
	v_add_f32_dpp v154, v154, v154 quad_perm:[1,0,3,2] row_mask:0xf bank_mask:0xf bound_ctrl:1
	v_pk_mul_f32 v[144:145], v[148:149], v[200:201]
	v_add_f32_e32 v170, v152, v153
	v_add_f32_dpp v154, v154, v154 quad_perm:[2,3,0,1] row_mask:0xf bank_mask:0xf bound_ctrl:1
	v_pk_fma_f32 v[142:143], v[240:241], v[196:197], v[142:143] op_sel:[0,0,0] op_sel_hi:[0,1,1]
	v_pk_fma_f32 v[144:145], v[240:241], v[204:205], v[144:145] op_sel:[0,0,0] op_sel_hi:[0,1,1]
	v_add_f32_dpp v154, v154, v154 row_half_mirror row_mask:0xf bank_mask:0xf bound_ctrl:1
	ds_read_b128 v[126:129], v184 offset:9216
	ds_read_b128 v[130:133], v184 offset:9232
	v_add_f32_dpp v154, v154, v154 row_mirror row_mask:0xf bank_mask:0xf bound_ctrl:1
	ds_read_b64 v[236:237], v184 offset:9248
	ds_read_b128 v[134:137], v185 offset:9216
	v_pk_fma_f32 v[142:143], v[154:155], v[194:195], v[142:143] op_sel_hi:[0,1,1]
	v_pk_fma_f32 v[144:145], v[154:155], v[202:203], v[144:145] op_sel_hi:[0,1,1]
	ds_read_b128 v[222:225], v185 offset:9232
	ds_read_b64 v[238:239], v185 offset:9248
	ds_read_b32 v242, v186 offset:3136
	s_waitcnt lgkmcnt(7)
	v_pk_mul_f32 v[150:151], v[142:143], v[206:207]
	v_pk_fma_f32 v[150:151], v[144:145], v[214:215], v[150:151]
	v_pk_mul_f32 v[152:153], v[142:143], v[228:229]
	v_add_f32_e32 v154, v150, v151
	v_pk_fma_f32 v[152:153], v[144:145], v[230:231], v[152:153]
	v_pk_mul_f32 v[146:147], v[142:143], v[208:209]
	v_add_f32_dpp v154, v154, v154 quad_perm:[1,0,3,2] row_mask:0xf bank_mask:0xf bound_ctrl:1
	v_pk_mul_f32 v[148:149], v[144:145], v[216:217]
	v_add_f32_e32 v171, v152, v153
	v_add_f32_dpp v154, v154, v154 quad_perm:[2,3,0,1] row_mask:0xf bank_mask:0xf bound_ctrl:1
	v_pk_fma_f32 v[146:147], v[240:241], v[212:213], v[146:147] op_sel:[1,0,0] op_sel_hi:[1,1,1]
	v_pk_fma_f32 v[148:149], v[240:241], v[220:221], v[148:149] op_sel:[1,0,0] op_sel_hi:[1,1,1]
	v_add_f32_dpp v154, v154, v154 row_half_mirror row_mask:0xf bank_mask:0xf bound_ctrl:1
	ds_read_b128 v[190:193], v184 offset:10752
	ds_read_b128 v[194:197], v184 offset:10768
	v_add_f32_dpp v154, v154, v154 row_mirror row_mask:0xf bank_mask:0xf bound_ctrl:1
	ds_read_b64 v[228:229], v184 offset:10784
	ds_read_b128 v[198:201], v185 offset:10752
	v_pk_fma_f32 v[146:147], v[154:155], v[210:211], v[146:147] op_sel_hi:[0,1,1]
	v_pk_fma_f32 v[148:149], v[154:155], v[218:219], v[148:149] op_sel_hi:[0,1,1]
	ds_read_b128 v[202:205], v185 offset:10768
	ds_read_b64 v[230:231], v185 offset:10784
	ds_read_b32 v240, v186 offset:3200
	s_waitcnt lgkmcnt(7)
	v_cndmask_b32_e64 v172, v164, v156, s[10:11]
	v_cndmask_b32_e64 v174, v165, v157, s[10:11]
	v_cndmask_b32_e64 v176, v166, v158, s[10:11]
	v_cndmask_b32_e64 v178, v167, v159, s[10:11]
	v_cndmask_b32_e64 v173, v156, v164, s[10:11]
	v_cndmask_b32_e64 v175, v157, v165, s[10:11]
	v_cndmask_b32_e64 v177, v158, v166, s[10:11]
	v_cndmask_b32_e64 v179, v159, v167, s[10:11]
	v_add_f32_dpp v156, v172, v173 row_ror:8 row_mask:0xf bank_mask:0xf
	v_add_f32_dpp v157, v174, v175 row_ror:8 row_mask:0xf bank_mask:0xf
	v_add_f32_dpp v158, v176, v177 row_ror:8 row_mask:0xf bank_mask:0xf
	v_add_f32_dpp v159, v178, v179 row_ror:8 row_mask:0xf bank_mask:0xf
	v_cndmask_b32_e64 v172, v168, v160, s[10:11]
	v_cndmask_b32_e64 v174, v169, v161, s[10:11]
	v_cndmask_b32_e64 v176, v170, v162, s[10:11]
	v_cndmask_b32_e64 v178, v171, v163, s[10:11]
	v_cndmask_b32_e64 v173, v160, v168, s[10:11]
	v_cndmask_b32_e64 v175, v161, v169, s[10:11]
	v_cndmask_b32_e64 v177, v162, v170, s[10:11]
	v_cndmask_b32_e64 v179, v163, v171, s[10:11]
	v_add_f32_dpp v160, v172, v173 row_ror:8 row_mask:0xf bank_mask:0xf
	v_add_f32_dpp v161, v174, v175 row_ror:8 row_mask:0xf bank_mask:0xf
	v_add_f32_dpp v162, v176, v177 row_ror:8 row_mask:0xf bank_mask:0xf
	v_add_f32_dpp v163, v178, v179 row_ror:8 row_mask:0xf bank_mask:0xf
	v_cndmask_b32_e64 v172, v160, v156, s[12:13]
	v_cndmask_b32_e64 v174, v161, v157, s[12:13]
	v_cndmask_b32_e64 v176, v162, v158, s[12:13]
	v_cndmask_b32_e64 v178, v163, v159, s[12:13]
	v_cndmask_b32_e64 v173, v156, v160, s[12:13]
	v_cndmask_b32_e64 v175, v157, v161, s[12:13]
	v_cndmask_b32_e64 v177, v158, v162, s[12:13]
	v_cndmask_b32_e64 v179, v159, v163, s[12:13]
	v_add_f32_dpp v156, v172, v173 row_half_mirror row_mask:0xf bank_mask:0xf
	v_add_f32_dpp v157, v174, v175 row_half_mirror row_mask:0xf bank_mask:0xf
	v_add_f32_dpp v158, v176, v177 row_half_mirror row_mask:0xf bank_mask:0xf
	v_add_f32_dpp v159, v178, v179 row_half_mirror row_mask:0xf bank_mask:0xf
	v_cndmask_b32_e64 v172, v158, v156, s[14:15]
	v_cndmask_b32_e64 v174, v159, v157, s[14:15]
	v_cndmask_b32_e64 v173, v156, v158, s[14:15]
	v_cndmask_b32_e64 v175, v157, v159, s[14:15]
	v_add_f32_dpp v156, v172, v173 quad_perm:[2,3,0,1] row_mask:0xf bank_mask:0xf
	v_add_f32_dpp v157, v174, v175 quad_perm:[2,3,0,1] row_mask:0xf bank_mask:0xf
	v_cndmask_b32_e64 v172, v157, v156, s[16:17]
	v_cndmask_b32_e64 v173, v156, v157, s[16:17]
	s_nop 0
	v_add_f32_dpp v156, v172, v173 quad_perm:[1,0,3,2] row_mask:0xf bank_mask:0xf
	v_mov_b32_e32 v180, v156
	v_pk_mul_f32 v[150:151], v[146:147], v[126:127]
	v_pk_fma_f32 v[150:151], v[148:149], v[134:135], v[150:151]
	v_pk_mul_f32 v[152:153], v[146:147], v[232:233]
	v_add_f32_e32 v154, v150, v151
	v_pk_fma_f32 v[152:153], v[148:149], v[234:235], v[152:153]
	v_pk_mul_f32 v[142:143], v[146:147], v[128:129]
	v_add_f32_dpp v154, v154, v154 quad_perm:[1,0,3,2] row_mask:0xf bank_mask:0xf bound_ctrl:1
	v_pk_mul_f32 v[144:145], v[148:149], v[136:137]
	v_add_f32_e32 v156, v152, v153
	v_add_f32_dpp v154, v154, v154 quad_perm:[2,3,0,1] row_mask:0xf bank_mask:0xf bound_ctrl:1
	v_pk_fma_f32 v[142:143], v[242:243], v[132:133], v[142:143] op_sel:[0,0,0] op_sel_hi:[0,1,1]
	v_pk_fma_f32 v[144:145], v[242:243], v[224:225], v[144:145] op_sel:[0,0,0] op_sel_hi:[0,1,1]
	v_add_f32_dpp v154, v154, v154 row_half_mirror row_mask:0xf bank_mask:0xf bound_ctrl:1
	ds_read_b128 v[206:209], v184 offset:12288
	ds_read_b128 v[210:213], v184 offset:12304
	v_add_f32_dpp v154, v154, v154 row_mirror row_mask:0xf bank_mask:0xf bound_ctrl:1
	ds_read_b64 v[232:233], v184 offset:12320
	ds_read_b128 v[214:217], v185 offset:12288
	v_pk_fma_f32 v[142:143], v[154:155], v[130:131], v[142:143] op_sel_hi:[0,1,1]
	v_pk_fma_f32 v[144:145], v[154:155], v[222:223], v[144:145] op_sel_hi:[0,1,1]
	ds_read_b128 v[218:221], v185 offset:12304
	ds_read_b64 v[234:235], v185 offset:12320
	ds_read_b32 v241, v186 offset:3264
	s_waitcnt lgkmcnt(7)
; __device__ __forceinline__ void wkv_phase(const WkvT& W, unsigned char* lds) {
;     ...
;                 for (int t = 0; t < 32; ++t) {
;                     const f32x2 a2 = {nA[0], nA[1]}, w2 = {nA[2], nA[3]}, b2 = {nB[0], nB[1]}, k2 = {nB[2], nB[3]}, r2 = nr; const float v = nv;
;                     if (t + 1 < 32) { nA = *(const f32x4*)(pp + (t + 1) * 384); nB = *(const f32x4*)(pp + (t + 1) * 384 + 4); nr = *(const f32x2*)(pp + (t + 1) * 384 + 8); nv = pv[(t + 1) * 16]; }
;                     float S0 = S.x, S1 = S.y;
;                     float d = S0 * a2.x; d = __builtin_fmaf(S1, a2.y, d);
;                     float t0 = S0 * w2.x; t0 = __builtin_fmaf(v, k2.x, t0); asm volatile("" : "+v"(t0));
;                     float t1 = S1 * w2.y; t1 = __builtin_fmaf(v, k2.y, t1); asm volatile("" : "+v"(t1));
;                     float yprev; const float sa = wkv_reduce(d, ep, yprev);
;                     S0 = __builtin_fmaf(sa, b2.x, t0); asm volatile("" : "+v"(S0));
;                     S1 = __builtin_fmaf(sa, b2.y, t1); asm volatile("" : "+v"(S1));
;                     ep = S0 * r2.x; ep = __builtin_fmaf(S1, r2.y, ep);
;                     S.x = S0; S.y = S1;
	v_pk_mul_f32 v[150:151], v[142:143], v[190:191]
	v_pk_fma_f32 v[150:151], v[144:145], v[198:199], v[150:151]
	v_pk_mul_f32 v[152:153], v[142:143], v[236:237]
	v_add_f32_e32 v154, v150, v151
	v_pk_fma_f32 v[152:153], v[144:145], v[238:239], v[152:153]
	v_pk_mul_f32 v[146:147], v[142:143], v[192:193]
	v_add_f32_dpp v154, v154, v154 quad_perm:[1,0,3,2] row_mask:0xf bank_mask:0xf bound_ctrl:1
	v_pk_mul_f32 v[148:149], v[144:145], v[200:201]
	v_add_f32_e32 v157, v152, v153
	v_add_f32_dpp v154, v154, v154 quad_perm:[2,3,0,1] row_mask:0xf bank_mask:0xf bound_ctrl:1
	v_pk_fma_f32 v[146:147], v[240:241], v[196:197], v[146:147] op_sel:[0,0,0] op_sel_hi:[0,1,1]
	v_pk_fma_f32 v[148:149], v[240:241], v[204:205], v[148:149] op_sel:[0,0,0] op_sel_hi:[0,1,1]
	v_add_f32_dpp v154, v154, v154 row_half_mirror row_mask:0xf bank_mask:0xf bound_ctrl:1
	ds_read_b128 v[126:129], v184 offset:13824
	ds_read_b128 v[130:133], v184 offset:13840
	v_add_f32_dpp v154, v154, v154 row_mirror row_mask:0xf bank_mask:0xf bound_ctrl:1
	ds_read_b64 v[236:237], v184 offset:13856
	ds_read_b128 v[134:137], v185 offset:13824
	v_pk_fma_f32 v[146:147], v[154:155], v[194:195], v[146:147] op_sel_hi:[0,1,1]
	v_pk_fma_f32 v[148:149], v[154:155], v[202:203], v[148:149] op_sel_hi:[0,1,1]
	ds_read_b128 v[222:225], v185 offset:13840
	ds_read_b64 v[238:239], v185 offset:13856
	ds_read_b32 v242, v186 offset:3328
	s_waitcnt lgkmcnt(7)
	v_pk_mul_f32 v[150:151], v[146:147], v[206:207]
	v_pk_fma_f32 v[150:151], v[148:149], v[214:215], v[150:151]
	v_pk_mul_f32 v[152:153], v[146:147], v[228:229]
	v_add_f32_e32 v154, v150, v151
	v_pk_fma_f32 v[152:153], v[148:149], v[230:231], v[152:153]
	v_pk_mul_f32 v[142:143], v[146:147], v[208:209]
	v_add_f32_dpp v154, v154, v154 quad_perm:[1,0,3,2] row_mask:0xf bank_mask:0xf bound_ctrl:1
	v_pk_mul_f32 v[144:145], v[148:149], v[216:217]
	v_add_f32_e32 v158, v152, v153
	v_add_f32_dpp v154, v154, v154 quad_perm:[2,3,0,1] row_mask:0xf bank_mask:0xf bound_ctrl:1
	v_pk_fma_f32 v[142:143], v[240:241], v[212:213], v[142:143] op_sel:[1,0,0] op_sel_hi:[1,1,1]
	v_pk_fma_f32 v[144:145], v[240:241], v[220:221], v[144:145] op_sel:[1,0,0] op_sel_hi:[1,1,1]
	v_add_f32_dpp v154, v154, v154 row_half_mirror row_mask:0xf bank_mask:0xf bound_ctrl:1
	ds_read_b128 v[190:193], v184 offset:15360
	ds_read_b128 v[194:197], v184 offset:15376
	v_add_f32_dpp v154, v154, v154 row_mirror row_mask:0xf bank_mask:0xf bound_ctrl:1
	ds_read_b64 v[228:229], v184 offset:15392
	ds_read_b128 v[198:201], v185 offset:15360
	v_pk_fma_f32 v[142:143], v[154:155], v[210:211], v[142:143] op_sel_hi:[0,1,1]
	v_pk_fma_f32 v[144:145], v[154:155], v[218:219], v[144:145] op_sel_hi:[0,1,1]
	ds_read_b128 v[202:205], v185 offset:15376
	ds_read_b64 v[230:231], v185 offset:15392
	ds_read_b32 v240, v186 offset:3392
	s_waitcnt lgkmcnt(7)
	v_pk_mul_f32 v[150:151], v[142:143], v[126:127]
	v_pk_fma_f32 v[150:151], v[144:145], v[134:135], v[150:151]
	v_pk_mul_f32 v[152:153], v[142:143], v[232:233]
	v_add_f32_e32 v154, v150, v151
	v_pk_fma_f32 v[152:153], v[144:145], v[234:235], v[152:153]
	v_pk_mul_f32 v[146:147], v[142:143], v[128:129]
	v_add_f32_dpp v154, v154, v154 quad_perm:[1,0,3,2] row_mask:0xf bank_mask:0xf bound_ctrl:1
	v_pk_mul_f32 v[148:149], v[144:145], v[136:137]
	v_add_f32_e32 v159, v152, v153
	v_add_f32_dpp v154, v154, v154 quad_perm:[2,3,0,1] row_mask:0xf bank_mask:0xf bound_ctrl:1
	v_pk_fma_f32 v[146:147], v[242:243], v[132:133], v[146:147] op_sel:[0,0,0] op_sel_hi:[0,1,1]
	v_pk_fma_f32 v[148:149], v[242:243], v[224:225], v[148:149] op_sel:[0,0,0] op_sel_hi:[0,1,1]
	v_add_f32_dpp v154, v154, v154 row_half_mirror row_mask:0xf bank_mask:0xf bound_ctrl:1
	ds_read_b128 v[206:209], v184 offset:16896
	ds_read_b128 v[210:213], v184 offset:16912
	v_add_f32_dpp v154, v154, v154 row_mirror row_mask:0xf bank_mask:0xf bound_ctrl:1
	ds_read_b64 v[232:233], v184 offset:16928
	ds_read_b128 v[214:217], v185 offset:16896
	v_pk_fma_f32 v[146:147], v[154:155], v[130:131], v[146:147] op_sel_hi:[0,1,1]
	v_pk_fma_f32 v[148:149], v[154:155], v[222:223], v[148:149] op_sel_hi:[0,1,1]
	ds_read_b128 v[218:221], v185 offset:16912
	ds_read_b64 v[234:235], v185 offset:16928
	ds_read_b32 v241, v186 offset:3456
	s_waitcnt lgkmcnt(7)
	v_pk_mul_f32 v[150:151], v[146:147], v[190:191]
	v_pk_fma_f32 v[150:151], v[148:149], v[198:199], v[150:151]
	v_pk_mul_f32 v[152:153], v[146:147], v[236:237]
	v_add_f32_e32 v154, v150, v151
	v_pk_fma_f32 v[152:153], v[148:149], v[238:239], v[152:153]
	v_pk_mul_f32 v[142:143], v[146:147], v[192:193]
	v_add_f32_dpp v154, v154, v154 quad_perm:[1,0,3,2] row_mask:0xf bank_mask:0xf bound_ctrl:1
	v_pk_mul_f32 v[144:145], v[148:149], v[200:201]
	v_add_f32_e32 v160, v152, v153
	v_add_f32_dpp v154, v154, v154 quad_perm:[2,3,0,1] row_mask:0xf bank_mask:0xf bound_ctrl:1
	v_pk_fma_f32 v[142:143], v[240:241], v[196:197], v[142:143] op_sel:[0,0,0] op_sel_hi:[0,1,1]
	v_pk_fma_f32 v[144:145], v[240:241], v[204:205], v[144:145] op_sel:[0,0,0] op_sel_hi:[0,1,1]
	v_add_f32_dpp v154, v154, v154 row_half_mirror row_mask:0xf bank_mask:0xf bound_ctrl:1
	ds_read_b128 v[126:129], v184 offset:18432
	ds_read_b128 v[130:133], v184 offset:18448
	v_add_f32_dpp v154, v154, v154 row_mirror row_mask:0xf bank_mask:0xf bound_ctrl:1
	ds_read_b64 v[236:237], v184 offset:18464
	ds_read_b128 v[134:137], v185 offset:18432
	v_pk_fma_f32 v[142:143], v[154:155], v[194:195], v[142:143] op_sel_hi:[0,1,1]
	v_pk_fma_f32 v[144:145], v[154:155], v[202:203], v[144:145] op_sel_hi:[0,1,1]
	ds_read_b128 v[222:225], v185 offset:18448
	ds_read_b64 v[238:239], v185 offset:18464
	ds_read_b32 v242, v186 offset:3520
	s_waitcnt lgkmcnt(7)
; __device__ __forceinline__ void wkv_phase(const WkvT& W, unsigned char* lds) {
;     ...
;                 for (int t = 0; t < 32; ++t) {
;                     const f32x2 a2 = {nA[0], nA[1]}, w2 = {nA[2], nA[3]}, b2 = {nB[0], nB[1]}, k2 = {nB[2], nB[3]}, r2 = nr; const float v = nv;
;                     if (t + 1 < 32) { nA = *(const f32x4*)(pp + (t + 1) * 384); nB = *(const f32x4*)(pp + (t + 1) * 384 + 4); nr = *(const f32x2*)(pp + (t + 1) * 384 + 8); nv = pv[(t + 1) * 16]; }
;                     float S0 = S.x, S1 = S.y;
;                     float d = S0 * a2.x; d = __builtin_fmaf(S1, a2.y, d);
;                     float t0 = S0 * w2.x; t0 = __builtin_fmaf(v, k2.x, t0); asm volatile("" : "+v"(t0));
;                     float t1 = S1 * w2.y; t1 = __builtin_fmaf(v, k2.y, t1); asm volatile("" : "+v"(t1));
;                     float yprev; const float sa = wkv_reduce(d, ep, yprev);
;                     S0 = __builtin_fmaf(sa, b2.x, t0); asm volatile("" : "+v"(S0));
;                     S1 = __builtin_fmaf(sa, b2.y, t1); asm volatile("" : "+v"(S1));
;                     ep = S0 * r2.x; ep = __builtin_fmaf(S1, r2.y, ep);
;                     S.x = S0; S.y = S1;
	v_pk_mul_f32 v[150:151], v[142:143], v[206:207]
	v_pk_fma_f32 v[150:151], v[144:145], v[214:215], v[150:151]
	v_pk_mul_f32 v[152:153], v[142:143], v[228:229]
	v_add_f32_e32 v154, v150, v151
	v_pk_fma_f32 v[152:153], v[144:145], v[230:231], v[152:153]
	v_pk_mul_f32 v[146:147], v[142:143], v[208:209]
	v_add_f32_dpp v154, v154, v154 quad_perm:[1,0,3,2] row_mask:0xf bank_mask:0xf bound_ctrl:1
	v_pk_mul_f32 v[148:149], v[144:145], v[216:217]
	v_add_f32_e32 v161, v152, v153
	v_add_f32_dpp v154, v154, v154 quad_perm:[2,3,0,1] row_mask:0xf bank_mask:0xf bound_ctrl:1
	v_pk_fma_f32 v[146:147], v[240:241], v[212:213], v[146:147] op_sel:[1,0,0] op_sel_hi:[1,1,1]
	v_pk_fma_f32 v[148:149], v[240:241], v[220:221], v[148:149] op_sel:[1,0,0] op_sel_hi:[1,1,1]
	v_add_f32_dpp v154, v154, v154 row_half_mirror row_mask:0xf bank_mask:0xf bound_ctrl:1
	ds_read_b128 v[190:193], v184 offset:19968
	ds_read_b128 v[194:197], v184 offset:19984
	v_add_f32_dpp v154, v154, v154 row_mirror row_mask:0xf bank_mask:0xf bound_ctrl:1
	ds_read_b64 v[228:229], v184 offset:20000
	ds_read_b128 v[198:201], v185 offset:19968
	v_pk_fma_f32 v[146:147], v[154:155], v[210:211], v[146:147] op_sel_hi:[0,1,1]
	v_pk_fma_f32 v[148:149], v[154:155], v[218:219], v[148:149] op_sel_hi:[0,1,1]
	ds_read_b128 v[202:205], v185 offset:19984
	ds_read_b64 v[230:231], v185 offset:20000
	ds_read_b32 v240, v186 offset:3584
	s_waitcnt lgkmcnt(7)
	v_pk_mul_f32 v[150:151], v[146:147], v[126:127]
	v_pk_fma_f32 v[150:151], v[148:149], v[134:135], v[150:151]
	v_pk_mul_f32 v[152:153], v[146:147], v[232:233]
	v_add_f32_e32 v154, v150, v151
	v_pk_fma_f32 v[152:153], v[148:149], v[234:235], v[152:153]
	v_pk_mul_f32 v[142:143], v[146:147], v[128:129]
	v_add_f32_dpp v154, v154, v154 quad_perm:[1,0,3,2] row_mask:0xf bank_mask:0xf bound_ctrl:1
	v_pk_mul_f32 v[144:145], v[148:149], v[136:137]
	v_add_f32_e32 v162, v152, v153
	v_add_f32_dpp v154, v154, v154 quad_perm:[2,3,0,1] row_mask:0xf bank_mask:0xf bound_ctrl:1
	v_pk_fma_f32 v[142:143], v[242:243], v[132:133], v[142:143] op_sel:[0,0,0] op_sel_hi:[0,1,1]
	v_pk_fma_f32 v[144:145], v[242:243], v[224:225], v[144:145] op_sel:[0,0,0] op_sel_hi:[0,1,1]
	v_add_f32_dpp v154, v154, v154 row_half_mirror row_mask:0xf bank_mask:0xf bound_ctrl:1
	ds_read_b128 v[206:209], v184 offset:21504
	ds_read_b128 v[210:213], v184 offset:21520
	v_add_f32_dpp v154, v154, v154 row_mirror row_mask:0xf bank_mask:0xf bound_ctrl:1
	ds_read_b64 v[232:233], v184 offset:21536
	ds_read_b128 v[214:217], v185 offset:21504
	v_pk_fma_f32 v[142:143], v[154:155], v[130:131], v[142:143] op_sel_hi:[0,1,1]
	v_pk_fma_f32 v[144:145], v[154:155], v[222:223], v[144:145] op_sel_hi:[0,1,1]
	ds_read_b128 v[218:221], v185 offset:21520
	ds_read_b64 v[234:235], v185 offset:21536
	ds_read_b32 v241, v186 offset:3648
	s_waitcnt lgkmcnt(7)
	v_pk_mul_f32 v[150:151], v[142:143], v[190:191]
	v_pk_fma_f32 v[150:151], v[144:145], v[198:199], v[150:151]
	v_pk_mul_f32 v[152:153], v[142:143], v[236:237]
	v_add_f32_e32 v154, v150, v151
	v_pk_fma_f32 v[152:153], v[144:145], v[238:239], v[152:153]
	v_pk_mul_f32 v[146:147], v[142:143], v[192:193]
	v_add_f32_dpp v154, v154, v154 quad_perm:[1,0,3,2] row_mask:0xf bank_mask:0xf bound_ctrl:1
	v_pk_mul_f32 v[148:149], v[144:145], v[200:201]
	v_add_f32_e32 v163, v152, v153
	v_add_f32_dpp v154, v154, v154 quad_perm:[2,3,0,1] row_mask:0xf bank_mask:0xf bound_ctrl:1
	v_pk_fma_f32 v[146:147], v[240:241], v[196:197], v[146:147] op_sel:[0,0,0] op_sel_hi:[0,1,1]
	v_pk_fma_f32 v[148:149], v[240:241], v[204:205], v[148:149] op_sel:[0,0,0] op_sel_hi:[0,1,1]
	v_add_f32_dpp v154, v154, v154 row_half_mirror row_mask:0xf bank_mask:0xf bound_ctrl:1
	ds_read_b128 v[126:129], v184 offset:23040
	ds_read_b128 v[130:133], v184 offset:23056
	v_add_f32_dpp v154, v154, v154 row_mirror row_mask:0xf bank_mask:0xf bound_ctrl:1
	ds_read_b64 v[236:237], v184 offset:23072
	ds_read_b128 v[134:137], v185 offset:23040
	v_pk_fma_f32 v[146:147], v[154:155], v[194:195], v[146:147] op_sel_hi:[0,1,1]
	v_pk_fma_f32 v[148:149], v[154:155], v[202:203], v[148:149] op_sel_hi:[0,1,1]
	ds_read_b128 v[222:225], v185 offset:23056
	ds_read_b64 v[238:239], v185 offset:23072
	ds_read_b32 v242, v186 offset:3712
	s_waitcnt lgkmcnt(7)
	v_pk_mul_f32 v[150:151], v[146:147], v[206:207]
	v_pk_fma_f32 v[150:151], v[148:149], v[214:215], v[150:151]
	v_pk_mul_f32 v[152:153], v[146:147], v[228:229]
	v_add_f32_e32 v154, v150, v151
	v_pk_fma_f32 v[152:153], v[148:149], v[230:231], v[152:153]
	v_pk_mul_f32 v[142:143], v[146:147], v[208:209]
	v_add_f32_dpp v154, v154, v154 quad_perm:[1,0,3,2] row_mask:0xf bank_mask:0xf bound_ctrl:1
	v_pk_mul_f32 v[144:145], v[148:149], v[216:217]
	v_add_f32_e32 v164, v152, v153
	v_add_f32_dpp v154, v154, v154 quad_perm:[2,3,0,1] row_mask:0xf bank_mask:0xf bound_ctrl:1
	v_pk_fma_f32 v[142:143], v[240:241], v[212:213], v[142:143] op_sel:[1,0,0] op_sel_hi:[1,1,1]
	v_pk_fma_f32 v[144:145], v[240:241], v[220:221], v[144:145] op_sel:[1,0,0] op_sel_hi:[1,1,1]
	v_add_f32_dpp v154, v154, v154 row_half_mirror row_mask:0xf bank_mask:0xf bound_ctrl:1
	ds_read_b128 v[190:193], v184 offset:24576
	ds_read_b128 v[194:197], v184 offset:24592
	v_add_f32_dpp v154, v154, v154 row_mirror row_mask:0xf bank_mask:0xf bound_ctrl:1
	ds_read_b64 v[228:229], v184 offset:24608
	ds_read_b128 v[198:201], v185 offset:24576
	v_pk_fma_f32 v[142:143], v[154:155], v[210:211], v[142:143] op_sel_hi:[0,1,1]
	v_pk_fma_f32 v[144:145], v[154:155], v[218:219], v[144:145] op_sel_hi:[0,1,1]
	ds_read_b128 v[202:205], v185 offset:24592
	ds_read_b64 v[230:231], v185 offset:24608
	ds_read_b32 v240, v186 offset:3776
	s_waitcnt lgkmcnt(7)
; __device__ __forceinline__ void wkv_phase(const WkvT& W, unsigned char* lds) {
;     ...
;                 for (int t = 0; t < 32; ++t) {
;                     const f32x2 a2 = {nA[0], nA[1]}, w2 = {nA[2], nA[3]}, b2 = {nB[0], nB[1]}, k2 = {nB[2], nB[3]}, r2 = nr; const float v = nv;
;                     if (t + 1 < 32) { nA = *(const f32x4*)(pp + (t + 1) * 384); nB = *(const f32x4*)(pp + (t + 1) * 384 + 4); nr = *(const f32x2*)(pp + (t + 1) * 384 + 8); nv = pv[(t + 1) * 16]; }
;                     float S0 = S.x, S1 = S.y;
;                     float d = S0 * a2.x; d = __builtin_fmaf(S1, a2.y, d);
;                     float t0 = S0 * w2.x; t0 = __builtin_fmaf(v, k2.x, t0); asm volatile("" : "+v"(t0));
;                     float t1 = S1 * w2.y; t1 = __builtin_fmaf(v, k2.y, t1); asm volatile("" : "+v"(t1));
;                     float yprev; const float sa = wkv_reduce(d, ep, yprev);
;                     S0 = __builtin_fmaf(sa, b2.x, t0); asm volatile("" : "+v"(S0));
;                     S1 = __builtin_fmaf(sa, b2.y, t1); asm volatile("" : "+v"(S1));
;                     ep = S0 * r2.x; ep = __builtin_fmaf(S1, r2.y, ep);
;                     S.x = S0; S.y = S1;
	v_pk_mul_f32 v[150:151], v[142:143], v[126:127]
	v_pk_fma_f32 v[150:151], v[144:145], v[134:135], v[150:151]
	v_pk_mul_f32 v[152:153], v[142:143], v[232:233]
	v_add_f32_e32 v154, v150, v151
	v_pk_fma_f32 v[152:153], v[144:145], v[234:235], v[152:153]
	v_pk_mul_f32 v[146:147], v[142:143], v[128:129]
	v_add_f32_dpp v154, v154, v154 quad_perm:[1,0,3,2] row_mask:0xf bank_mask:0xf bound_ctrl:1
	v_pk_mul_f32 v[148:149], v[144:145], v[136:137]
	v_add_f32_e32 v165, v152, v153
	v_add_f32_dpp v154, v154, v154 quad_perm:[2,3,0,1] row_mask:0xf bank_mask:0xf bound_ctrl:1
	v_pk_fma_f32 v[146:147], v[242:243], v[132:133], v[146:147] op_sel:[0,0,0] op_sel_hi:[0,1,1]
	v_pk_fma_f32 v[148:149], v[242:243], v[224:225], v[148:149] op_sel:[0,0,0] op_sel_hi:[0,1,1]
	v_add_f32_dpp v154, v154, v154 row_half_mirror row_mask:0xf bank_mask:0xf bound_ctrl:1
	ds_read_b128 v[206:209], v184 offset:26112
	ds_read_b128 v[210:213], v184 offset:26128
	v_add_f32_dpp v154, v154, v154 row_mirror row_mask:0xf bank_mask:0xf bound_ctrl:1
	ds_read_b64 v[232:233], v184 offset:26144
	ds_read_b128 v[214:217], v185 offset:26112
	v_pk_fma_f32 v[146:147], v[154:155], v[130:131], v[146:147] op_sel_hi:[0,1,1]
	v_pk_fma_f32 v[148:149], v[154:155], v[222:223], v[148:149] op_sel_hi:[0,1,1]
	ds_read_b128 v[218:221], v185 offset:26128
	ds_read_b64 v[234:235], v185 offset:26144
	ds_read_b32 v241, v186 offset:3840
	s_waitcnt lgkmcnt(7)
	v_pk_mul_f32 v[150:151], v[146:147], v[190:191]
	v_pk_fma_f32 v[150:151], v[148:149], v[198:199], v[150:151]
	v_pk_mul_f32 v[152:153], v[146:147], v[236:237]
	v_add_f32_e32 v154, v150, v151
	v_pk_fma_f32 v[152:153], v[148:149], v[238:239], v[152:153]
	v_pk_mul_f32 v[142:143], v[146:147], v[192:193]
	v_add_f32_dpp v154, v154, v154 quad_perm:[1,0,3,2] row_mask:0xf bank_mask:0xf bound_ctrl:1
	v_pk_mul_f32 v[144:145], v[148:149], v[200:201]
	v_add_f32_e32 v166, v152, v153
	v_add_f32_dpp v154, v154, v154 quad_perm:[2,3,0,1] row_mask:0xf bank_mask:0xf bound_ctrl:1
	v_pk_fma_f32 v[142:143], v[240:241], v[196:197], v[142:143] op_sel:[0,0,0] op_sel_hi:[0,1,1]
	v_pk_fma_f32 v[144:145], v[240:241], v[204:205], v[144:145] op_sel:[0,0,0] op_sel_hi:[0,1,1]
	v_add_f32_dpp v154, v154, v154 row_half_mirror row_mask:0xf bank_mask:0xf bound_ctrl:1
	ds_read_b128 v[126:129], v184 offset:27648
	ds_read_b128 v[130:133], v184 offset:27664
	v_add_f32_dpp v154, v154, v154 row_mirror row_mask:0xf bank_mask:0xf bound_ctrl:1
	ds_read_b64 v[236:237], v184 offset:27680
	ds_read_b128 v[134:137], v185 offset:27648
	v_pk_fma_f32 v[142:143], v[154:155], v[194:195], v[142:143] op_sel_hi:[0,1,1]
	v_pk_fma_f32 v[144:145], v[154:155], v[202:203], v[144:145] op_sel_hi:[0,1,1]
	ds_read_b128 v[222:225], v185 offset:27664
	ds_read_b64 v[238:239], v185 offset:27680
	ds_read_b32 v242, v186 offset:3904
	s_waitcnt lgkmcnt(7)
	v_pk_mul_f32 v[150:151], v[142:143], v[206:207]
	v_pk_fma_f32 v[150:151], v[144:145], v[214:215], v[150:151]
	v_pk_mul_f32 v[152:153], v[142:143], v[228:229]
	v_add_f32_e32 v154, v150, v151
	v_pk_fma_f32 v[152:153], v[144:145], v[230:231], v[152:153]
	v_pk_mul_f32 v[146:147], v[142:143], v[208:209]
	v_add_f32_dpp v154, v154, v154 quad_perm:[1,0,3,2] row_mask:0xf bank_mask:0xf bound_ctrl:1
	v_pk_mul_f32 v[148:149], v[144:145], v[216:217]
	v_add_f32_e32 v167, v152, v153
	v_add_f32_dpp v154, v154, v154 quad_perm:[2,3,0,1] row_mask:0xf bank_mask:0xf bound_ctrl:1
	v_pk_fma_f32 v[146:147], v[240:241], v[212:213], v[146:147] op_sel:[1,0,0] op_sel_hi:[1,1,1]
	v_pk_fma_f32 v[148:149], v[240:241], v[220:221], v[148:149] op_sel:[1,0,0] op_sel_hi:[1,1,1]
	v_add_f32_dpp v154, v154, v154 row_half_mirror row_mask:0xf bank_mask:0xf bound_ctrl:1
	ds_read_b128 v[190:193], v184 offset:29184
	ds_read_b128 v[194:197], v184 offset:29200
	v_add_f32_dpp v154, v154, v154 row_mirror row_mask:0xf bank_mask:0xf bound_ctrl:1
	ds_read_b64 v[228:229], v184 offset:29216
	ds_read_b128 v[198:201], v185 offset:29184
	v_pk_fma_f32 v[146:147], v[154:155], v[210:211], v[146:147] op_sel_hi:[0,1,1]
	v_pk_fma_f32 v[148:149], v[154:155], v[218:219], v[148:149] op_sel_hi:[0,1,1]
	ds_read_b128 v[202:205], v185 offset:29200
	ds_read_b64 v[230:231], v185 offset:29216
	ds_read_b32 v240, v186 offset:3968
	s_waitcnt lgkmcnt(7)
	v_pk_mul_f32 v[150:151], v[146:147], v[126:127]
	v_pk_fma_f32 v[150:151], v[148:149], v[134:135], v[150:151]
	v_pk_mul_f32 v[152:153], v[146:147], v[232:233]
	v_add_f32_e32 v154, v150, v151
	v_pk_fma_f32 v[152:153], v[148:149], v[234:235], v[152:153]
	v_pk_mul_f32 v[142:143], v[146:147], v[128:129]
	v_add_f32_dpp v154, v154, v154 quad_perm:[1,0,3,2] row_mask:0xf bank_mask:0xf bound_ctrl:1
	v_pk_mul_f32 v[144:145], v[148:149], v[136:137]
	v_add_f32_e32 v168, v152, v153
	v_add_f32_dpp v154, v154, v154 quad_perm:[2,3,0,1] row_mask:0xf bank_mask:0xf bound_ctrl:1
	v_pk_fma_f32 v[142:143], v[242:243], v[132:133], v[142:143] op_sel:[0,0,0] op_sel_hi:[0,1,1]
	v_pk_fma_f32 v[144:145], v[242:243], v[224:225], v[144:145] op_sel:[0,0,0] op_sel_hi:[0,1,1]
	v_add_f32_dpp v154, v154, v154 row_half_mirror row_mask:0xf bank_mask:0xf bound_ctrl:1
	ds_read_b128 v[206:209], v184 offset:30720
	ds_read_b128 v[210:213], v184 offset:30736
	v_add_f32_dpp v154, v154, v154 row_mirror row_mask:0xf bank_mask:0xf bound_ctrl:1
	ds_read_b64 v[232:233], v184 offset:30752
	ds_read_b128 v[214:217], v185 offset:30720
	v_pk_fma_f32 v[142:143], v[154:155], v[130:131], v[142:143] op_sel_hi:[0,1,1]
	v_pk_fma_f32 v[144:145], v[154:155], v[222:223], v[144:145] op_sel_hi:[0,1,1]
	ds_read_b128 v[218:221], v185 offset:30736
	ds_read_b64 v[234:235], v185 offset:30752
	ds_read_b32 v241, v186 offset:4032
	s_waitcnt lgkmcnt(7)
; __device__ __forceinline__ void wkv_phase(const WkvT& W, unsigned char* lds) {
;     ...
;                 for (int t = 0; t < 32; ++t) {
;                     const f32x2 a2 = {nA[0], nA[1]}, w2 = {nA[2], nA[3]}, b2 = {nB[0], nB[1]}, k2 = {nB[2], nB[3]}, r2 = nr; const float v = nv;
;                     if (t + 1 < 32) { nA = *(const f32x4*)(pp + (t + 1) * 384); nB = *(const f32x4*)(pp + (t + 1) * 384 + 4); nr = *(const f32x2*)(pp + (t + 1) * 384 + 8); nv = pv[(t + 1) * 16]; }
;                     float S0 = S.x, S1 = S.y;
;                     float d = S0 * a2.x; d = __builtin_fmaf(S1, a2.y, d);
;                     float t0 = S0 * w2.x; t0 = __builtin_fmaf(v, k2.x, t0); asm volatile("" : "+v"(t0));
;                     float t1 = S1 * w2.y; t1 = __builtin_fmaf(v, k2.y, t1); asm volatile("" : "+v"(t1));
;                     float yprev; const float sa = wkv_reduce(d, ep, yprev);
;                     S0 = __builtin_fmaf(sa, b2.x, t0); asm volatile("" : "+v"(S0));
;                     S1 = __builtin_fmaf(sa, b2.y, t1); asm volatile("" : "+v"(S1));
;                     ep = S0 * r2.x; ep = __builtin_fmaf(S1, r2.y, ep);
;                     S.x = S0; S.y = S1;
;                     if (t >= 1) { const bool hit = oddrow && ((lane & 15) == ((t - 1) & 15)); if (t <= 16) yk0 = hit ? yprev : yk0; else yk1 = hit ? yprev : yk1; }
;                 }
;                 { float ylast; (void)wkv_reduce(0.f, ep, ylast); yk1 = (oddrow && (lane & 15) == 15) ? ylast : yk1; }
;                 if (oddrow) { sY[bi * 512 + (lane & 15) * 16 + il] = yk0; sY[bi * 512 + (16 + (lane & 15)) * 16 + il] = yk1; }
	v_pk_mul_f32 v[150:151], v[142:143], v[190:191]
	v_pk_fma_f32 v[150:151], v[144:145], v[198:199], v[150:151]
	v_pk_mul_f32 v[152:153], v[142:143], v[236:237]
	v_add_f32_e32 v154, v150, v151
	v_pk_fma_f32 v[152:153], v[144:145], v[238:239], v[152:153]
	v_pk_mul_f32 v[146:147], v[142:143], v[192:193]
	v_add_f32_dpp v154, v154, v154 quad_perm:[1,0,3,2] row_mask:0xf bank_mask:0xf bound_ctrl:1
	v_pk_mul_f32 v[148:149], v[144:145], v[200:201]
	v_add_f32_e32 v169, v152, v153
	v_add_f32_dpp v154, v154, v154 quad_perm:[2,3,0,1] row_mask:0xf bank_mask:0xf bound_ctrl:1
	v_pk_fma_f32 v[146:147], v[240:241], v[196:197], v[146:147] op_sel:[0,0,0] op_sel_hi:[0,1,1]
	v_pk_fma_f32 v[148:149], v[240:241], v[204:205], v[148:149] op_sel:[0,0,0] op_sel_hi:[0,1,1]
	v_add_f32_dpp v154, v154, v154 row_half_mirror row_mask:0xf bank_mask:0xf bound_ctrl:1
	s_nop 1
	v_add_f32_dpp v154, v154, v154 row_mirror row_mask:0xf bank_mask:0xf bound_ctrl:1
	v_pk_fma_f32 v[146:147], v[154:155], v[194:195], v[146:147] op_sel_hi:[0,1,1]
	v_pk_fma_f32 v[148:149], v[154:155], v[202:203], v[148:149] op_sel_hi:[0,1,1]
	s_waitcnt lgkmcnt(0)
	v_pk_mul_f32 v[150:151], v[146:147], v[206:207]
	v_pk_fma_f32 v[150:151], v[148:149], v[214:215], v[150:151]
	v_pk_mul_f32 v[152:153], v[146:147], v[228:229]
	v_add_f32_e32 v154, v150, v151
	v_pk_fma_f32 v[152:153], v[148:149], v[230:231], v[152:153]
	v_pk_mul_f32 v[142:143], v[146:147], v[208:209]
	v_add_f32_dpp v154, v154, v154 quad_perm:[1,0,3,2] row_mask:0xf bank_mask:0xf bound_ctrl:1
	v_pk_mul_f32 v[144:145], v[148:149], v[216:217]
	v_add_f32_e32 v170, v152, v153
	v_add_f32_dpp v154, v154, v154 quad_perm:[2,3,0,1] row_mask:0xf bank_mask:0xf bound_ctrl:1
	v_pk_fma_f32 v[142:143], v[240:241], v[212:213], v[142:143] op_sel:[1,0,0] op_sel_hi:[1,1,1]
	v_pk_fma_f32 v[144:145], v[240:241], v[220:221], v[144:145] op_sel:[1,0,0] op_sel_hi:[1,1,1]
	v_add_f32_dpp v154, v154, v154 row_half_mirror row_mask:0xf bank_mask:0xf bound_ctrl:1
	s_nop 1
	v_add_f32_dpp v154, v154, v154 row_mirror row_mask:0xf bank_mask:0xf bound_ctrl:1
	v_pk_fma_f32 v[142:143], v[154:155], v[210:211], v[142:143] op_sel_hi:[0,1,1]
	v_pk_fma_f32 v[144:145], v[154:155], v[218:219], v[144:145] op_sel_hi:[0,1,1]
	v_pk_mul_f32 v[152:153], v[142:143], v[232:233]
	v_pk_fma_f32 v[152:153], v[144:145], v[234:235], v[152:153]
	s_nop 0
	v_add_f32_e32 v171, v152, v153
	v_cndmask_b32_e64 v172, v164, v156, s[10:11]
	v_cndmask_b32_e64 v174, v165, v157, s[10:11]
	v_cndmask_b32_e64 v176, v166, v158, s[10:11]
	v_cndmask_b32_e64 v178, v167, v159, s[10:11]
	v_cndmask_b32_e64 v173, v156, v164, s[10:11]
	v_cndmask_b32_e64 v175, v157, v165, s[10:11]
	v_cndmask_b32_e64 v177, v158, v166, s[10:11]
	v_cndmask_b32_e64 v179, v159, v167, s[10:11]
	v_add_f32_dpp v156, v172, v173 row_ror:8 row_mask:0xf bank_mask:0xf
	v_add_f32_dpp v157, v174, v175 row_ror:8 row_mask:0xf bank_mask:0xf
	v_add_f32_dpp v158, v176, v177 row_ror:8 row_mask:0xf bank_mask:0xf
	v_add_f32_dpp v159, v178, v179 row_ror:8 row_mask:0xf bank_mask:0xf
	v_cndmask_b32_e64 v172, v168, v160, s[10:11]
	v_cndmask_b32_e64 v174, v169, v161, s[10:11]
	v_cndmask_b32_e64 v176, v170, v162, s[10:11]
	v_cndmask_b32_e64 v178, v171, v163, s[10:11]
	v_cndmask_b32_e64 v173, v160, v168, s[10:11]
	v_cndmask_b32_e64 v175, v161, v169, s[10:11]
	v_cndmask_b32_e64 v177, v162, v170, s[10:11]
	v_cndmask_b32_e64 v179, v163, v171, s[10:11]
	v_add_f32_dpp v160, v172, v173 row_ror:8 row_mask:0xf bank_mask:0xf
	v_add_f32_dpp v161, v174, v175 row_ror:8 row_mask:0xf bank_mask:0xf
	v_add_f32_dpp v162, v176, v177 row_ror:8 row_mask:0xf bank_mask:0xf
	v_add_f32_dpp v163, v178, v179 row_ror:8 row_mask:0xf bank_mask:0xf
	v_cndmask_b32_e64 v172, v160, v156, s[12:13]
	v_cndmask_b32_e64 v174, v161, v157, s[12:13]
	v_cndmask_b32_e64 v176, v162, v158, s[12:13]
	v_cndmask_b32_e64 v178, v163, v159, s[12:13]
	v_cndmask_b32_e64 v173, v156, v160, s[12:13]
	v_cndmask_b32_e64 v175, v157, v161, s[12:13]
	v_cndmask_b32_e64 v177, v158, v162, s[12:13]
	v_cndmask_b32_e64 v179, v159, v163, s[12:13]
	v_add_f32_dpp v156, v172, v173 row_half_mirror row_mask:0xf bank_mask:0xf
	v_add_f32_dpp v157, v174, v175 row_half_mirror row_mask:0xf bank_mask:0xf
	v_add_f32_dpp v158, v176, v177 row_half_mirror row_mask:0xf bank_mask:0xf
	v_add_f32_dpp v159, v178, v179 row_half_mirror row_mask:0xf bank_mask:0xf
	v_cndmask_b32_e64 v172, v158, v156, s[14:15]
	v_cndmask_b32_e64 v174, v159, v157, s[14:15]
	v_cndmask_b32_e64 v173, v156, v158, s[14:15]
	v_cndmask_b32_e64 v175, v157, v159, s[14:15]
	v_add_f32_dpp v156, v172, v173 quad_perm:[2,3,0,1] row_mask:0xf bank_mask:0xf
	v_add_f32_dpp v157, v174, v175 quad_perm:[2,3,0,1] row_mask:0xf bank_mask:0xf
	v_cndmask_b32_e64 v172, v157, v156, s[16:17]
	v_cndmask_b32_e64 v173, v156, v157, s[16:17]
	s_nop 0
	v_add_f32_dpp v156, v172, v173 quad_perm:[1,0,3,2] row_mask:0xf bank_mask:0xf
	v_mov_b32_e32 v181, v156
	ds_write2st64_b32 v187, v180, v181 offset0:8 offset1:12
.Lwkv4_b2_skip:
	s_mov_b64 s[96:97], exec

; __global__ void __launch_bounds__(512, 2) mega_fwd(Params p, int ph_lo, int ph_hi) {
;     extern __shared__ __attribute__((aligned(16))) unsigned char lds[];
	.amdhsa_kernel _Z8mega_fwd6Paramsii
		.amdhsa_group_segment_fixed_size 0
		.amdhsa_private_segment_fixed_size 0
		.amdhsa_kernarg_size 568
		.amdhsa_user_sgpr_count 2
		.amdhsa_user_sgpr_dispatch_ptr 0
		.amdhsa_user_sgpr_queue_ptr 0
		.amdhsa_user_sgpr_kernarg_segment_ptr 1
		.amdhsa_user_sgpr_dispatch_id 0
		.amdhsa_user_sgpr_kernarg_preload_length 0
		.amdhsa_user_sgpr_kernarg_preload_offset 0
		.amdhsa_user_sgpr_private_segment_size 0
		.amdhsa_uses_dynamic_stack 0
		.amdhsa_enable_private_segment 0
		.amdhsa_system_sgpr_workgroup_id_x 1
		.amdhsa_system_sgpr_workgroup_id_y 0
		.amdhsa_system_sgpr_workgroup_id_z 0
		.amdhsa_system_sgpr_workgroup_info 0
		.amdhsa_system_vgpr_workitem_id 0
		.amdhsa_next_free_vgpr 245
		.amdhsa_next_free_sgpr 100
		.amdhsa_accum_offset 248
		.amdhsa_reserve_vcc 1
		.amdhsa_float_round_mode_32 0
		.amdhsa_float_round_mode_16_64 0
		.amdhsa_float_denorm_mode_32 3
		.amdhsa_float_denorm_mode_16_64 3
		.amdhsa_dx10_clamp 1
		.amdhsa_ieee_mode 1
		.amdhsa_fp16_overflow 0
		.amdhsa_tg_split 0
		.amdhsa_exception_fp_ieee_invalid_op 0
		.amdhsa_exception_fp_denorm_src 0
		.amdhsa_exception_fp_ieee_div_zero 0
		.amdhsa_exception_fp_ieee_overflow 0
		.amdhsa_exception_fp_ieee_underflow 0
		.amdhsa_exception_fp_ieee_inexact 0
		.amdhsa_exception_int_div_zero 0
	.end_amdhsa_kernel
